# nt hint on the gemm_in and MoE up-projection epilogue outputs as well
# speedup vs baseline: 1.0087x; 1.0015x over previous
; DI void gemm_in_phase(const Params& P, int l, char* smem) {
;     ...
;     } else {
;       const int head = nt - 12;
;       half_t* vbase = P.vT + ((size_t)(b * 4 + head) * 128 + wc * 64) * KV + pos0;
; #pragma unroll
;       for (int h = 0; h < 2; h++) {
; #pragma unroll
;         for (int ml = 0; ml < 4; ml++)
; #pragma unroll
;           for (int n = 0; n < 4; n++) {
;             h4 o; o[0] = (half_t)acc[h * 4 + ml][n][0]; o[1] = (half_t)acc[h * 4 + ml][n][1]; o[2] = (half_t)acc[h * 4 + ml][n][2]; o[3] = (half_t)acc[h * 4 + ml][n][3];
;             *(h4*)(stg + (n * 16 + fr) * 144 + (ml * 16 + fq * 4) * 2) = o;
;           }
;         __builtin_amdgcn_wave_barrier();
; #pragma unroll
;         for (int i = 0; i < 8; i++) {
;           const int c = i * 64 + lane, drow = c >> 3, c16 = c & 7;
;           h8 v = *(const h8*)(stg + drow * 144 + c16 * 16);
;           *(h8*)(vbase + (size_t)drow * KV + h * 64 + c16 * 8) = v;
;         }
;         __builtin_amdgcn_wave_barrier();
;       }
.LBB0_250:
	v_ashrrev_i32_e32 v4, 6, v10
	s_movk_i32 s6, 0x3000
	v_and_b32_e32 v19, 1, v4
	v_mul_lo_u32 v4, v4, s6
	s_add_i32 s6, s22, -16
	v_add_u32_e32 v18, 0x18000, v4
	s_cmp_gt_u32 s6, -13
	s_mov_b64 s[6:7], -1
	s_cbranch_scc0 .LBB0_324
	v_bfe_u32 v20, v10, 4, 2
	s_cmp_gt_u32 s22, 11
	s_cbranch_scc0 .LBB0_253
	v_lshlrev_b32_e32 v4, 2, v9
	v_add3_u32 v4, s22, -12, v4
	v_ashrrev_i32_e32 v5, 31, v4
	v_readlane_b32 s6, v255, 56
	v_lshlrev_b64 v[4:5], 7, v[4:5]
	v_readlane_b32 s7, v255, 57
	v_lshl_or_b32 v4, v19, 6, v4
	s_movk_i32 s8, 0x4200
	v_mov_b64_e32 v[6:7], s[6:7]
	v_mad_u64_u32 v[6:7], s[6:7], v4, s8, v[6:7]
	v_mad_i32_i24 v7, v5, s8, v7
	v_lshl_add_u64 v[4:5], v[148:149], 1, v[6:7]
	v_lshlrev_b32_e32 v6, 4, v10
	v_and_b32_e32 v11, 63, v10
	v_lshlrev_b32_e32 v16, 3, v20
	v_and_b32_e32 v6, 0x70, v6
	v_mov_b32_e32 v7, v149
	v_accvgpr_write_b32 a0, v28
	v_mul_u32_u24_e32 v10, 0x90, v8
	v_mov_b32_e32 v116, v22
	v_add_u32_e32 v22, v18, v6
	v_lshl_add_u64 v[4:5], v[4:5], 0, v[6:7]
	v_accvgpr_write_b32 a1, v29
	v_accvgpr_write_b32 a2, v30
	v_accvgpr_write_b32 a3, v31
	v_cvt_pk_f16_f32 v7, v139, v121
	v_cvt_pk_f16_f32 v6, v105, v104
	v_add3_u32 v29, v18, v16, v10
	v_cvt_pk_f16_f32 v21, v174, v191
	v_mov_b32_e32 v118, v20
	v_cvt_pk_f16_f32 v20, v180, v173
	v_lshrrev_b32_e32 v23, 3, v11
	v_cvt_pk_f16_f32 v11, v175, v128
	v_cvt_pk_f16_f32 v10, v120, v190
	ds_write2_b64 v29, v[6:7], v[20:21] offset1:4
	v_cvt_pk_f16_f32 v7, v176, v189
	v_cvt_pk_f16_f32 v6, v194, v193
	v_add_u32_e32 v30, 0x800, v29
	v_cvt_pk_f16_f32 v17, v102, v101
	v_cvt_pk_f16_f32 v16, v195, v103
	ds_write2_b64 v30, v[10:11], v[6:7] offset0:32 offset1:36
	v_cvt_pk_f16_f32 v7, v186, v185
	v_cvt_pk_f16_f32 v6, v188, v187
	v_add_u32_e32 v31, 0x1000, v29
	v_mov_b32_e32 v115, v19
	v_cvt_pk_f16_f32 v19, v192, v196
	v_mov_b32_e32 v112, v18
	v_cvt_pk_f16_f32 v18, v100, v179
	ds_write2_b64 v31, v[16:17], v[6:7] offset0:64 offset1:68
	v_cvt_pk_f16_f32 v7, v182, v181
	v_cvt_pk_f16_f32 v6, v184, v183
	v_add_u32_e32 v32, 0x1800, v29
	ds_write2_b64 v32, v[18:19], v[6:7] offset0:96 offset1:100
	v_cvt_pk_f16_f32 v7, v250, v249
	v_cvt_pk_f16_f32 v6, v252, v251
	v_cvt_pk_f16_f32 v21, v234, v233
	v_cvt_pk_f16_f32 v20, v236, v235
	v_cvt_pk_f16_f32 v11, v246, v245
	v_cvt_pk_f16_f32 v10, v248, v247
	ds_write2_b64 v29, v[6:7], v[20:21] offset0:8 offset1:12
	v_cvt_pk_f16_f32 v7, v230, v229
	v_cvt_pk_f16_f32 v6, v232, v231
	v_cvt_pk_f16_f32 v17, v242, v241
	v_cvt_pk_f16_f32 v16, v244, v243
	ds_write2_b64 v30, v[10:11], v[6:7] offset0:40 offset1:44
	v_cvt_pk_f16_f32 v7, v226, v225
	v_cvt_pk_f16_f32 v6, v228, v227
	v_cvt_pk_f16_f32 v19, v238, v237
	v_cvt_pk_f16_f32 v18, v240, v239
	ds_write2_b64 v31, v[16:17], v[6:7] offset0:72 offset1:76
	v_cvt_pk_f16_f32 v7, v222, v221
	v_cvt_pk_f16_f32 v6, v224, v223
	ds_write2_b64 v32, v[18:19], v[6:7] offset0:104 offset1:108
	v_mul_u32_u24_e32 v6, 0x2100, v23
	v_lshlrev_b32_e32 v6, 1, v6
	v_mov_b32_e32 v7, v149
	v_lshl_add_u64 v[10:11], v[4:5], 0, v[6:7]
	v_or_b32_e32 v7, 8, v23
	v_mad_u32_u24 v28, v23, s40, v22
	v_mad_u32_u24 v106, v7, s40, v22
	s_waitcnt vmcnt(0)
	ds_read_b128 v[122:125], v28
	ds_read_b128 v[20:23], v106
	s_mov_b64 s[6:7], 0x21000
	v_lshl_add_u64 v[16:17], v[10:11], 0, s[6:7]
	s_mov_b32 s6, 0x21000
	v_add_co_u32_e32 v18, vcc, s6, v10
	s_waitcnt lgkmcnt(0)
	global_store_dwordx4 v[10:11], v[122:125], off nt
	v_addc_co_u32_e32 v19, vcc, 0, v11, vcc
	global_store_dwordx4 v[18:19], v[20:23], off nt
	ds_read_b128 v[20:23], v106 offset:1152
	ds_read_b128 v[122:125], v106 offset:2304
	s_mov_b32 s6, 0x42000
	v_add_co_u32_e32 v18, vcc, s6, v10
	s_mov_b32 s6, 0x63000
	s_nop 0
	v_addc_co_u32_e32 v19, vcc, 0, v11, vcc
	s_waitcnt lgkmcnt(1)
	global_store_dwordx4 v[18:19], v[20:23], off nt
	v_add_co_u32_e32 v18, vcc, s6, v10
	ds_read_b128 v[20:23], v106 offset:3456
	s_nop 0
	v_addc_co_u32_e32 v19, vcc, 0, v11, vcc
	s_waitcnt lgkmcnt(1)
; DI void gemm_in_phase(const Params& P, int l, char* smem) {
;     ...
; #pragma unroll
;       for (int h = 0; h < 2; h++) {
; #pragma unroll
;         for (int ml = 0; ml < 4; ml++)
; #pragma unroll
;           for (int n = 0; n < 4; n++) {
;             h4 o; o[0] = (half_t)acc[h * 4 + ml][n][0]; o[1] = (half_t)acc[h * 4 + ml][n][1]; o[2] = (half_t)acc[h * 4 + ml][n][2]; o[3] = (half_t)acc[h * 4 + ml][n][3];
;             *(h4*)(stg + (n * 16 + fr) * 144 + (ml * 16 + fq * 4) * 2) = o;
;           }
;         __builtin_amdgcn_wave_barrier();
; #pragma unroll
;         for (int i = 0; i < 8; i++) {
;           const int c = i * 64 + lane, drow = c >> 3, c16 = c & 7;
;           h8 v = *(const h8*)(stg + drow * 144 + c16 * 16);
;           *(h8*)(vbase + (size_t)drow * KV + h * 64 + c16 * 8) = v;
;         }
;         __builtin_amdgcn_wave_barrier();
;       }
	global_store_dwordx4 v[18:19], v[122:125], off nt
	ds_read_b128 v[122:125], v106 offset:4608
	v_add_u32_e32 v18, 0x84000, v6
	v_mov_b32_e32 v19, v149
	v_lshl_add_u64 v[126:127], v[4:5], 0, v[18:19]
	v_add_u32_e32 v18, 0xa5000, v6
	s_waitcnt lgkmcnt(1)
	global_store_dwordx4 v[126:127], v[20:23], off nt
	v_lshl_add_u64 v[44:45], v[4:5], 0, v[18:19]
	ds_read_b128 v[20:23], v106 offset:5760
	s_waitcnt lgkmcnt(1)
	global_store_dwordx4 v[44:45], v[122:125], off nt
	ds_read_b128 v[122:125], v106 offset:6912
	v_add_u32_e32 v18, 0xc6000, v6
	v_lshl_add_u64 v[46:47], v[4:5], 0, v[18:19]
	v_add_u32_e32 v6, 0xe7000, v6
	v_mov_b32_e32 v7, v149
	s_waitcnt lgkmcnt(1)
	global_store_dwordx4 v[46:47], v[20:23], off nt
	v_mov_b32_e32 v108, v98
	v_lshl_add_u64 v[98:99], v[4:5], 0, v[6:7]
	v_cvt_pk_f16_f32 v5, v218, v217
	v_cvt_pk_f16_f32 v4, v220, v219
	v_cvt_pk_f16_f32 v23, v202, v201
	v_cvt_pk_f16_f32 v22, v204, v203
	s_waitcnt lgkmcnt(0)
	global_store_dwordx4 v[98:99], v[122:125], off nt
	v_cvt_pk_f16_f32 v7, v214, v213
	v_cvt_pk_f16_f32 v6, v216, v215
	ds_write2_b64 v29, v[4:5], v[22:23] offset1:4
	v_cvt_pk_f16_f32 v5, v198, v197
	v_cvt_pk_f16_f32 v4, v200, v199
	v_cvt_pk_f16_f32 v19, v210, v209
	v_cvt_pk_f16_f32 v18, v212, v211
	ds_write2_b64 v30, v[6:7], v[4:5] offset0:32 offset1:36
	v_cvt_pk_f16_f32 v5, v169, v168
	v_cvt_pk_f16_f32 v4, v171, v170
	v_cvt_pk_f16_f32 v21, v206, v205
	v_cvt_pk_f16_f32 v20, v208, v207
	ds_write2_b64 v31, v[18:19], v[4:5] offset0:64 offset1:68
	v_cvt_pk_f16_f32 v5, v165, v164
	v_cvt_pk_f16_f32 v4, v167, v166
	ds_write2_b64 v32, v[20:21], v[4:5] offset0:96 offset1:100
	v_cvt_pk_f16_f32 v5, v161, v160
	v_cvt_pk_f16_f32 v4, v163, v162
	v_cvt_pk_f16_f32 v23, v143, v142
	v_cvt_pk_f16_f32 v22, v145, v144
	v_cvt_pk_f16_f32 v7, v157, v156
	v_cvt_pk_f16_f32 v6, v159, v158
	ds_write2_b64 v29, v[4:5], v[22:23] offset0:8 offset1:12
	v_cvt_pk_f16_f32 v5, v138, v137
	v_cvt_pk_f16_f32 v4, v141, v140
	v_cvt_pk_f16_f32 v19, v153, v152
	v_cvt_pk_f16_f32 v18, v155, v154
	ds_write2_b64 v30, v[6:7], v[4:5] offset0:40 offset1:44
	v_cvt_pk_f16_f32 v5, v134, v133
	v_cvt_pk_f16_f32 v4, v136, v135
	v_cvt_pk_f16_f32 v21, v147, v146
	v_cvt_pk_f16_f32 v20, v151, v150
	ds_write2_b64 v31, v[18:19], v[4:5] offset0:72 offset1:76
	v_cvt_pk_f16_f32 v5, v130, v129
	v_cvt_pk_f16_f32 v4, v132, v131
	ds_write2_b64 v32, v[20:21], v[4:5] offset0:104 offset1:108
	ds_read_b128 v[20:23], v28
	ds_read_b128 v[122:125], v106
	ds_read_b128 v[32:35], v106 offset:1152
	s_mov_b64 s[6:7], 0x42000
	v_lshl_add_u64 v[4:5], v[10:11], 0, s[6:7]
	s_waitcnt lgkmcnt(2)
	global_store_dwordx4 v[10:11], v[20:23], off offset:128 nt
	s_waitcnt lgkmcnt(1)
	global_store_dwordx4 v[16:17], v[122:125], off offset:128 nt
	ds_read_b128 v[20:23], v106 offset:2304
	s_waitcnt lgkmcnt(1)
	global_store_dwordx4 v[4:5], v[32:35], off offset:128 nt
	ds_read_b128 v[32:35], v106 offset:3456
	ds_read_b128 v[122:125], v106 offset:4608
	ds_read_b128 v[4:7], v106 offset:5760
	ds_read_b128 v[16:19], v106 offset:6912
	s_mov_b64 s[6:7], 0x63000
	v_lshl_add_u64 v[28:29], v[10:11], 0, s[6:7]
	s_waitcnt lgkmcnt(4)
	global_store_dwordx4 v[28:29], v[20:23], off offset:128 nt
	v_accvgpr_read_b32 v31, a3
	v_accvgpr_read_b32 v30, a2
	v_mov_b32_e32 v20, v118
	v_accvgpr_read_b32 v29, a1
	v_accvgpr_read_b32 v28, a0
	v_mov_b32_e32 v22, v116
	s_waitcnt lgkmcnt(3)
	global_store_dwordx4 v[126:127], v[32:35], off offset:128 nt
	s_waitcnt lgkmcnt(2)
	global_store_dwordx4 v[44:45], v[122:125], off offset:128 nt
	s_waitcnt lgkmcnt(1)
	global_store_dwordx4 v[46:47], v[4:7], off offset:128 nt
	s_waitcnt lgkmcnt(0)
	global_store_dwordx4 v[98:99], v[16:19], off offset:128 nt
	v_mov_b32_e32 v98, v108
	s_mov_b64 s[6:7], 0
	v_mov_b32_e32 v19, v115
	v_mov_b32_e32 v18, v112

; #define TIDX tid_opaque()
; template <class RP, class SC>
; DI void stage_flush(char* stg, int h, RP rowptr, SC rowscale) {
;   const int lane = TIDX & 63;
;   __builtin_amdgcn_wave_barrier();
; #pragma unroll
;   for (int i = 0; i < 8; i++) {
;     const int c = i * 64 + lane, row = c >> 3, c16 = c & 7;
;     h8 v = *(const h8*)(stg + row * 144 + c16 * 16);
;     half_t* d = rowptr(h * 64 + row);
;     if (d) { rowscale(h * 64 + row, v); *(h8*)(d + c16 * 8) = v; }
;   }
;   __builtin_amdgcn_wave_barrier();
; }
; DI void gemm_in_phase(const Params& P, int l, char* smem) {
;     ...
;             float ss = 0.f;
; #pragma unroll
;             for (int n = 0; n < 4; n++) ss += acc[m][n][j] * acc[m][n][j];
;             ss = dpp_row_sum(ss);
;             const float rstd = rsqrtf(ss * (1.f / 64.f) + EPS);
;             float o[4];
; #pragma unroll
;             for (int n = 0; n < 4; n++) o[n] = acc[m][n][j] * rstd * gg[n];
;             if (!isctx) {
;               const float2 cr = rr2[mh], cc = rcl[(mm * 16 + fq * 4 + j) * 16 + fr];
;               float a0 = o[0] * cr.x - o[1] * cr.y, a1 = o[1] * cr.x + o[0] * cr.y;
;               float a2 = o[2] * cc.x - o[3] * cc.y, a3 = o[3] * cc.x + o[2] * cc.y;
;               o[0] = a0; o[1] = a1; o[2] = a2; o[3] = a3;
;             }
.LBB0_290:
	s_or_b64 exec, exec, s[10:11]
	s_and_b64 s[6:7], s[6:7], exec
	s_cselect_b32 s6, -4, -8
	s_add_i32 s10, s6, s22
	s_add_u32 s6, s90, s8
	s_addc_u32 s7, s91, s9
	v_lshlrev_b64 v[4:5], 10, v[32:33]
	v_lshl_add_u64 v[4:5], s[6:7], 0, v[4:5]
	s_lshl_b32 s84, s10, 8
	v_lshl_add_u64 v[4:5], v[4:5], 0, s[84:85]
	v_lshlrev_b32_e32 v148, 7, v19
	v_lshl_add_u64 v[48:49], v[4:5], 0, v[148:149]
	v_cvt_f16_f32_e32 v4, v53
	v_mov_b32_e32 v8, v172
	v_mov_b32_e32 v5, v149
	ds_write_b16 v66, v4 offset:2304
	v_cvt_f16_f32_e32 v4, v55
	ds_write_b16 v66, v4 offset:2336
	v_cvt_f16_f32_e32 v4, v50
	ds_write_b16 v66, v4 offset:2368
	v_cvt_f16_f32_e32 v4, v54
	ds_write_b16 v66, v4 offset:2400
	s_nop 0
	v_lshlrev_b32_e32 v4, 4, v8
	v_and_b32_e32 v4, 0x70, v4
	v_add_u32_e32 v16, v18, v4
	v_and_b32_e32 v17, 56, v8
	v_bfe_u32 v8, v8, 3, 3
	v_mad_u32_u24 v8, v8, s40, v16
	ds_read_b128 v[8:11], v8
	v_lshlrev_b32_e32 v148, 7, v17
	v_lshl_add_u64 v[6:7], v[48:49], 0, v[148:149]
	v_lshl_add_u64 v[6:7], v[6:7], 0, v[4:5]
	s_waitcnt lgkmcnt(0)
	global_store_dwordx4 v[6:7], v[8:11], off nt
	s_nop 1
	v_or_b32_e32 v8, 64, v17
	v_lshlrev_b32_e32 v148, 7, v8
	v_lshrrev_b32_e32 v8, 3, v8
	v_mad_u32_u24 v8, v8, s40, v16
	ds_read_b128 v[8:11], v8
	v_lshl_add_u64 v[6:7], v[48:49], 0, v[148:149]
	v_lshl_add_u64 v[6:7], v[6:7], 0, v[4:5]
	s_waitcnt lgkmcnt(0)
	global_store_dwordx4 v[6:7], v[8:11], off nt
	s_nop 1
	v_or_b32_e32 v8, 0x80, v17
	v_lshlrev_b32_e32 v148, 7, v8
	v_lshrrev_b32_e32 v8, 3, v8
	v_mad_u32_u24 v8, v8, s40, v16
	ds_read_b128 v[8:11], v8
	v_lshl_add_u64 v[6:7], v[48:49], 0, v[148:149]
	v_lshl_add_u64 v[6:7], v[6:7], 0, v[4:5]
	s_waitcnt lgkmcnt(0)
	global_store_dwordx4 v[6:7], v[8:11], off nt
	s_nop 1
	v_or_b32_e32 v8, 0xc0, v17
	v_lshlrev_b32_e32 v148, 7, v8
	v_lshrrev_b32_e32 v8, 3, v8
	v_mad_u32_u24 v8, v8, s40, v16
	ds_read_b128 v[8:11], v8
	v_lshl_add_u64 v[6:7], v[48:49], 0, v[148:149]
	v_lshl_add_u64 v[6:7], v[6:7], 0, v[4:5]
	s_waitcnt lgkmcnt(0)
	global_store_dwordx4 v[6:7], v[8:11], off nt
	s_nop 1
	v_or_b32_e32 v8, 0x100, v17
	v_lshlrev_b32_e32 v148, 7, v8
	v_lshrrev_b32_e32 v8, 3, v8
	v_mad_u32_u24 v8, v8, s40, v16
	ds_read_b128 v[8:11], v8
	v_lshl_add_u64 v[6:7], v[48:49], 0, v[148:149]
	v_lshl_add_u64 v[6:7], v[6:7], 0, v[4:5]
	s_waitcnt lgkmcnt(0)
	global_store_dwordx4 v[6:7], v[8:11], off nt
	s_nop 1
	v_or_b32_e32 v8, 0x140, v17
	v_lshlrev_b32_e32 v148, 7, v8
	v_lshrrev_b32_e32 v8, 3, v8
	v_mad_u32_u24 v8, v8, s40, v16
	ds_read_b128 v[8:11], v8
	v_lshl_add_u64 v[6:7], v[48:49], 0, v[148:149]
	v_lshl_add_u64 v[6:7], v[6:7], 0, v[4:5]
	s_waitcnt lgkmcnt(0)
	global_store_dwordx4 v[6:7], v[8:11], off nt
	s_nop 1
	v_or_b32_e32 v8, 0x180, v17
	v_lshlrev_b32_e32 v148, 7, v8
	v_lshrrev_b32_e32 v8, 3, v8
	v_mad_u32_u24 v8, v8, s40, v16
	ds_read_b128 v[8:11], v8
	v_lshl_add_u64 v[6:7], v[48:49], 0, v[148:149]
	v_lshl_add_u64 v[6:7], v[6:7], 0, v[4:5]
	s_waitcnt lgkmcnt(0)
	global_store_dwordx4 v[6:7], v[8:11], off nt
	s_nop 1
	v_or_b32_e32 v8, 0x1c0, v17
	v_lshlrev_b32_e32 v148, 7, v8
	v_lshl_add_u64 v[6:7], v[48:49], 0, v[148:149]
	v_lshl_add_u64 v[4:5], v[6:7], 0, v[4:5]
	v_lshrrev_b32_e32 v6, 3, v8
	v_mad_u32_u24 v6, v6, s40, v16
	ds_read_b128 v[8:11], v6
	v_accvgpr_read_b32 v6, a84
	v_mov_b32_e32 v7, v40
	v_pk_mul_f32 v[6:7], v[6:7], v[6:7]
	s_waitcnt lgkmcnt(0)
	global_store_dwordx4 v[4:5], v[8:11], off nt
	v_mov_b32_e32 v4, v28
	v_mov_b32_e32 v5, v36
	v_pk_mul_f32 v[4:5], v[4:5], v[4:5]
	v_accvgpr_read_b32 v8, a84
	v_add_f32_e32 v4, v4, v5
	v_add_f32_e32 v4, v4, v6
	v_add_f32_e32 v4, v4, v7
	v_mov_b32_e32 v5, 0x358637bd
	v_mov_b32_e32 v6, v40
	v_add_f32_dpp v4, v4, v4 row_ror:8 row_mask:0xf bank_mask:0xf bound_ctrl:1
	v_mov_b32_e32 v7, v28
	v_mov_b32_e32 v9, v36
	v_add_f32_dpp v4, v4, v4 row_ror:4 row_mask:0xf bank_mask:0xf bound_ctrl:1
	v_mov_b32_e32 v10, v40
	v_mov_b32_e32 v11, v36
	v_add_f32_dpp v4, v4, v4 row_ror:2 row_mask:0xf bank_mask:0xf bound_ctrl:1
	s_nop 1
	v_add_f32_dpp v4, v4, v4 row_ror:1 row_mask:0xf bank_mask:0xf bound_ctrl:1
	v_fmamk_f32 v4, v4, 0x3c800000, v5
	v_cmp_gt_f32_e32 vcc, s46, v4
	v_mul_f32_e32 v5, 0x4b800000, v4
	s_nop 0
	v_cndmask_b32_e32 v4, v4, v5, vcc
	v_rsq_f32_e32 v4, v4
	s_nop 0
	v_mul_f32_e32 v5, 0x45800000, v4
	v_cndmask_b32_e32 v4, v4, v5, vcc
	v_pk_mul_f32 v[6:7], v[6:7], v[4:5] op_sel_hi:[1,0]
	v_pk_mul_f32 v[8:9], v[8:9], v[4:5] op_sel_hi:[1,0]
	v_pk_mul_f32 v[4:5], v[10:11], v[4:5] op_sel_hi:[1,0]
	v_pk_mul_f32 v[52:53], v[110:111], v[8:9]
	v_pk_mul_f32 v[50:51], v[114:115], v[4:5]
	v_pk_mul_f32 v[54:55], v[112:113], v[6:7]
	s_and_saveexec_b64 s[6:7], s[2:3]
	s_xor_b64 s[6:7], exec, s[6:7]
	s_cbranch_execz .LBB0_292
	ds_read_b64 v[8:9], v106
	v_mov_b32_e32 v5, v55
	s_waitcnt lgkmcnt(0)
	v_mov_b32_e32 v106, v8
	v_mov_b32_e32 v108, v9
	v_mov_b32_e32 v4, v8
	v_mov_b32_e32 v8, v9
	v_mov_b32_e32 v9, v107
	v_pk_mul_f32 v[6:7], v[52:53], v[108:109]
	v_mov_b32_e32 v53, v109
	v_pk_mul_f32 v[8:9], v[8:9], v[50:51]
	v_pk_fma_f32 v[50:51], v[54:55], v[106:107], v[6:7]
	v_pk_fma_f32 v[52:53], v[52:53], v[4:5], v[8:9] neg_lo:[0,0,1] neg_hi:[0,0,1]
	s_nop 0
	v_mov_b32_e32 v55, v53

; #define TIDX tid_opaque()
; template <class RP, class SC>
; DI void stage_flush(char* stg, int h, RP rowptr, SC rowscale) {
;   const int lane = TIDX & 63;
;   __builtin_amdgcn_wave_barrier();
; #pragma unroll
;   for (int i = 0; i < 8; i++) {
;     const int c = i * 64 + lane, row = c >> 3, c16 = c & 7;
;     h8 v = *(const h8*)(stg + row * 144 + c16 * 16);
;     half_t* d = rowptr(h * 64 + row);
;     if (d) { rowscale(h * 64 + row, v); *(h8*)(d + c16 * 8) = v; }
;   }
;   __builtin_amdgcn_wave_barrier();
; }
; DI void gemm_in_phase(const Params& P, int l, char* smem) {
;     ...
;             for (int n = 0; n < 4; n++) stage_put(stg, mm, n, j, fr, fq, o[n]);
;           }
;         }
;         stage_flush(stg, mh, [&](int r) { return base + (size_t)r * 512; }, noscale);
.LBB0_322:
	s_or_b64 exec, exec, s[6:7]
	v_cvt_f16_f32_e32 v1, v1
	v_cvt_f16_f32_e32 v3, v5
	v_cvt_f16_f32_e32 v0, v0
	v_mov_b32_e32 v5, v149
	ds_write_b16 v66, v1 offset:2336
	v_cvt_f16_f32_e32 v1, v2
	v_mov_b32_e32 v2, v172
	ds_write_b16 v66, v3 offset:2304
	ds_write_b16 v66, v0 offset:2400
	ds_write_b16 v66, v1 offset:2368
	s_mov_b32 s2, 0x10000
	v_and_b32_e32 v9, 56, v2
	v_lshlrev_b32_e32 v0, 4, v2
	v_lshlrev_b32_e32 v148, 7, v9
	v_and_b32_e32 v4, 0x70, v0
	v_lshl_add_u64 v[0:1], v[48:49], 0, v[148:149]
	v_add_u32_e32 v8, v18, v4
	v_lshl_add_u64 v[6:7], v[0:1], 0, v[4:5]
	v_bfe_u32 v0, v2, 3, 3
	v_mad_u32_u24 v0, v0, s40, v8
	ds_read_b128 v[0:3], v0
	v_add_co_u32_e32 v6, vcc, s2, v6
	s_mov_b32 s33, 0x10000
	s_nop 0
	v_addc_co_u32_e32 v7, vcc, 0, v7, vcc
	s_waitcnt lgkmcnt(0)
	global_store_dwordx4 v[6:7], v[0:3], off nt
	s_nop 1
	v_or_b32_e32 v2, 64, v9
	v_lshlrev_b32_e32 v148, 7, v2
	v_lshl_add_u64 v[0:1], v[48:49], 0, v[148:149]
	v_lshl_add_u64 v[6:7], v[0:1], 0, v[4:5]
	v_lshrrev_b32_e32 v0, 3, v2
	v_mad_u32_u24 v0, v0, s40, v8
	ds_read_b128 v[0:3], v0
	v_add_co_u32_e32 v6, vcc, s2, v6
	s_nop 1
	v_addc_co_u32_e32 v7, vcc, 0, v7, vcc
	s_waitcnt lgkmcnt(0)
	global_store_dwordx4 v[6:7], v[0:3], off nt
	s_nop 1
	v_or_b32_e32 v2, 0x80, v9
	v_lshlrev_b32_e32 v148, 7, v2
	v_lshl_add_u64 v[0:1], v[48:49], 0, v[148:149]
	v_lshl_add_u64 v[6:7], v[0:1], 0, v[4:5]
	v_lshrrev_b32_e32 v0, 3, v2
	v_mad_u32_u24 v0, v0, s40, v8
	ds_read_b128 v[0:3], v0
	v_add_co_u32_e32 v6, vcc, s2, v6
	s_nop 1
	v_addc_co_u32_e32 v7, vcc, 0, v7, vcc
	s_waitcnt lgkmcnt(0)
	global_store_dwordx4 v[6:7], v[0:3], off nt
	s_nop 1
	v_or_b32_e32 v2, 0xc0, v9
	v_lshlrev_b32_e32 v148, 7, v2
	v_lshl_add_u64 v[0:1], v[48:49], 0, v[148:149]
	v_lshl_add_u64 v[6:7], v[0:1], 0, v[4:5]
	v_lshrrev_b32_e32 v0, 3, v2
	v_mad_u32_u24 v0, v0, s40, v8
	ds_read_b128 v[0:3], v0
	v_add_co_u32_e32 v6, vcc, s2, v6
	s_nop 1
	v_addc_co_u32_e32 v7, vcc, 0, v7, vcc
	s_waitcnt lgkmcnt(0)
	global_store_dwordx4 v[6:7], v[0:3], off nt
	s_nop 1
	v_or_b32_e32 v2, 0x100, v9
	v_lshlrev_b32_e32 v148, 7, v2
	v_lshl_add_u64 v[0:1], v[48:49], 0, v[148:149]
	v_lshl_add_u64 v[6:7], v[0:1], 0, v[4:5]
	v_lshrrev_b32_e32 v0, 3, v2
	v_mad_u32_u24 v0, v0, s40, v8
	ds_read_b128 v[0:3], v0
	v_add_co_u32_e32 v6, vcc, s2, v6
	s_nop 1
	v_addc_co_u32_e32 v7, vcc, 0, v7, vcc
	s_waitcnt lgkmcnt(0)
	global_store_dwordx4 v[6:7], v[0:3], off nt
	s_nop 1
	v_or_b32_e32 v2, 0x140, v9
	v_lshlrev_b32_e32 v148, 7, v2
	v_lshl_add_u64 v[0:1], v[48:49], 0, v[148:149]
	v_lshl_add_u64 v[6:7], v[0:1], 0, v[4:5]
	v_lshrrev_b32_e32 v0, 3, v2
	v_mad_u32_u24 v0, v0, s40, v8
	ds_read_b128 v[0:3], v0
	v_add_co_u32_e32 v6, vcc, s2, v6
	s_nop 1
	v_addc_co_u32_e32 v7, vcc, 0, v7, vcc
	s_waitcnt lgkmcnt(0)
	global_store_dwordx4 v[6:7], v[0:3], off nt
	s_nop 1
	v_or_b32_e32 v2, 0x180, v9
	v_lshlrev_b32_e32 v148, 7, v2
	v_lshl_add_u64 v[0:1], v[48:49], 0, v[148:149]
	v_lshl_add_u64 v[6:7], v[0:1], 0, v[4:5]
	v_lshrrev_b32_e32 v0, 3, v2
	v_mad_u32_u24 v0, v0, s40, v8
	ds_read_b128 v[0:3], v0
	v_add_co_u32_e32 v6, vcc, s2, v6
	s_nop 1
	v_addc_co_u32_e32 v7, vcc, 0, v7, vcc
	s_waitcnt lgkmcnt(0)
	global_store_dwordx4 v[6:7], v[0:3], off nt
	s_nop 1
	v_or_b32_e32 v2, 0x1c0, v9
	v_lshlrev_b32_e32 v148, 7, v2
	v_lshl_add_u64 v[0:1], v[48:49], 0, v[148:149]
	v_lshl_add_u64 v[4:5], v[0:1], 0, v[4:5]
	v_lshrrev_b32_e32 v0, 3, v2
	v_mad_u32_u24 v0, v0, s40, v8
	ds_read_b128 v[0:3], v0
	v_add_co_u32_e32 v4, vcc, 0x10000, v4
	s_nop 1
	v_addc_co_u32_e32 v5, vcc, 0, v5, vcc
	s_waitcnt lgkmcnt(0)
	global_store_dwordx4 v[4:5], v[0:3], off nt

; #define TIDX tid_opaque()
; template <class RP, class SC>
; DI void stage_flush(char* stg, int h, RP rowptr, SC rowscale) {
;   const int lane = TIDX & 63;
;   __builtin_amdgcn_wave_barrier();
; #pragma unroll
;   for (int i = 0; i < 8; i++) {
;     const int c = i * 64 + lane, row = c >> 3, c16 = c & 7;
;     h8 v = *(const h8*)(stg + row * 144 + c16 * 16);
;     half_t* d = rowptr(h * 64 + row);
;     if (d) { rowscale(h * 64 + row, v); *(h8*)(d + c16 * 8) = v; }
;   }
;   __builtin_amdgcn_wave_barrier();
; }
; template <class VF, class RP, class SC>
; DI void wave_store_tile(VF val, char* stg, RP rowptr, SC rowscale) {
;   const int lane = TIDX & 63, fr = lane & 15, fq = lane >> 4;
; #pragma unroll
;   for (int h = 0; h < 2; h++) {
; #pragma unroll
;     for (int ml = 0; ml < 4; ml++)
; #pragma unroll
;       for (int n = 0; n < 4; n++)
; #pragma unroll
;         for (int j = 0; j < 4; j++) stage_put(stg, ml, n, j, fr, fq, val(h * 4 + ml, n, j));
;     stage_flush(stg, h, rowptr, rowscale);
;   }
; }
; DI void gemm_in_phase(const Params& P, int l, char* smem) {
;     ...
;     if (nt < 4 || nt >= 16) {
;       half_t* dst; int ld, c0; bool gel = false;
;       if (nt < 4) { dst = P.QF; ld = 512; c0 = nt * 128; }
;       else if (nt < 18) { dst = P.gy; ld = 256; c0 = (nt - 16) * 128; gel = true; }
;       else { dst = P.rr; ld = 256; c0 = (nt - 18) * 128; }
;       half_t* base = dst + (size_t)r0 * ld + c0 + wc * 64;
;       if (gel) wave_store_tile([&](int m, int n, int j) { return gelu_tanh(acc[m][n][j]); }, stg, [&](int r) { return base + (size_t)r * ld; }, noscale);
;       else wave_store_tile([&](int m, int n, int j) { return acc[m][n][j]; }, stg, [&](int r) { return base + (size_t)r * ld; }, noscale);
.LBB0_332:
	v_mad_i64_i32 v[0:1], s[22:23], s2, v22, 0
	s_ashr_i32 s7, s6, 31
	v_lshl_add_u64 v[0:1], v[0:1], 1, s[10:11]
	v_lshl_add_u64 v[0:1], s[6:7], 1, v[0:1]
	v_lshlrev_b32_e32 v148, 7, v19
	v_lshl_add_u64 v[0:1], v[0:1], 0, v[148:149]
	s_andn2_b64 vcc, exec, s[8:9]
	s_mov_b64 s[6:7], -1
	s_cbranch_vccz .LBB0_334
	v_mov_b32_e32 v2, v172
	v_cvt_f16_f32_e32 v4, v105
	v_lshrrev_b32_e32 v3, 2, v2
	v_and_b32_e32 v3, 12, v3
	v_lshlrev_b32_e32 v2, 1, v2
	v_and_b32_e32 v2, 30, v2
	v_mul_u32_u24_e32 v3, 0x90, v3
	v_add3_u32 v2, v18, v2, v3
	v_cvt_f16_f32_e32 v3, v104
	ds_write_b16 v2, v4
	v_mov_b32_e32 v9, v149
	s_mov_b64 s[6:7], 0
	ds_write_b16 v2, v3 offset:144
	v_cvt_f16_f32_e32 v3, v139
	ds_write_b16 v2, v3 offset:288
	v_cvt_f16_f32_e32 v3, v121
	ds_write_b16 v2, v3 offset:432
	v_cvt_f16_f32_e32 v3, v120
	ds_write_b16 v2, v3 offset:32
	v_cvt_f16_f32_e32 v3, v190
	ds_write_b16 v2, v3 offset:176
	v_cvt_f16_f32_e32 v3, v175
	ds_write_b16 v2, v3 offset:320
	v_cvt_f16_f32_e32 v3, v128
	ds_write_b16 v2, v3 offset:464
	v_cvt_f16_f32_e32 v3, v195
	ds_write_b16 v2, v3 offset:64
	v_cvt_f16_f32_e32 v3, v103
	ds_write_b16 v2, v3 offset:208
	v_cvt_f16_f32_e32 v3, v102
	ds_write_b16 v2, v3 offset:352
	v_cvt_f16_f32_e32 v3, v101
	ds_write_b16 v2, v3 offset:496
	v_cvt_f16_f32_e32 v3, v100
	ds_write_b16 v2, v3 offset:96
	v_cvt_f16_f32_e32 v3, v179
	ds_write_b16 v2, v3 offset:240
	v_cvt_f16_f32_e32 v3, v192
	ds_write_b16 v2, v3 offset:384
	v_cvt_f16_f32_e32 v3, v196
	ds_write_b16 v2, v3 offset:528
	v_cvt_f16_f32_e32 v3, v180
	ds_write_b16 v2, v3 offset:2304
	v_cvt_f16_f32_e32 v3, v173
	ds_write_b16 v2, v3 offset:2448
	v_cvt_f16_f32_e32 v3, v174
	ds_write_b16 v2, v3 offset:2592
	v_cvt_f16_f32_e32 v3, v191
	ds_write_b16 v2, v3 offset:2736
	v_cvt_f16_f32_e32 v3, v194
	ds_write_b16 v2, v3 offset:2336
	v_cvt_f16_f32_e32 v3, v193
	ds_write_b16 v2, v3 offset:2480
	v_cvt_f16_f32_e32 v3, v176
	ds_write_b16 v2, v3 offset:2624
	v_cvt_f16_f32_e32 v3, v189
	ds_write_b16 v2, v3 offset:2768
	v_cvt_f16_f32_e32 v3, v188
	ds_write_b16 v2, v3 offset:2368
	v_cvt_f16_f32_e32 v3, v187
	ds_write_b16 v2, v3 offset:2512
	v_cvt_f16_f32_e32 v3, v186
	ds_write_b16 v2, v3 offset:2656
	v_cvt_f16_f32_e32 v3, v185
	ds_write_b16 v2, v3 offset:2800
	v_cvt_f16_f32_e32 v3, v184
	ds_write_b16 v2, v3 offset:2400
	v_cvt_f16_f32_e32 v3, v183
	ds_write_b16 v2, v3 offset:2544
	v_cvt_f16_f32_e32 v3, v182
	ds_write_b16 v2, v3 offset:2688
	v_cvt_f16_f32_e32 v3, v181
	ds_write_b16 v2, v3 offset:2832
	v_cvt_f16_f32_e32 v3, v252
	ds_write_b16 v2, v3 offset:4608
	v_cvt_f16_f32_e32 v3, v251
	ds_write_b16 v2, v3 offset:4752
	v_cvt_f16_f32_e32 v3, v250
	ds_write_b16 v2, v3 offset:4896
	v_cvt_f16_f32_e32 v3, v249
	ds_write_b16 v2, v3 offset:5040
	v_cvt_f16_f32_e32 v3, v248
	ds_write_b16 v2, v3 offset:4640
	v_cvt_f16_f32_e32 v3, v247
	ds_write_b16 v2, v3 offset:4784
	v_cvt_f16_f32_e32 v3, v246
	ds_write_b16 v2, v3 offset:4928
	v_cvt_f16_f32_e32 v3, v245
	ds_write_b16 v2, v3 offset:5072
	v_cvt_f16_f32_e32 v3, v244
	ds_write_b16 v2, v3 offset:4672
	v_cvt_f16_f32_e32 v3, v243
	ds_write_b16 v2, v3 offset:4816
	v_cvt_f16_f32_e32 v3, v242
	ds_write_b16 v2, v3 offset:4960
	v_cvt_f16_f32_e32 v3, v241
	ds_write_b16 v2, v3 offset:5104
	v_cvt_f16_f32_e32 v3, v240
	ds_write_b16 v2, v3 offset:4704
	v_cvt_f16_f32_e32 v3, v239
	ds_write_b16 v2, v3 offset:4848
	v_cvt_f16_f32_e32 v3, v238
	ds_write_b16 v2, v3 offset:4992
	v_cvt_f16_f32_e32 v3, v237
	ds_write_b16 v2, v3 offset:5136
	v_cvt_f16_f32_e32 v3, v236
	ds_write_b16 v2, v3 offset:6912
	v_cvt_f16_f32_e32 v3, v235
	ds_write_b16 v2, v3 offset:7056
	v_cvt_f16_f32_e32 v3, v234
	ds_write_b16 v2, v3 offset:7200
	v_cvt_f16_f32_e32 v3, v233
	ds_write_b16 v2, v3 offset:7344
	v_cvt_f16_f32_e32 v3, v232
	ds_write_b16 v2, v3 offset:6944
	v_cvt_f16_f32_e32 v3, v231
	ds_write_b16 v2, v3 offset:7088
	v_cvt_f16_f32_e32 v3, v230
	ds_write_b16 v2, v3 offset:7232
	v_cvt_f16_f32_e32 v3, v229
	ds_write_b16 v2, v3 offset:7376
	v_cvt_f16_f32_e32 v3, v228
	ds_write_b16 v2, v3 offset:6976
	v_cvt_f16_f32_e32 v3, v227
	ds_write_b16 v2, v3 offset:7120
	v_cvt_f16_f32_e32 v3, v226
	ds_write_b16 v2, v3 offset:7264
	v_cvt_f16_f32_e32 v3, v225
	ds_write_b16 v2, v3 offset:7408
	v_cvt_f16_f32_e32 v3, v224
	ds_write_b16 v2, v3 offset:7008
	v_cvt_f16_f32_e32 v3, v223
	ds_write_b16 v2, v3 offset:7152
	v_cvt_f16_f32_e32 v3, v222
	ds_write_b16 v2, v3 offset:7296
	v_cvt_f16_f32_e32 v3, v221
	ds_write_b16 v2, v3 offset:7440
	v_mov_b32_e32 v3, v172
	s_nop 0
	v_lshlrev_b32_e32 v4, 4, v3
	v_bfe_u32 v3, v3, 3, 3
	v_and_b32_e32 v8, 0x70, v4
	v_mul_u32_u24_e32 v4, s2, v3
	v_lshlrev_b32_e32 v148, 1, v4
	v_lshl_add_u64 v[4:5], v[0:1], 0, v[148:149]
	v_lshl_add_u64 v[10:11], v[4:5], 0, v[8:9]
	v_mul_u32_u24_e32 v4, 0x90, v3
	v_add3_u32 v12, v18, v8, v4
	s_waitcnt vmcnt(0)
	ds_read_b128 v[4:7], v12
	s_waitcnt lgkmcnt(0)
	global_store_dwordx4 v[10:11], v[4:7], off nt
	s_nop 1
	v_or_b32_e32 v4, 8, v3
	v_mul_u32_u24_e32 v4, s2, v4
	v_lshlrev_b32_e32 v148, 1, v4
	v_lshl_add_u64 v[4:5], v[0:1], 0, v[148:149]
	v_lshl_add_u64 v[10:11], v[4:5], 0, v[8:9]
	ds_read_b128 v[4:7], v12 offset:1152
	s_waitcnt lgkmcnt(0)
	global_store_dwordx4 v[10:11], v[4:7], off nt
	s_nop 1
	v_or_b32_e32 v4, 16, v3
	v_mul_u32_u24_e32 v4, s2, v4
	v_lshlrev_b32_e32 v148, 1, v4
	v_lshl_add_u64 v[4:5], v[0:1], 0, v[148:149]
	v_lshl_add_u64 v[10:11], v[4:5], 0, v[8:9]
	ds_read_b128 v[4:7], v12 offset:2304
	s_waitcnt lgkmcnt(0)
	global_store_dwordx4 v[10:11], v[4:7], off nt
	s_nop 1
	v_or_b32_e32 v4, 24, v3
	v_mul_u32_u24_e32 v4, s2, v4
	v_lshlrev_b32_e32 v148, 1, v4
	v_lshl_add_u64 v[4:5], v[0:1], 0, v[148:149]
	v_lshl_add_u64 v[10:11], v[4:5], 0, v[8:9]
	ds_read_b128 v[4:7], v12 offset:3456
	s_waitcnt lgkmcnt(0)
; #define TIDX tid_opaque()
; template <class RP, class SC>
; DI void stage_flush(char* stg, int h, RP rowptr, SC rowscale) {
;   const int lane = TIDX & 63;
;   __builtin_amdgcn_wave_barrier();
; #pragma unroll
;   for (int i = 0; i < 8; i++) {
;     const int c = i * 64 + lane, row = c >> 3, c16 = c & 7;
;     h8 v = *(const h8*)(stg + row * 144 + c16 * 16);
;     half_t* d = rowptr(h * 64 + row);
;     if (d) { rowscale(h * 64 + row, v); *(h8*)(d + c16 * 8) = v; }
;   }
;   __builtin_amdgcn_wave_barrier();
; }
; template <class VF, class RP, class SC>
; DI void wave_store_tile(VF val, char* stg, RP rowptr, SC rowscale) {
;   const int lane = TIDX & 63, fr = lane & 15, fq = lane >> 4;
; #pragma unroll
;   for (int h = 0; h < 2; h++) {
; #pragma unroll
;     for (int ml = 0; ml < 4; ml++)
; #pragma unroll
;       for (int n = 0; n < 4; n++)
; #pragma unroll
;         for (int j = 0; j < 4; j++) stage_put(stg, ml, n, j, fr, fq, val(h * 4 + ml, n, j));
;     stage_flush(stg, h, rowptr, rowscale);
;   }
; }
	global_store_dwordx4 v[10:11], v[4:7], off nt
	s_nop 1
	v_or_b32_e32 v4, 32, v3
	v_mul_u32_u24_e32 v4, s2, v4
	v_lshlrev_b32_e32 v148, 1, v4
	v_lshl_add_u64 v[4:5], v[0:1], 0, v[148:149]
	v_lshl_add_u64 v[10:11], v[4:5], 0, v[8:9]
	ds_read_b128 v[4:7], v12 offset:4608
	s_waitcnt lgkmcnt(0)
	global_store_dwordx4 v[10:11], v[4:7], off nt
	s_nop 1
	v_or_b32_e32 v4, 40, v3
	v_mul_u32_u24_e32 v4, s2, v4
	v_lshlrev_b32_e32 v148, 1, v4
	v_lshl_add_u64 v[4:5], v[0:1], 0, v[148:149]
	v_lshl_add_u64 v[10:11], v[4:5], 0, v[8:9]
	ds_read_b128 v[4:7], v12 offset:5760
	s_waitcnt lgkmcnt(0)
	global_store_dwordx4 v[10:11], v[4:7], off nt
	s_nop 1
	v_or_b32_e32 v4, 48, v3
	v_mul_u32_u24_e32 v4, s2, v4
	v_lshlrev_b32_e32 v148, 1, v4
	v_lshl_add_u64 v[4:5], v[0:1], 0, v[148:149]
	v_lshl_add_u64 v[10:11], v[4:5], 0, v[8:9]
	ds_read_b128 v[4:7], v12 offset:6912
	v_or_b32_e32 v3, 56, v3
	v_mul_u32_u24_e32 v3, s2, v3
	v_lshlrev_b32_e32 v148, 1, v3
	v_cvt_f16_f32_e32 v3, v220
	s_waitcnt lgkmcnt(0)
	global_store_dwordx4 v[10:11], v[4:7], off nt
	s_nop 1
	v_lshl_add_u64 v[4:5], v[0:1], 0, v[148:149]
	v_lshl_add_u64 v[8:9], v[4:5], 0, v[8:9]
	ds_read_b128 v[4:7], v12 offset:8064
	s_waitcnt lgkmcnt(0)
	global_store_dwordx4 v[8:9], v[4:7], off nt
	ds_write_b16 v2, v3
	v_cvt_f16_f32_e32 v3, v219
	v_mov_b32_e32 v7, v149
	ds_write_b16 v2, v3 offset:144
	v_cvt_f16_f32_e32 v3, v218
	ds_write_b16 v2, v3 offset:288
	v_cvt_f16_f32_e32 v3, v217
	ds_write_b16 v2, v3 offset:432
	v_cvt_f16_f32_e32 v3, v216
	ds_write_b16 v2, v3 offset:32
	v_cvt_f16_f32_e32 v3, v215
	ds_write_b16 v2, v3 offset:176
	v_cvt_f16_f32_e32 v3, v214
	ds_write_b16 v2, v3 offset:320
	v_cvt_f16_f32_e32 v3, v213
	ds_write_b16 v2, v3 offset:464
	v_cvt_f16_f32_e32 v3, v212
	ds_write_b16 v2, v3 offset:64
	v_cvt_f16_f32_e32 v3, v211
	ds_write_b16 v2, v3 offset:208
	v_cvt_f16_f32_e32 v3, v210
	ds_write_b16 v2, v3 offset:352
	v_cvt_f16_f32_e32 v3, v209
	ds_write_b16 v2, v3 offset:496
	v_cvt_f16_f32_e32 v3, v208
	ds_write_b16 v2, v3 offset:96
	v_cvt_f16_f32_e32 v3, v207
	ds_write_b16 v2, v3 offset:240
	v_cvt_f16_f32_e32 v3, v206
	ds_write_b16 v2, v3 offset:384
	v_cvt_f16_f32_e32 v3, v205
	ds_write_b16 v2, v3 offset:528
	v_cvt_f16_f32_e32 v3, v204
	ds_write_b16 v2, v3 offset:2304
	v_cvt_f16_f32_e32 v3, v203
	ds_write_b16 v2, v3 offset:2448
	v_cvt_f16_f32_e32 v3, v202
	ds_write_b16 v2, v3 offset:2592
	v_cvt_f16_f32_e32 v3, v201
	ds_write_b16 v2, v3 offset:2736
	v_cvt_f16_f32_e32 v3, v200
	ds_write_b16 v2, v3 offset:2336
	v_cvt_f16_f32_e32 v3, v199
	ds_write_b16 v2, v3 offset:2480
	v_cvt_f16_f32_e32 v3, v198
	ds_write_b16 v2, v3 offset:2624
	v_cvt_f16_f32_e32 v3, v197
	ds_write_b16 v2, v3 offset:2768
	v_cvt_f16_f32_e32 v3, v171
	ds_write_b16 v2, v3 offset:2368
	v_cvt_f16_f32_e32 v3, v170
	ds_write_b16 v2, v3 offset:2512
	v_cvt_f16_f32_e32 v3, v169
	ds_write_b16 v2, v3 offset:2656
	v_cvt_f16_f32_e32 v3, v168
	ds_write_b16 v2, v3 offset:2800
	v_cvt_f16_f32_e32 v3, v167
	ds_write_b16 v2, v3 offset:2400
	v_cvt_f16_f32_e32 v3, v166
	ds_write_b16 v2, v3 offset:2544
	v_cvt_f16_f32_e32 v3, v165
	ds_write_b16 v2, v3 offset:2688
	v_cvt_f16_f32_e32 v3, v164
	ds_write_b16 v2, v3 offset:2832
	v_cvt_f16_f32_e32 v3, v163
	ds_write_b16 v2, v3 offset:4608
	v_cvt_f16_f32_e32 v3, v162
	ds_write_b16 v2, v3 offset:4752
	v_cvt_f16_f32_e32 v3, v161
	ds_write_b16 v2, v3 offset:4896
	v_cvt_f16_f32_e32 v3, v160
	ds_write_b16 v2, v3 offset:5040
	v_cvt_f16_f32_e32 v3, v159
	ds_write_b16 v2, v3 offset:4640
	v_cvt_f16_f32_e32 v3, v158
	ds_write_b16 v2, v3 offset:4784
	v_cvt_f16_f32_e32 v3, v157
	ds_write_b16 v2, v3 offset:4928
	v_cvt_f16_f32_e32 v3, v156
	ds_write_b16 v2, v3 offset:5072
	v_cvt_f16_f32_e32 v3, v155
	ds_write_b16 v2, v3 offset:4672
	v_cvt_f16_f32_e32 v3, v154
	ds_write_b16 v2, v3 offset:4816
	v_cvt_f16_f32_e32 v3, v153
	ds_write_b16 v2, v3 offset:4960
	v_cvt_f16_f32_e32 v3, v152
	ds_write_b16 v2, v3 offset:5104
	v_cvt_f16_f32_e32 v3, v151
	ds_write_b16 v2, v3 offset:4704
	v_cvt_f16_f32_e32 v3, v150
	ds_write_b16 v2, v3 offset:4848
	v_cvt_f16_f32_e32 v3, v147
	ds_write_b16 v2, v3 offset:4992
	v_cvt_f16_f32_e32 v3, v146
	ds_write_b16 v2, v3 offset:5136
	v_cvt_f16_f32_e32 v3, v145
	ds_write_b16 v2, v3 offset:6912
	v_cvt_f16_f32_e32 v3, v144
	ds_write_b16 v2, v3 offset:7056
	v_cvt_f16_f32_e32 v3, v143
	ds_write_b16 v2, v3 offset:7200
	v_cvt_f16_f32_e32 v3, v142
	ds_write_b16 v2, v3 offset:7344
	v_cvt_f16_f32_e32 v3, v141
	ds_write_b16 v2, v3 offset:6944
	v_cvt_f16_f32_e32 v3, v140
	ds_write_b16 v2, v3 offset:7088
	v_cvt_f16_f32_e32 v3, v138
	ds_write_b16 v2, v3 offset:7232
	v_cvt_f16_f32_e32 v3, v137
	ds_write_b16 v2, v3 offset:7376
	v_cvt_f16_f32_e32 v3, v136
	ds_write_b16 v2, v3 offset:6976
	v_cvt_f16_f32_e32 v3, v135
	ds_write_b16 v2, v3 offset:7120
	v_cvt_f16_f32_e32 v3, v134
	ds_write_b16 v2, v3 offset:7264
	v_cvt_f16_f32_e32 v3, v133
	ds_write_b16 v2, v3 offset:7408
	v_cvt_f16_f32_e32 v3, v132
	ds_write_b16 v2, v3 offset:7008
	v_cvt_f16_f32_e32 v3, v131
	ds_write_b16 v2, v3 offset:7152
	v_cvt_f16_f32_e32 v3, v130
	ds_write_b16 v2, v3 offset:7296
	v_cvt_f16_f32_e32 v3, v129
	ds_write_b16 v2, v3 offset:7440
	v_mov_b32_e32 v2, v172
	s_nop 0
	v_bfe_u32 v10, v2, 3, 3
	v_lshlrev_b32_e32 v3, 4, v2
	v_or_b32_e32 v2, 64, v10
	v_mul_u32_u24_e32 v2, s2, v2
	v_lshlrev_b32_e32 v148, 1, v2
	v_and_b32_e32 v6, 0x70, v3
	v_lshl_add_u64 v[2:3], v[0:1], 0, v[148:149]
	v_lshl_add_u64 v[8:9], v[2:3], 0, v[6:7]
	v_mul_u32_u24_e32 v2, 0x90, v10
	v_add3_u32 v11, v18, v6, v2
	ds_read_b128 v[2:5], v11
	s_waitcnt lgkmcnt(0)
; #define TIDX tid_opaque()
; DI float gelu_tanh(float x) {
;   float u = 0.7978845608028654f * (x + 0.044715f * x * x * x);
;   float e = __expf(2.f * u);
;   float t = 1.f - 2.f / (e + 1.f);
;   return 0.5f * x * (1.f + t);
; }
; template <class RP, class SC>
; DI void stage_flush(char* stg, int h, RP rowptr, SC rowscale) {
;   const int lane = TIDX & 63;
;   __builtin_amdgcn_wave_barrier();
; #pragma unroll
;   for (int i = 0; i < 8; i++) {
;     const int c = i * 64 + lane, row = c >> 3, c16 = c & 7;
;     h8 v = *(const h8*)(stg + row * 144 + c16 * 16);
;     half_t* d = rowptr(h * 64 + row);
;     if (d) { rowscale(h * 64 + row, v); *(h8*)(d + c16 * 8) = v; }
;   }
;   __builtin_amdgcn_wave_barrier();
; }
; template <class VF, class RP, class SC>
; DI void wave_store_tile(VF val, char* stg, RP rowptr, SC rowscale) {
;   const int lane = TIDX & 63, fr = lane & 15, fq = lane >> 4;
; #pragma unroll
;   for (int h = 0; h < 2; h++) {
; #pragma unroll
;     for (int ml = 0; ml < 4; ml++)
; #pragma unroll
;       for (int n = 0; n < 4; n++)
; #pragma unroll
;         for (int j = 0; j < 4; j++) stage_put(stg, ml, n, j, fr, fq, val(h * 4 + ml, n, j));
;     stage_flush(stg, h, rowptr, rowscale);
;   }
; }
	global_store_dwordx4 v[8:9], v[2:5], off nt
	s_nop 1
	v_or_b32_e32 v2, 0x48, v10
	v_mul_u32_u24_e32 v2, s2, v2
	v_lshlrev_b32_e32 v148, 1, v2
	v_lshl_add_u64 v[2:3], v[0:1], 0, v[148:149]
	v_lshl_add_u64 v[8:9], v[2:3], 0, v[6:7]
	ds_read_b128 v[2:5], v11 offset:1152
	s_waitcnt lgkmcnt(0)
	global_store_dwordx4 v[8:9], v[2:5], off nt
	s_nop 1
	v_or_b32_e32 v2, 0x50, v10
	v_mul_u32_u24_e32 v2, s2, v2
	v_lshlrev_b32_e32 v148, 1, v2
	v_lshl_add_u64 v[2:3], v[0:1], 0, v[148:149]
	v_lshl_add_u64 v[8:9], v[2:3], 0, v[6:7]
	ds_read_b128 v[2:5], v11 offset:2304
	s_waitcnt lgkmcnt(0)
	global_store_dwordx4 v[8:9], v[2:5], off nt
	s_nop 1
	v_or_b32_e32 v2, 0x58, v10
	v_mul_u32_u24_e32 v2, s2, v2
	v_lshlrev_b32_e32 v148, 1, v2
	v_lshl_add_u64 v[2:3], v[0:1], 0, v[148:149]
	v_lshl_add_u64 v[8:9], v[2:3], 0, v[6:7]
	ds_read_b128 v[2:5], v11 offset:3456
	s_waitcnt lgkmcnt(0)
	global_store_dwordx4 v[8:9], v[2:5], off nt
	s_nop 1
	v_or_b32_e32 v2, 0x60, v10
	v_mul_u32_u24_e32 v2, s2, v2
	v_lshlrev_b32_e32 v148, 1, v2
	v_lshl_add_u64 v[2:3], v[0:1], 0, v[148:149]
	v_lshl_add_u64 v[8:9], v[2:3], 0, v[6:7]
	ds_read_b128 v[2:5], v11 offset:4608
	s_waitcnt lgkmcnt(0)
	global_store_dwordx4 v[8:9], v[2:5], off nt
	s_nop 1
	v_or_b32_e32 v2, 0x68, v10
	v_mul_u32_u24_e32 v2, s2, v2
	v_lshlrev_b32_e32 v148, 1, v2
	v_lshl_add_u64 v[2:3], v[0:1], 0, v[148:149]
	v_lshl_add_u64 v[8:9], v[2:3], 0, v[6:7]
	ds_read_b128 v[2:5], v11 offset:5760
	s_waitcnt lgkmcnt(0)
	global_store_dwordx4 v[8:9], v[2:5], off nt
	s_nop 1
	v_or_b32_e32 v2, 0x70, v10
	v_mul_u32_u24_e32 v2, s2, v2
	v_lshlrev_b32_e32 v148, 1, v2
	v_lshl_add_u64 v[2:3], v[0:1], 0, v[148:149]
	v_lshl_add_u64 v[8:9], v[2:3], 0, v[6:7]
	ds_read_b128 v[2:5], v11 offset:6912
	s_waitcnt lgkmcnt(0)
	global_store_dwordx4 v[8:9], v[2:5], off nt
	s_nop 1
	v_or_b32_e32 v2, 0x78, v10
	v_mul_u32_u24_e32 v2, s2, v2
	v_lshlrev_b32_e32 v148, 1, v2
	v_lshl_add_u64 v[2:3], v[0:1], 0, v[148:149]
	v_lshl_add_u64 v[6:7], v[2:3], 0, v[6:7]
	ds_read_b128 v[2:5], v11 offset:8064
	s_waitcnt lgkmcnt(0)
	global_store_dwordx4 v[6:7], v[2:5], off nt
.LBB0_334:
	s_andn2_b64 vcc, exec, s[6:7]
	s_cbranch_vccnz .LBB0_224
	v_mul_f32_e32 v4, 0x3d372713, v105
	v_mul_f32_e32 v4, v105, v4
	v_fma_f32 v4, v105, v4, v105
	v_mul_f32_e32 v4, 0x3f4c422a, v4
	v_add_f32_e32 v4, v4, v4
	v_mul_f32_e32 v4, 0x3fb8aa3b, v4
	v_exp_f32_e32 v4, v4
	v_mov_b32_e32 v2, v172
	v_add_f32_e32 v4, 1.0, v4
	v_div_scale_f32 v5, s[6:7], v4, v4, 2.0
	v_rcp_f32_e32 v6, v5
	v_lshrrev_b32_e32 v3, 2, v2
	v_and_b32_e32 v3, 12, v3
	v_lshlrev_b32_e32 v2, 1, v2
	v_and_b32_e32 v2, 30, v2
	v_mul_u32_u24_e32 v3, 0x90, v3
	v_fma_f32 v7, -v5, v6, 1.0
	v_add3_u32 v2, v18, v2, v3
	v_mul_f32_e32 v3, 0x3d372713, v104
	v_fmac_f32_e32 v6, v7, v6
	v_div_scale_f32 v7, vcc, 2.0, v4, 2.0
	v_mul_f32_e32 v3, v104, v3
	v_mul_f32_e32 v8, v7, v6
	v_fma_f32 v3, v104, v3, v104
	v_fma_f32 v9, -v5, v8, v7
	v_mul_f32_e32 v3, 0x3f4c422a, v3
	v_fmac_f32_e32 v8, v9, v6
	v_add_f32_e32 v3, v3, v3
	v_fma_f32 v5, -v5, v8, v7
	v_mul_f32_e32 v3, 0x3fb8aa3b, v3
	v_div_fmas_f32 v5, v5, v6, v8
	v_exp_f32_e32 v3, v3
	v_div_fixup_f32 v4, v5, v4, 2.0
	v_sub_f32_e32 v4, 1.0, v4
	v_mul_f32_e32 v5, 0.5, v105
	v_add_f32_e32 v4, 1.0, v4
	v_fma_mixlo_f16 v4, v5, v4, 0
	v_add_f32_e32 v3, 1.0, v3
	ds_write_b16 v2, v4
	v_div_scale_f32 v4, s[6:7], v3, v3, 2.0
	v_rcp_f32_e32 v5, v4
	v_mov_b32_e32 v9, v149
	v_fma_f32 v6, -v4, v5, 1.0
	v_fmac_f32_e32 v5, v6, v5
	v_div_scale_f32 v6, vcc, 2.0, v3, 2.0
	v_mul_f32_e32 v7, v6, v5
	v_fma_f32 v8, -v4, v7, v6
	v_fmac_f32_e32 v7, v8, v5
	v_fma_f32 v4, -v4, v7, v6
	v_div_fmas_f32 v4, v4, v5, v7
	v_div_fixup_f32 v3, v4, v3, 2.0
	v_sub_f32_e32 v3, 1.0, v3
	v_mul_f32_e32 v4, 0.5, v104
	v_add_f32_e32 v3, 1.0, v3
	v_fma_mixlo_f16 v3, v4, v3, 0
	ds_write_b16 v2, v3 offset:144
	v_mul_f32_e32 v3, 0x3d372713, v139
	v_mul_f32_e32 v3, v139, v3
	v_fma_f32 v3, v139, v3, v139
	v_mul_f32_e32 v3, 0x3f4c422a, v3
	v_add_f32_e32 v3, v3, v3
	v_mul_f32_e32 v3, 0x3fb8aa3b, v3
	v_exp_f32_e32 v3, v3
	s_nop 0
	v_add_f32_e32 v3, 1.0, v3
	v_div_scale_f32 v4, s[6:7], v3, v3, 2.0
	v_rcp_f32_e32 v5, v4
	s_nop 0
	v_fma_f32 v6, -v4, v5, 1.0
	v_fmac_f32_e32 v5, v6, v5
	v_div_scale_f32 v6, vcc, 2.0, v3, 2.0
	v_mul_f32_e32 v7, v6, v5
	v_fma_f32 v8, -v4, v7, v6
	v_fmac_f32_e32 v7, v8, v5
	v_fma_f32 v4, -v4, v7, v6
	v_div_fmas_f32 v4, v4, v5, v7
	v_div_fixup_f32 v3, v4, v3, 2.0
	v_sub_f32_e32 v3, 1.0, v3
	v_mul_f32_e32 v4, 0.5, v139
	v_add_f32_e32 v3, 1.0, v3
	v_fma_mixlo_f16 v3, v4, v3, 0
	ds_write_b16 v2, v3 offset:288
	v_mul_f32_e32 v3, 0x3d372713, v121
	v_mul_f32_e32 v3, v121, v3
	v_fma_f32 v3, v121, v3, v121
	v_mul_f32_e32 v3, 0x3f4c422a, v3
	v_add_f32_e32 v3, v3, v3
	v_mul_f32_e32 v3, 0x3fb8aa3b, v3
	v_exp_f32_e32 v3, v3
	s_nop 0
	v_add_f32_e32 v3, 1.0, v3
	v_div_scale_f32 v4, s[6:7], v3, v3, 2.0
	v_rcp_f32_e32 v5, v4
	s_nop 0
	v_fma_f32 v6, -v4, v5, 1.0
	v_fmac_f32_e32 v5, v6, v5
	v_div_scale_f32 v6, vcc, 2.0, v3, 2.0
	v_mul_f32_e32 v7, v6, v5
	v_fma_f32 v8, -v4, v7, v6
	v_fmac_f32_e32 v7, v8, v5
	v_fma_f32 v4, -v4, v7, v6
	v_div_fmas_f32 v4, v4, v5, v7
	v_div_fixup_f32 v3, v4, v3, 2.0
	v_sub_f32_e32 v3, 1.0, v3
	v_mul_f32_e32 v4, 0.5, v121
	v_add_f32_e32 v3, 1.0, v3
	v_fma_mixlo_f16 v3, v4, v3, 0
	ds_write_b16 v2, v3 offset:432
	v_mul_f32_e32 v3, 0x3d372713, v120
	v_mul_f32_e32 v3, v120, v3
	v_fma_f32 v3, v120, v3, v120
	v_mul_f32_e32 v3, 0x3f4c422a, v3
	v_add_f32_e32 v3, v3, v3
	v_mul_f32_e32 v3, 0x3fb8aa3b, v3
	v_exp_f32_e32 v3, v3
	s_nop 0
	v_add_f32_e32 v3, 1.0, v3
	v_div_scale_f32 v4, s[6:7], v3, v3, 2.0
	v_rcp_f32_e32 v5, v4
	s_nop 0
	v_fma_f32 v6, -v4, v5, 1.0
	v_fmac_f32_e32 v5, v6, v5
	v_div_scale_f32 v6, vcc, 2.0, v3, 2.0
; DI float gelu_tanh(float x) {
;   float u = 0.7978845608028654f * (x + 0.044715f * x * x * x);
;   float e = __expf(2.f * u);
;   float t = 1.f - 2.f / (e + 1.f);
;   return 0.5f * x * (1.f + t);
; }
; DI void gemm_in_phase(const Params& P, int l, char* smem) {
;     ...
;       if (gel) wave_store_tile([&](int m, int n, int j) { return gelu_tanh(acc[m][n][j]); }, stg, [&](int r) { return base + (size_t)r * ld; }, noscale);
	v_mul_f32_e32 v7, v6, v5
	v_fma_f32 v8, -v4, v7, v6
	v_fmac_f32_e32 v7, v8, v5
	v_fma_f32 v4, -v4, v7, v6
	v_div_fmas_f32 v4, v4, v5, v7
	v_div_fixup_f32 v3, v4, v3, 2.0
	v_sub_f32_e32 v3, 1.0, v3
	v_mul_f32_e32 v4, 0.5, v120
	v_add_f32_e32 v3, 1.0, v3
	v_fma_mixlo_f16 v3, v4, v3, 0
	ds_write_b16 v2, v3 offset:32
	v_mul_f32_e32 v3, 0x3d372713, v190
	v_mul_f32_e32 v3, v190, v3
	v_fma_f32 v3, v190, v3, v190
	v_mul_f32_e32 v3, 0x3f4c422a, v3
	v_add_f32_e32 v3, v3, v3
	v_mul_f32_e32 v3, 0x3fb8aa3b, v3
	v_exp_f32_e32 v3, v3
	s_nop 0
	v_add_f32_e32 v3, 1.0, v3
	v_div_scale_f32 v4, s[6:7], v3, v3, 2.0
	v_rcp_f32_e32 v5, v4
	s_nop 0
	v_fma_f32 v6, -v4, v5, 1.0
	v_fmac_f32_e32 v5, v6, v5
	v_div_scale_f32 v6, vcc, 2.0, v3, 2.0
	v_mul_f32_e32 v7, v6, v5
	v_fma_f32 v8, -v4, v7, v6
	v_fmac_f32_e32 v7, v8, v5
	v_fma_f32 v4, -v4, v7, v6
	v_div_fmas_f32 v4, v4, v5, v7
	v_div_fixup_f32 v3, v4, v3, 2.0
	v_sub_f32_e32 v3, 1.0, v3
	v_mul_f32_e32 v4, 0.5, v190
	v_add_f32_e32 v3, 1.0, v3
	v_fma_mixlo_f16 v3, v4, v3, 0
	ds_write_b16 v2, v3 offset:176
	v_mul_f32_e32 v3, 0x3d372713, v175
	v_mul_f32_e32 v3, v175, v3
	v_fma_f32 v3, v175, v3, v175
	v_mul_f32_e32 v3, 0x3f4c422a, v3
	v_add_f32_e32 v3, v3, v3
	v_mul_f32_e32 v3, 0x3fb8aa3b, v3
	v_exp_f32_e32 v3, v3
	s_nop 0
	v_add_f32_e32 v3, 1.0, v3
	v_div_scale_f32 v4, s[6:7], v3, v3, 2.0
	v_rcp_f32_e32 v5, v4
	s_nop 0
	v_fma_f32 v6, -v4, v5, 1.0
	v_fmac_f32_e32 v5, v6, v5
	v_div_scale_f32 v6, vcc, 2.0, v3, 2.0
	v_mul_f32_e32 v7, v6, v5
	v_fma_f32 v8, -v4, v7, v6
	v_fmac_f32_e32 v7, v8, v5
	v_fma_f32 v4, -v4, v7, v6
	v_div_fmas_f32 v4, v4, v5, v7
	v_div_fixup_f32 v3, v4, v3, 2.0
	v_sub_f32_e32 v3, 1.0, v3
	v_mul_f32_e32 v4, 0.5, v175
	v_add_f32_e32 v3, 1.0, v3
	v_fma_mixlo_f16 v3, v4, v3, 0
	ds_write_b16 v2, v3 offset:320
	v_mul_f32_e32 v3, 0x3d372713, v128
	v_mul_f32_e32 v3, v128, v3
	v_fma_f32 v3, v128, v3, v128
	v_mul_f32_e32 v3, 0x3f4c422a, v3
	v_add_f32_e32 v3, v3, v3
	v_mul_f32_e32 v3, 0x3fb8aa3b, v3
	v_exp_f32_e32 v3, v3
	s_nop 0
	v_add_f32_e32 v3, 1.0, v3
	v_div_scale_f32 v4, s[6:7], v3, v3, 2.0
	v_rcp_f32_e32 v5, v4
	s_nop 0
	v_fma_f32 v6, -v4, v5, 1.0
	v_fmac_f32_e32 v5, v6, v5
	v_div_scale_f32 v6, vcc, 2.0, v3, 2.0
	v_mul_f32_e32 v7, v6, v5
	v_fma_f32 v8, -v4, v7, v6
	v_fmac_f32_e32 v7, v8, v5
	v_fma_f32 v4, -v4, v7, v6
	v_div_fmas_f32 v4, v4, v5, v7
	v_div_fixup_f32 v3, v4, v3, 2.0
	v_sub_f32_e32 v3, 1.0, v3
	v_mul_f32_e32 v4, 0.5, v128
	v_add_f32_e32 v3, 1.0, v3
	v_fma_mixlo_f16 v3, v4, v3, 0
	ds_write_b16 v2, v3 offset:464
	v_mul_f32_e32 v3, 0x3d372713, v195
	v_mul_f32_e32 v3, v195, v3
	v_fma_f32 v3, v195, v3, v195
	v_mul_f32_e32 v3, 0x3f4c422a, v3
	v_add_f32_e32 v3, v3, v3
	v_mul_f32_e32 v3, 0x3fb8aa3b, v3
	v_exp_f32_e32 v3, v3
	s_nop 0
	v_add_f32_e32 v3, 1.0, v3
	v_div_scale_f32 v4, s[6:7], v3, v3, 2.0
	v_rcp_f32_e32 v5, v4
	s_nop 0
	v_fma_f32 v6, -v4, v5, 1.0
	v_fmac_f32_e32 v5, v6, v5
	v_div_scale_f32 v6, vcc, 2.0, v3, 2.0
	v_mul_f32_e32 v7, v6, v5
	v_fma_f32 v8, -v4, v7, v6
	v_fmac_f32_e32 v7, v8, v5
	v_fma_f32 v4, -v4, v7, v6
	v_div_fmas_f32 v4, v4, v5, v7
	v_div_fixup_f32 v3, v4, v3, 2.0
	v_sub_f32_e32 v3, 1.0, v3
	v_mul_f32_e32 v4, 0.5, v195
	v_add_f32_e32 v3, 1.0, v3
	v_fma_mixlo_f16 v3, v4, v3, 0
	ds_write_b16 v2, v3 offset:64
	v_mul_f32_e32 v3, 0x3d372713, v103
	v_mul_f32_e32 v3, v103, v3
	v_fma_f32 v3, v103, v3, v103
	v_mul_f32_e32 v3, 0x3f4c422a, v3
	v_add_f32_e32 v3, v3, v3
	v_mul_f32_e32 v3, 0x3fb8aa3b, v3
	v_exp_f32_e32 v3, v3
	s_nop 0
	v_add_f32_e32 v3, 1.0, v3
	v_div_scale_f32 v4, s[6:7], v3, v3, 2.0
	v_rcp_f32_e32 v5, v4
	s_nop 0
	v_fma_f32 v6, -v4, v5, 1.0
	v_fmac_f32_e32 v5, v6, v5
	v_div_scale_f32 v6, vcc, 2.0, v3, 2.0
	v_mul_f32_e32 v7, v6, v5
	v_fma_f32 v8, -v4, v7, v6
	v_fmac_f32_e32 v7, v8, v5
	v_fma_f32 v4, -v4, v7, v6
	v_div_fmas_f32 v4, v4, v5, v7
	v_div_fixup_f32 v3, v4, v3, 2.0
	v_sub_f32_e32 v3, 1.0, v3
	v_mul_f32_e32 v4, 0.5, v103
	v_add_f32_e32 v3, 1.0, v3
	v_fma_mixlo_f16 v3, v4, v3, 0
	ds_write_b16 v2, v3 offset:208
	v_mul_f32_e32 v3, 0x3d372713, v102
	v_mul_f32_e32 v3, v102, v3
	v_fma_f32 v3, v102, v3, v102
	v_mul_f32_e32 v3, 0x3f4c422a, v3
	v_add_f32_e32 v3, v3, v3
	v_mul_f32_e32 v3, 0x3fb8aa3b, v3
	v_exp_f32_e32 v3, v3
	s_nop 0
	v_add_f32_e32 v3, 1.0, v3
	v_div_scale_f32 v4, s[6:7], v3, v3, 2.0
	v_rcp_f32_e32 v5, v4
	s_nop 0
	v_fma_f32 v6, -v4, v5, 1.0
	v_fmac_f32_e32 v5, v6, v5
	v_div_scale_f32 v6, vcc, 2.0, v3, 2.0
	v_mul_f32_e32 v7, v6, v5
	v_fma_f32 v8, -v4, v7, v6
	v_fmac_f32_e32 v7, v8, v5
	v_fma_f32 v4, -v4, v7, v6
	v_div_fmas_f32 v4, v4, v5, v7
	v_div_fixup_f32 v3, v4, v3, 2.0
	v_sub_f32_e32 v3, 1.0, v3
	v_mul_f32_e32 v4, 0.5, v102
	v_add_f32_e32 v3, 1.0, v3
	v_fma_mixlo_f16 v3, v4, v3, 0
	ds_write_b16 v2, v3 offset:352
	v_mul_f32_e32 v3, 0x3d372713, v101
	v_mul_f32_e32 v3, v101, v3
	v_fma_f32 v3, v101, v3, v101
	v_mul_f32_e32 v3, 0x3f4c422a, v3
	v_add_f32_e32 v3, v3, v3
	v_mul_f32_e32 v3, 0x3fb8aa3b, v3
	v_exp_f32_e32 v3, v3
	s_nop 0
	v_add_f32_e32 v3, 1.0, v3
	v_div_scale_f32 v4, s[6:7], v3, v3, 2.0
	v_rcp_f32_e32 v5, v4
	s_nop 0
	v_fma_f32 v6, -v4, v5, 1.0
	v_fmac_f32_e32 v5, v6, v5
	v_div_scale_f32 v6, vcc, 2.0, v3, 2.0
	v_mul_f32_e32 v7, v6, v5
	v_fma_f32 v8, -v4, v7, v6
	v_fmac_f32_e32 v7, v8, v5
	v_fma_f32 v4, -v4, v7, v6
	v_div_fmas_f32 v4, v4, v5, v7
	v_div_fixup_f32 v3, v4, v3, 2.0
	v_sub_f32_e32 v3, 1.0, v3
	v_mul_f32_e32 v4, 0.5, v101
	v_add_f32_e32 v3, 1.0, v3
	v_fma_mixlo_f16 v3, v4, v3, 0
	ds_write_b16 v2, v3 offset:496
	v_mul_f32_e32 v3, 0x3d372713, v100
	v_mul_f32_e32 v3, v100, v3
	v_fma_f32 v3, v100, v3, v100
	v_mul_f32_e32 v3, 0x3f4c422a, v3
	v_add_f32_e32 v3, v3, v3
	v_mul_f32_e32 v3, 0x3fb8aa3b, v3
	v_exp_f32_e32 v3, v3
	s_nop 0
; DI float gelu_tanh(float x) {
;   float u = 0.7978845608028654f * (x + 0.044715f * x * x * x);
;   float e = __expf(2.f * u);
;   float t = 1.f - 2.f / (e + 1.f);
;   return 0.5f * x * (1.f + t);
; }
; DI void gemm_in_phase(const Params& P, int l, char* smem) {
;     ...
;       if (gel) wave_store_tile([&](int m, int n, int j) { return gelu_tanh(acc[m][n][j]); }, stg, [&](int r) { return base + (size_t)r * ld; }, noscale);
	v_add_f32_e32 v3, 1.0, v3
	v_div_scale_f32 v4, s[6:7], v3, v3, 2.0
	v_rcp_f32_e32 v5, v4
	s_nop 0
	v_fma_f32 v6, -v4, v5, 1.0
	v_fmac_f32_e32 v5, v6, v5
	v_div_scale_f32 v6, vcc, 2.0, v3, 2.0
	v_mul_f32_e32 v7, v6, v5
	v_fma_f32 v8, -v4, v7, v6
	v_fmac_f32_e32 v7, v8, v5
	v_fma_f32 v4, -v4, v7, v6
	v_div_fmas_f32 v4, v4, v5, v7
	v_div_fixup_f32 v3, v4, v3, 2.0
	v_sub_f32_e32 v3, 1.0, v3
	v_mul_f32_e32 v4, 0.5, v100
	v_add_f32_e32 v3, 1.0, v3
	v_fma_mixlo_f16 v3, v4, v3, 0
	ds_write_b16 v2, v3 offset:96
	v_mul_f32_e32 v3, 0x3d372713, v179
	v_mul_f32_e32 v3, v179, v3
	v_fma_f32 v3, v179, v3, v179
	v_mul_f32_e32 v3, 0x3f4c422a, v3
	v_add_f32_e32 v3, v3, v3
	v_mul_f32_e32 v3, 0x3fb8aa3b, v3
	v_exp_f32_e32 v3, v3
	s_nop 0
	v_add_f32_e32 v3, 1.0, v3
	v_div_scale_f32 v4, s[6:7], v3, v3, 2.0
	v_rcp_f32_e32 v5, v4
	s_nop 0
	v_fma_f32 v6, -v4, v5, 1.0
	v_fmac_f32_e32 v5, v6, v5
	v_div_scale_f32 v6, vcc, 2.0, v3, 2.0
	v_mul_f32_e32 v7, v6, v5
	v_fma_f32 v8, -v4, v7, v6
	v_fmac_f32_e32 v7, v8, v5
	v_fma_f32 v4, -v4, v7, v6
	v_div_fmas_f32 v4, v4, v5, v7
	v_div_fixup_f32 v3, v4, v3, 2.0
	v_sub_f32_e32 v3, 1.0, v3
	v_mul_f32_e32 v4, 0.5, v179
	v_add_f32_e32 v3, 1.0, v3
	v_fma_mixlo_f16 v3, v4, v3, 0
	ds_write_b16 v2, v3 offset:240
	v_mul_f32_e32 v3, 0x3d372713, v192
	v_mul_f32_e32 v3, v192, v3
	v_fma_f32 v3, v192, v3, v192
	v_mul_f32_e32 v3, 0x3f4c422a, v3
	v_add_f32_e32 v3, v3, v3
	v_mul_f32_e32 v3, 0x3fb8aa3b, v3
	v_exp_f32_e32 v3, v3
	s_nop 0
	v_add_f32_e32 v3, 1.0, v3
	v_div_scale_f32 v4, s[6:7], v3, v3, 2.0
	v_rcp_f32_e32 v5, v4
	s_nop 0
	v_fma_f32 v6, -v4, v5, 1.0
	v_fmac_f32_e32 v5, v6, v5
	v_div_scale_f32 v6, vcc, 2.0, v3, 2.0
	v_mul_f32_e32 v7, v6, v5
	v_fma_f32 v8, -v4, v7, v6
	v_fmac_f32_e32 v7, v8, v5
	v_fma_f32 v4, -v4, v7, v6
	v_div_fmas_f32 v4, v4, v5, v7
	v_div_fixup_f32 v3, v4, v3, 2.0
	v_sub_f32_e32 v3, 1.0, v3
	v_mul_f32_e32 v4, 0.5, v192
	v_add_f32_e32 v3, 1.0, v3
	v_fma_mixlo_f16 v3, v4, v3, 0
	ds_write_b16 v2, v3 offset:384
	v_mul_f32_e32 v3, 0x3d372713, v196
	v_mul_f32_e32 v3, v196, v3
	v_fma_f32 v3, v196, v3, v196
	v_mul_f32_e32 v3, 0x3f4c422a, v3
	v_add_f32_e32 v3, v3, v3
	v_mul_f32_e32 v3, 0x3fb8aa3b, v3
	v_exp_f32_e32 v3, v3
	s_nop 0
	v_add_f32_e32 v3, 1.0, v3
	v_div_scale_f32 v4, s[6:7], v3, v3, 2.0
	v_rcp_f32_e32 v5, v4
	s_nop 0
	v_fma_f32 v6, -v4, v5, 1.0
	v_fmac_f32_e32 v5, v6, v5
	v_div_scale_f32 v6, vcc, 2.0, v3, 2.0
	v_mul_f32_e32 v7, v6, v5
	v_fma_f32 v8, -v4, v7, v6
	v_fmac_f32_e32 v7, v8, v5
	v_fma_f32 v4, -v4, v7, v6
	v_div_fmas_f32 v4, v4, v5, v7
	v_div_fixup_f32 v3, v4, v3, 2.0
	v_sub_f32_e32 v3, 1.0, v3
	v_mul_f32_e32 v4, 0.5, v196
	v_add_f32_e32 v3, 1.0, v3
	v_fma_mixlo_f16 v3, v4, v3, 0
	ds_write_b16 v2, v3 offset:528
	v_mul_f32_e32 v3, 0x3d372713, v180
	v_mul_f32_e32 v3, v180, v3
	v_fma_f32 v3, v180, v3, v180
	v_mul_f32_e32 v3, 0x3f4c422a, v3
	v_add_f32_e32 v3, v3, v3
	v_mul_f32_e32 v3, 0x3fb8aa3b, v3
	v_exp_f32_e32 v3, v3
	s_nop 0
	v_add_f32_e32 v3, 1.0, v3
	v_div_scale_f32 v4, s[6:7], v3, v3, 2.0
	v_rcp_f32_e32 v5, v4
	s_nop 0
	v_fma_f32 v6, -v4, v5, 1.0
	v_fmac_f32_e32 v5, v6, v5
	v_div_scale_f32 v6, vcc, 2.0, v3, 2.0
	v_mul_f32_e32 v7, v6, v5
	v_fma_f32 v8, -v4, v7, v6
	v_fmac_f32_e32 v7, v8, v5
	v_fma_f32 v4, -v4, v7, v6
	v_div_fmas_f32 v4, v4, v5, v7
	v_div_fixup_f32 v3, v4, v3, 2.0
	v_sub_f32_e32 v3, 1.0, v3
	v_mul_f32_e32 v4, 0.5, v180
	v_add_f32_e32 v3, 1.0, v3
	v_fma_mixlo_f16 v3, v4, v3, 0
	ds_write_b16 v2, v3 offset:2304
	v_mul_f32_e32 v3, 0x3d372713, v173
	v_mul_f32_e32 v3, v173, v3
	v_fma_f32 v3, v173, v3, v173
	v_mul_f32_e32 v3, 0x3f4c422a, v3
	v_add_f32_e32 v3, v3, v3
	v_mul_f32_e32 v3, 0x3fb8aa3b, v3
	v_exp_f32_e32 v3, v3
	s_nop 0
	v_add_f32_e32 v3, 1.0, v3
	v_div_scale_f32 v4, s[6:7], v3, v3, 2.0
	v_rcp_f32_e32 v5, v4
	s_nop 0
	v_fma_f32 v6, -v4, v5, 1.0
	v_fmac_f32_e32 v5, v6, v5
	v_div_scale_f32 v6, vcc, 2.0, v3, 2.0
	v_mul_f32_e32 v7, v6, v5
	v_fma_f32 v8, -v4, v7, v6
	v_fmac_f32_e32 v7, v8, v5
	v_fma_f32 v4, -v4, v7, v6
	v_div_fmas_f32 v4, v4, v5, v7
	v_div_fixup_f32 v3, v4, v3, 2.0
	v_sub_f32_e32 v3, 1.0, v3
	v_mul_f32_e32 v4, 0.5, v173
	v_add_f32_e32 v3, 1.0, v3
	v_fma_mixlo_f16 v3, v4, v3, 0
	ds_write_b16 v2, v3 offset:2448
	v_mul_f32_e32 v3, 0x3d372713, v174
	v_mul_f32_e32 v3, v174, v3
	v_fma_f32 v3, v174, v3, v174
	v_mul_f32_e32 v3, 0x3f4c422a, v3
	v_add_f32_e32 v3, v3, v3
	v_mul_f32_e32 v3, 0x3fb8aa3b, v3
	v_exp_f32_e32 v3, v3
	s_nop 0
	v_add_f32_e32 v3, 1.0, v3
	v_div_scale_f32 v4, s[6:7], v3, v3, 2.0
	v_rcp_f32_e32 v5, v4
	s_nop 0
	v_fma_f32 v6, -v4, v5, 1.0
	v_fmac_f32_e32 v5, v6, v5
	v_div_scale_f32 v6, vcc, 2.0, v3, 2.0
	v_mul_f32_e32 v7, v6, v5
	v_fma_f32 v8, -v4, v7, v6
	v_fmac_f32_e32 v7, v8, v5
	v_fma_f32 v4, -v4, v7, v6
	v_div_fmas_f32 v4, v4, v5, v7
	v_div_fixup_f32 v3, v4, v3, 2.0
	v_sub_f32_e32 v3, 1.0, v3
	v_mul_f32_e32 v4, 0.5, v174
	v_add_f32_e32 v3, 1.0, v3
	v_fma_mixlo_f16 v3, v4, v3, 0
	ds_write_b16 v2, v3 offset:2592
	v_mul_f32_e32 v3, 0x3d372713, v191
	v_mul_f32_e32 v3, v191, v3
	v_fma_f32 v3, v191, v3, v191
	v_mul_f32_e32 v3, 0x3f4c422a, v3
	v_add_f32_e32 v3, v3, v3
	v_mul_f32_e32 v3, 0x3fb8aa3b, v3
	v_exp_f32_e32 v3, v3
	s_nop 0
	v_add_f32_e32 v3, 1.0, v3
	v_div_scale_f32 v4, s[6:7], v3, v3, 2.0
	v_rcp_f32_e32 v5, v4
	s_nop 0
	v_fma_f32 v6, -v4, v5, 1.0
	v_fmac_f32_e32 v5, v6, v5
	v_div_scale_f32 v6, vcc, 2.0, v3, 2.0
	v_mul_f32_e32 v7, v6, v5
	v_fma_f32 v8, -v4, v7, v6
	v_fmac_f32_e32 v7, v8, v5
	v_fma_f32 v4, -v4, v7, v6
	v_div_fmas_f32 v4, v4, v5, v7
	v_div_fixup_f32 v3, v4, v3, 2.0
	v_sub_f32_e32 v3, 1.0, v3
	v_mul_f32_e32 v4, 0.5, v191
	v_add_f32_e32 v3, 1.0, v3
	v_fma_mixlo_f16 v3, v4, v3, 0
	ds_write_b16 v2, v3 offset:2736
	v_mul_f32_e32 v3, 0x3d372713, v194
; DI float gelu_tanh(float x) {
;   float u = 0.7978845608028654f * (x + 0.044715f * x * x * x);
;   float e = __expf(2.f * u);
;   float t = 1.f - 2.f / (e + 1.f);
;   return 0.5f * x * (1.f + t);
; }
; DI void gemm_in_phase(const Params& P, int l, char* smem) {
;     ...
;       if (gel) wave_store_tile([&](int m, int n, int j) { return gelu_tanh(acc[m][n][j]); }, stg, [&](int r) { return base + (size_t)r * ld; }, noscale);
	v_mul_f32_e32 v3, v194, v3
	v_fma_f32 v3, v194, v3, v194
	v_mul_f32_e32 v3, 0x3f4c422a, v3
	v_add_f32_e32 v3, v3, v3
	v_mul_f32_e32 v3, 0x3fb8aa3b, v3
	v_exp_f32_e32 v3, v3
	s_nop 0
	v_add_f32_e32 v3, 1.0, v3
	v_div_scale_f32 v4, s[6:7], v3, v3, 2.0
	v_rcp_f32_e32 v5, v4
	s_nop 0
	v_fma_f32 v6, -v4, v5, 1.0
	v_fmac_f32_e32 v5, v6, v5
	v_div_scale_f32 v6, vcc, 2.0, v3, 2.0
	v_mul_f32_e32 v7, v6, v5
	v_fma_f32 v8, -v4, v7, v6
	v_fmac_f32_e32 v7, v8, v5
	v_fma_f32 v4, -v4, v7, v6
	v_div_fmas_f32 v4, v4, v5, v7
	v_div_fixup_f32 v3, v4, v3, 2.0
	v_sub_f32_e32 v3, 1.0, v3
	v_mul_f32_e32 v4, 0.5, v194
	v_add_f32_e32 v3, 1.0, v3
	v_fma_mixlo_f16 v3, v4, v3, 0
	ds_write_b16 v2, v3 offset:2336
	v_mul_f32_e32 v3, 0x3d372713, v193
	v_mul_f32_e32 v3, v193, v3
	v_fma_f32 v3, v193, v3, v193
	v_mul_f32_e32 v3, 0x3f4c422a, v3
	v_add_f32_e32 v3, v3, v3
	v_mul_f32_e32 v3, 0x3fb8aa3b, v3
	v_exp_f32_e32 v3, v3
	s_nop 0
	v_add_f32_e32 v3, 1.0, v3
	v_div_scale_f32 v4, s[6:7], v3, v3, 2.0
	v_rcp_f32_e32 v5, v4
	s_nop 0
	v_fma_f32 v6, -v4, v5, 1.0
	v_fmac_f32_e32 v5, v6, v5
	v_div_scale_f32 v6, vcc, 2.0, v3, 2.0
	v_mul_f32_e32 v7, v6, v5
	v_fma_f32 v8, -v4, v7, v6
	v_fmac_f32_e32 v7, v8, v5
	v_fma_f32 v4, -v4, v7, v6
	v_div_fmas_f32 v4, v4, v5, v7
	v_div_fixup_f32 v3, v4, v3, 2.0
	v_sub_f32_e32 v3, 1.0, v3
	v_mul_f32_e32 v4, 0.5, v193
	v_add_f32_e32 v3, 1.0, v3
	v_fma_mixlo_f16 v3, v4, v3, 0
	ds_write_b16 v2, v3 offset:2480
	v_mul_f32_e32 v3, 0x3d372713, v176
	v_mul_f32_e32 v3, v176, v3
	v_fma_f32 v3, v176, v3, v176
	v_mul_f32_e32 v3, 0x3f4c422a, v3
	v_add_f32_e32 v3, v3, v3
	v_mul_f32_e32 v3, 0x3fb8aa3b, v3
	v_exp_f32_e32 v3, v3
	s_nop 0
	v_add_f32_e32 v3, 1.0, v3
	v_div_scale_f32 v4, s[6:7], v3, v3, 2.0
	v_rcp_f32_e32 v5, v4
	s_nop 0
	v_fma_f32 v6, -v4, v5, 1.0
	v_fmac_f32_e32 v5, v6, v5
	v_div_scale_f32 v6, vcc, 2.0, v3, 2.0
	v_mul_f32_e32 v7, v6, v5
	v_fma_f32 v8, -v4, v7, v6
	v_fmac_f32_e32 v7, v8, v5
	v_fma_f32 v4, -v4, v7, v6
	v_div_fmas_f32 v4, v4, v5, v7
	v_div_fixup_f32 v3, v4, v3, 2.0
	v_sub_f32_e32 v3, 1.0, v3
	v_mul_f32_e32 v4, 0.5, v176
	v_add_f32_e32 v3, 1.0, v3
	v_fma_mixlo_f16 v3, v4, v3, 0
	ds_write_b16 v2, v3 offset:2624
	v_mul_f32_e32 v3, 0x3d372713, v189
	v_mul_f32_e32 v3, v189, v3
	v_fma_f32 v3, v189, v3, v189
	v_mul_f32_e32 v3, 0x3f4c422a, v3
	v_add_f32_e32 v3, v3, v3
	v_mul_f32_e32 v3, 0x3fb8aa3b, v3
	v_exp_f32_e32 v3, v3
	s_nop 0
	v_add_f32_e32 v3, 1.0, v3
	v_div_scale_f32 v4, s[6:7], v3, v3, 2.0
	v_rcp_f32_e32 v5, v4
	s_nop 0
	v_fma_f32 v6, -v4, v5, 1.0
	v_fmac_f32_e32 v5, v6, v5
	v_div_scale_f32 v6, vcc, 2.0, v3, 2.0
	v_mul_f32_e32 v7, v6, v5
	v_fma_f32 v8, -v4, v7, v6
	v_fmac_f32_e32 v7, v8, v5
	v_fma_f32 v4, -v4, v7, v6
	v_div_fmas_f32 v4, v4, v5, v7
	v_div_fixup_f32 v3, v4, v3, 2.0
	v_sub_f32_e32 v3, 1.0, v3
	v_mul_f32_e32 v4, 0.5, v189
	v_add_f32_e32 v3, 1.0, v3
	v_fma_mixlo_f16 v3, v4, v3, 0
	ds_write_b16 v2, v3 offset:2768
	v_mul_f32_e32 v3, 0x3d372713, v188
	v_mul_f32_e32 v3, v188, v3
	v_fma_f32 v3, v188, v3, v188
	v_mul_f32_e32 v3, 0x3f4c422a, v3
	v_add_f32_e32 v3, v3, v3
	v_mul_f32_e32 v3, 0x3fb8aa3b, v3
	v_exp_f32_e32 v3, v3
	s_nop 0
	v_add_f32_e32 v3, 1.0, v3
	v_div_scale_f32 v4, s[6:7], v3, v3, 2.0
	v_rcp_f32_e32 v5, v4
	s_nop 0
	v_fma_f32 v6, -v4, v5, 1.0
	v_fmac_f32_e32 v5, v6, v5
	v_div_scale_f32 v6, vcc, 2.0, v3, 2.0
	v_mul_f32_e32 v7, v6, v5
	v_fma_f32 v8, -v4, v7, v6
	v_fmac_f32_e32 v7, v8, v5
	v_fma_f32 v4, -v4, v7, v6
	v_div_fmas_f32 v4, v4, v5, v7
	v_div_fixup_f32 v3, v4, v3, 2.0
	v_sub_f32_e32 v3, 1.0, v3
	v_mul_f32_e32 v4, 0.5, v188
	v_add_f32_e32 v3, 1.0, v3
	v_fma_mixlo_f16 v3, v4, v3, 0
	ds_write_b16 v2, v3 offset:2368
	v_mul_f32_e32 v3, 0x3d372713, v187
	v_mul_f32_e32 v3, v187, v3
	v_fma_f32 v3, v187, v3, v187
	v_mul_f32_e32 v3, 0x3f4c422a, v3
	v_add_f32_e32 v3, v3, v3
	v_mul_f32_e32 v3, 0x3fb8aa3b, v3
	v_exp_f32_e32 v3, v3
	s_nop 0
	v_add_f32_e32 v3, 1.0, v3
	v_div_scale_f32 v4, s[6:7], v3, v3, 2.0
	v_rcp_f32_e32 v5, v4
	s_nop 0
	v_fma_f32 v6, -v4, v5, 1.0
	v_fmac_f32_e32 v5, v6, v5
	v_div_scale_f32 v6, vcc, 2.0, v3, 2.0
	v_mul_f32_e32 v7, v6, v5
	v_fma_f32 v8, -v4, v7, v6
	v_fmac_f32_e32 v7, v8, v5
	v_fma_f32 v4, -v4, v7, v6
	v_div_fmas_f32 v4, v4, v5, v7
	v_div_fixup_f32 v3, v4, v3, 2.0
	v_sub_f32_e32 v3, 1.0, v3
	v_mul_f32_e32 v4, 0.5, v187
	v_add_f32_e32 v3, 1.0, v3
	v_fma_mixlo_f16 v3, v4, v3, 0
	ds_write_b16 v2, v3 offset:2512
	v_mul_f32_e32 v3, 0x3d372713, v186
	v_mul_f32_e32 v3, v186, v3
	v_fma_f32 v3, v186, v3, v186
	v_mul_f32_e32 v3, 0x3f4c422a, v3
	v_add_f32_e32 v3, v3, v3
	v_mul_f32_e32 v3, 0x3fb8aa3b, v3
	v_exp_f32_e32 v3, v3
	s_nop 0
	v_add_f32_e32 v3, 1.0, v3
	v_div_scale_f32 v4, s[6:7], v3, v3, 2.0
	v_rcp_f32_e32 v5, v4
	s_nop 0
	v_fma_f32 v6, -v4, v5, 1.0
	v_fmac_f32_e32 v5, v6, v5
	v_div_scale_f32 v6, vcc, 2.0, v3, 2.0
	v_mul_f32_e32 v7, v6, v5
	v_fma_f32 v8, -v4, v7, v6
	v_fmac_f32_e32 v7, v8, v5
	v_fma_f32 v4, -v4, v7, v6
	v_div_fmas_f32 v4, v4, v5, v7
	v_div_fixup_f32 v3, v4, v3, 2.0
	v_sub_f32_e32 v3, 1.0, v3
	v_mul_f32_e32 v4, 0.5, v186
	v_add_f32_e32 v3, 1.0, v3
	v_fma_mixlo_f16 v3, v4, v3, 0
	ds_write_b16 v2, v3 offset:2656
	v_mul_f32_e32 v3, 0x3d372713, v185
	v_mul_f32_e32 v3, v185, v3
	v_fma_f32 v3, v185, v3, v185
	v_mul_f32_e32 v3, 0x3f4c422a, v3
	v_add_f32_e32 v3, v3, v3
	v_mul_f32_e32 v3, 0x3fb8aa3b, v3
	v_exp_f32_e32 v3, v3
	s_nop 0
	v_add_f32_e32 v3, 1.0, v3
	v_div_scale_f32 v4, s[6:7], v3, v3, 2.0
	v_rcp_f32_e32 v5, v4
	s_nop 0
	v_fma_f32 v6, -v4, v5, 1.0
	v_fmac_f32_e32 v5, v6, v5
	v_div_scale_f32 v6, vcc, 2.0, v3, 2.0
	v_mul_f32_e32 v7, v6, v5
	v_fma_f32 v8, -v4, v7, v6
	v_fmac_f32_e32 v7, v8, v5
	v_fma_f32 v4, -v4, v7, v6
	v_div_fmas_f32 v4, v4, v5, v7
; DI float gelu_tanh(float x) {
;   float u = 0.7978845608028654f * (x + 0.044715f * x * x * x);
;   float e = __expf(2.f * u);
;   float t = 1.f - 2.f / (e + 1.f);
;   return 0.5f * x * (1.f + t);
; }
; DI void gemm_in_phase(const Params& P, int l, char* smem) {
;     ...
;       if (gel) wave_store_tile([&](int m, int n, int j) { return gelu_tanh(acc[m][n][j]); }, stg, [&](int r) { return base + (size_t)r * ld; }, noscale);
	v_div_fixup_f32 v3, v4, v3, 2.0
	v_sub_f32_e32 v3, 1.0, v3
	v_mul_f32_e32 v4, 0.5, v185
	v_add_f32_e32 v3, 1.0, v3
	v_fma_mixlo_f16 v3, v4, v3, 0
	ds_write_b16 v2, v3 offset:2800
	v_mul_f32_e32 v3, 0x3d372713, v184
	v_mul_f32_e32 v3, v184, v3
	v_fma_f32 v3, v184, v3, v184
	v_mul_f32_e32 v3, 0x3f4c422a, v3
	v_add_f32_e32 v3, v3, v3
	v_mul_f32_e32 v3, 0x3fb8aa3b, v3
	v_exp_f32_e32 v3, v3
	s_nop 0
	v_add_f32_e32 v3, 1.0, v3
	v_div_scale_f32 v4, s[6:7], v3, v3, 2.0
	v_rcp_f32_e32 v5, v4
	s_nop 0
	v_fma_f32 v6, -v4, v5, 1.0
	v_fmac_f32_e32 v5, v6, v5
	v_div_scale_f32 v6, vcc, 2.0, v3, 2.0
	v_mul_f32_e32 v7, v6, v5
	v_fma_f32 v8, -v4, v7, v6
	v_fmac_f32_e32 v7, v8, v5
	v_fma_f32 v4, -v4, v7, v6
	v_div_fmas_f32 v4, v4, v5, v7
	v_div_fixup_f32 v3, v4, v3, 2.0
	v_sub_f32_e32 v3, 1.0, v3
	v_mul_f32_e32 v4, 0.5, v184
	v_add_f32_e32 v3, 1.0, v3
	v_fma_mixlo_f16 v3, v4, v3, 0
	ds_write_b16 v2, v3 offset:2400
	v_mul_f32_e32 v3, 0x3d372713, v183
	v_mul_f32_e32 v3, v183, v3
	v_fma_f32 v3, v183, v3, v183
	v_mul_f32_e32 v3, 0x3f4c422a, v3
	v_add_f32_e32 v3, v3, v3
	v_mul_f32_e32 v3, 0x3fb8aa3b, v3
	v_exp_f32_e32 v3, v3
	s_nop 0
	v_add_f32_e32 v3, 1.0, v3
	v_div_scale_f32 v4, s[6:7], v3, v3, 2.0
	v_rcp_f32_e32 v5, v4
	s_nop 0
	v_fma_f32 v6, -v4, v5, 1.0
	v_fmac_f32_e32 v5, v6, v5
	v_div_scale_f32 v6, vcc, 2.0, v3, 2.0
	v_mul_f32_e32 v7, v6, v5
	v_fma_f32 v8, -v4, v7, v6
	v_fmac_f32_e32 v7, v8, v5
	v_fma_f32 v4, -v4, v7, v6
	v_div_fmas_f32 v4, v4, v5, v7
	v_div_fixup_f32 v3, v4, v3, 2.0
	v_sub_f32_e32 v3, 1.0, v3
	v_mul_f32_e32 v4, 0.5, v183
	v_add_f32_e32 v3, 1.0, v3
	v_fma_mixlo_f16 v3, v4, v3, 0
	ds_write_b16 v2, v3 offset:2544
	v_mul_f32_e32 v3, 0x3d372713, v182
	v_mul_f32_e32 v3, v182, v3
	v_fma_f32 v3, v182, v3, v182
	v_mul_f32_e32 v3, 0x3f4c422a, v3
	v_add_f32_e32 v3, v3, v3
	v_mul_f32_e32 v3, 0x3fb8aa3b, v3
	v_exp_f32_e32 v3, v3
	s_nop 0
	v_add_f32_e32 v3, 1.0, v3
	v_div_scale_f32 v4, s[6:7], v3, v3, 2.0
	v_rcp_f32_e32 v5, v4
	s_nop 0
	v_fma_f32 v6, -v4, v5, 1.0
	v_fmac_f32_e32 v5, v6, v5
	v_div_scale_f32 v6, vcc, 2.0, v3, 2.0
	v_mul_f32_e32 v7, v6, v5
	v_fma_f32 v8, -v4, v7, v6
	v_fmac_f32_e32 v7, v8, v5
	v_fma_f32 v4, -v4, v7, v6
	v_div_fmas_f32 v4, v4, v5, v7
	v_div_fixup_f32 v3, v4, v3, 2.0
	v_sub_f32_e32 v3, 1.0, v3
	v_mul_f32_e32 v4, 0.5, v182
	v_add_f32_e32 v3, 1.0, v3
	v_fma_mixlo_f16 v3, v4, v3, 0
	ds_write_b16 v2, v3 offset:2688
	v_mul_f32_e32 v3, 0x3d372713, v181
	v_mul_f32_e32 v3, v181, v3
	v_fma_f32 v3, v181, v3, v181
	v_mul_f32_e32 v3, 0x3f4c422a, v3
	v_add_f32_e32 v3, v3, v3
	v_mul_f32_e32 v3, 0x3fb8aa3b, v3
	v_exp_f32_e32 v3, v3
	s_nop 0
	v_add_f32_e32 v3, 1.0, v3
	v_div_scale_f32 v4, s[6:7], v3, v3, 2.0
	v_rcp_f32_e32 v5, v4
	s_nop 0
	v_fma_f32 v6, -v4, v5, 1.0
	v_fmac_f32_e32 v5, v6, v5
	v_div_scale_f32 v6, vcc, 2.0, v3, 2.0
	v_mul_f32_e32 v7, v6, v5
	v_fma_f32 v8, -v4, v7, v6
	v_fmac_f32_e32 v7, v8, v5
	v_fma_f32 v4, -v4, v7, v6
	v_div_fmas_f32 v4, v4, v5, v7
	v_div_fixup_f32 v3, v4, v3, 2.0
	v_sub_f32_e32 v3, 1.0, v3
	v_mul_f32_e32 v4, 0.5, v181
	v_add_f32_e32 v3, 1.0, v3
	v_fma_mixlo_f16 v3, v4, v3, 0
	ds_write_b16 v2, v3 offset:2832
	v_mul_f32_e32 v3, 0x3d372713, v252
	v_mul_f32_e32 v3, v252, v3
	v_fma_f32 v3, v252, v3, v252
	v_mul_f32_e32 v3, 0x3f4c422a, v3
	v_add_f32_e32 v3, v3, v3
	v_mul_f32_e32 v3, 0x3fb8aa3b, v3
	v_exp_f32_e32 v3, v3
	s_nop 0
	v_add_f32_e32 v3, 1.0, v3
	v_div_scale_f32 v4, s[6:7], v3, v3, 2.0
	v_rcp_f32_e32 v5, v4
	s_nop 0
	v_fma_f32 v6, -v4, v5, 1.0
	v_fmac_f32_e32 v5, v6, v5
	v_div_scale_f32 v6, vcc, 2.0, v3, 2.0
	v_mul_f32_e32 v7, v6, v5
	v_fma_f32 v8, -v4, v7, v6
	v_fmac_f32_e32 v7, v8, v5
	v_fma_f32 v4, -v4, v7, v6
	v_div_fmas_f32 v4, v4, v5, v7
	v_div_fixup_f32 v3, v4, v3, 2.0
	v_sub_f32_e32 v3, 1.0, v3
	v_mul_f32_e32 v4, 0.5, v252
	v_add_f32_e32 v3, 1.0, v3
	v_fma_mixlo_f16 v3, v4, v3, 0
	ds_write_b16 v2, v3 offset:4608
	v_mul_f32_e32 v3, 0x3d372713, v251
	v_mul_f32_e32 v3, v251, v3
	v_fma_f32 v3, v251, v3, v251
	v_mul_f32_e32 v3, 0x3f4c422a, v3
	v_add_f32_e32 v3, v3, v3
	v_mul_f32_e32 v3, 0x3fb8aa3b, v3
	v_exp_f32_e32 v3, v3
	s_nop 0
	v_add_f32_e32 v3, 1.0, v3
	v_div_scale_f32 v4, s[6:7], v3, v3, 2.0
	v_rcp_f32_e32 v5, v4
	s_nop 0
	v_fma_f32 v6, -v4, v5, 1.0
	v_fmac_f32_e32 v5, v6, v5
	v_div_scale_f32 v6, vcc, 2.0, v3, 2.0
	v_mul_f32_e32 v7, v6, v5
	v_fma_f32 v8, -v4, v7, v6
	v_fmac_f32_e32 v7, v8, v5
	v_fma_f32 v4, -v4, v7, v6
	v_div_fmas_f32 v4, v4, v5, v7
	v_div_fixup_f32 v3, v4, v3, 2.0
	v_sub_f32_e32 v3, 1.0, v3
	v_mul_f32_e32 v4, 0.5, v251
	v_add_f32_e32 v3, 1.0, v3
	v_fma_mixlo_f16 v3, v4, v3, 0
	ds_write_b16 v2, v3 offset:4752
	v_mul_f32_e32 v3, 0x3d372713, v250
	v_mul_f32_e32 v3, v250, v3
	v_fma_f32 v3, v250, v3, v250
	v_mul_f32_e32 v3, 0x3f4c422a, v3
	v_add_f32_e32 v3, v3, v3
	v_mul_f32_e32 v3, 0x3fb8aa3b, v3
	v_exp_f32_e32 v3, v3
	s_nop 0
	v_add_f32_e32 v3, 1.0, v3
	v_div_scale_f32 v4, s[6:7], v3, v3, 2.0
	v_rcp_f32_e32 v5, v4
	s_nop 0
	v_fma_f32 v6, -v4, v5, 1.0
	v_fmac_f32_e32 v5, v6, v5
	v_div_scale_f32 v6, vcc, 2.0, v3, 2.0
	v_mul_f32_e32 v7, v6, v5
	v_fma_f32 v8, -v4, v7, v6
	v_fmac_f32_e32 v7, v8, v5
	v_fma_f32 v4, -v4, v7, v6
	v_div_fmas_f32 v4, v4, v5, v7
	v_div_fixup_f32 v3, v4, v3, 2.0
	v_sub_f32_e32 v3, 1.0, v3
	v_mul_f32_e32 v4, 0.5, v250
	v_add_f32_e32 v3, 1.0, v3
	v_fma_mixlo_f16 v3, v4, v3, 0
	ds_write_b16 v2, v3 offset:4896
	v_mul_f32_e32 v3, 0x3d372713, v249
	v_mul_f32_e32 v3, v249, v3
	v_fma_f32 v3, v249, v3, v249
	v_mul_f32_e32 v3, 0x3f4c422a, v3
	v_add_f32_e32 v3, v3, v3
	v_mul_f32_e32 v3, 0x3fb8aa3b, v3
	v_exp_f32_e32 v3, v3
	s_nop 0
	v_add_f32_e32 v3, 1.0, v3
	v_div_scale_f32 v4, s[6:7], v3, v3, 2.0
	v_rcp_f32_e32 v5, v4
	s_nop 0
	v_fma_f32 v6, -v4, v5, 1.0
; DI float gelu_tanh(float x) {
;   float u = 0.7978845608028654f * (x + 0.044715f * x * x * x);
;   float e = __expf(2.f * u);
;   float t = 1.f - 2.f / (e + 1.f);
;   return 0.5f * x * (1.f + t);
; }
; DI void gemm_in_phase(const Params& P, int l, char* smem) {
;     ...
;       if (gel) wave_store_tile([&](int m, int n, int j) { return gelu_tanh(acc[m][n][j]); }, stg, [&](int r) { return base + (size_t)r * ld; }, noscale);
	v_fmac_f32_e32 v5, v6, v5
	v_div_scale_f32 v6, vcc, 2.0, v3, 2.0
	v_mul_f32_e32 v7, v6, v5
	v_fma_f32 v8, -v4, v7, v6
	v_fmac_f32_e32 v7, v8, v5
	v_fma_f32 v4, -v4, v7, v6
	v_div_fmas_f32 v4, v4, v5, v7
	v_div_fixup_f32 v3, v4, v3, 2.0
	v_sub_f32_e32 v3, 1.0, v3
	v_mul_f32_e32 v4, 0.5, v249
	v_add_f32_e32 v3, 1.0, v3
	v_fma_mixlo_f16 v3, v4, v3, 0
	ds_write_b16 v2, v3 offset:5040
	v_mul_f32_e32 v3, 0x3d372713, v248
	v_mul_f32_e32 v3, v248, v3
	v_fma_f32 v3, v248, v3, v248
	v_mul_f32_e32 v3, 0x3f4c422a, v3
	v_add_f32_e32 v3, v3, v3
	v_mul_f32_e32 v3, 0x3fb8aa3b, v3
	v_exp_f32_e32 v3, v3
	s_nop 0
	v_add_f32_e32 v3, 1.0, v3
	v_div_scale_f32 v4, s[6:7], v3, v3, 2.0
	v_rcp_f32_e32 v5, v4
	s_nop 0
	v_fma_f32 v6, -v4, v5, 1.0
	v_fmac_f32_e32 v5, v6, v5
	v_div_scale_f32 v6, vcc, 2.0, v3, 2.0
	v_mul_f32_e32 v7, v6, v5
	v_fma_f32 v8, -v4, v7, v6
	v_fmac_f32_e32 v7, v8, v5
	v_fma_f32 v4, -v4, v7, v6
	v_div_fmas_f32 v4, v4, v5, v7
	v_div_fixup_f32 v3, v4, v3, 2.0
	v_sub_f32_e32 v3, 1.0, v3
	v_mul_f32_e32 v4, 0.5, v248
	v_add_f32_e32 v3, 1.0, v3
	v_fma_mixlo_f16 v3, v4, v3, 0
	ds_write_b16 v2, v3 offset:4640
	v_mul_f32_e32 v3, 0x3d372713, v247
	v_mul_f32_e32 v3, v247, v3
	v_fma_f32 v3, v247, v3, v247
	v_mul_f32_e32 v3, 0x3f4c422a, v3
	v_add_f32_e32 v3, v3, v3
	v_mul_f32_e32 v3, 0x3fb8aa3b, v3
	v_exp_f32_e32 v3, v3
	s_nop 0
	v_add_f32_e32 v3, 1.0, v3
	v_div_scale_f32 v4, s[6:7], v3, v3, 2.0
	v_rcp_f32_e32 v5, v4
	s_nop 0
	v_fma_f32 v6, -v4, v5, 1.0
	v_fmac_f32_e32 v5, v6, v5
	v_div_scale_f32 v6, vcc, 2.0, v3, 2.0
	v_mul_f32_e32 v7, v6, v5
	v_fma_f32 v8, -v4, v7, v6
	v_fmac_f32_e32 v7, v8, v5
	v_fma_f32 v4, -v4, v7, v6
	v_div_fmas_f32 v4, v4, v5, v7
	v_div_fixup_f32 v3, v4, v3, 2.0
	v_sub_f32_e32 v3, 1.0, v3
	v_mul_f32_e32 v4, 0.5, v247
	v_add_f32_e32 v3, 1.0, v3
	v_fma_mixlo_f16 v3, v4, v3, 0
	ds_write_b16 v2, v3 offset:4784
	v_mul_f32_e32 v3, 0x3d372713, v246
	v_mul_f32_e32 v3, v246, v3
	v_fma_f32 v3, v246, v3, v246
	v_mul_f32_e32 v3, 0x3f4c422a, v3
	v_add_f32_e32 v3, v3, v3
	v_mul_f32_e32 v3, 0x3fb8aa3b, v3
	v_exp_f32_e32 v3, v3
	s_nop 0
	v_add_f32_e32 v3, 1.0, v3
	v_div_scale_f32 v4, s[6:7], v3, v3, 2.0
	v_rcp_f32_e32 v5, v4
	s_nop 0
	v_fma_f32 v6, -v4, v5, 1.0
	v_fmac_f32_e32 v5, v6, v5
	v_div_scale_f32 v6, vcc, 2.0, v3, 2.0
	v_mul_f32_e32 v7, v6, v5
	v_fma_f32 v8, -v4, v7, v6
	v_fmac_f32_e32 v7, v8, v5
	v_fma_f32 v4, -v4, v7, v6
	v_div_fmas_f32 v4, v4, v5, v7
	v_div_fixup_f32 v3, v4, v3, 2.0
	v_sub_f32_e32 v3, 1.0, v3
	v_mul_f32_e32 v4, 0.5, v246
	v_add_f32_e32 v3, 1.0, v3
	v_fma_mixlo_f16 v3, v4, v3, 0
	ds_write_b16 v2, v3 offset:4928
	v_mul_f32_e32 v3, 0x3d372713, v245
	v_mul_f32_e32 v3, v245, v3
	v_fma_f32 v3, v245, v3, v245
	v_mul_f32_e32 v3, 0x3f4c422a, v3
	v_add_f32_e32 v3, v3, v3
	v_mul_f32_e32 v3, 0x3fb8aa3b, v3
	v_exp_f32_e32 v3, v3
	s_nop 0
	v_add_f32_e32 v3, 1.0, v3
	v_div_scale_f32 v4, s[6:7], v3, v3, 2.0
	v_rcp_f32_e32 v5, v4
	s_nop 0
	v_fma_f32 v6, -v4, v5, 1.0
	v_fmac_f32_e32 v5, v6, v5
	v_div_scale_f32 v6, vcc, 2.0, v3, 2.0
	v_mul_f32_e32 v7, v6, v5
	v_fma_f32 v8, -v4, v7, v6
	v_fmac_f32_e32 v7, v8, v5
	v_fma_f32 v4, -v4, v7, v6
	v_div_fmas_f32 v4, v4, v5, v7
	v_div_fixup_f32 v3, v4, v3, 2.0
	v_sub_f32_e32 v3, 1.0, v3
	v_mul_f32_e32 v4, 0.5, v245
	v_add_f32_e32 v3, 1.0, v3
	v_fma_mixlo_f16 v3, v4, v3, 0
	ds_write_b16 v2, v3 offset:5072
	v_mul_f32_e32 v3, 0x3d372713, v244
	v_mul_f32_e32 v3, v244, v3
	v_fma_f32 v3, v244, v3, v244
	v_mul_f32_e32 v3, 0x3f4c422a, v3
	v_add_f32_e32 v3, v3, v3
	v_mul_f32_e32 v3, 0x3fb8aa3b, v3
	v_exp_f32_e32 v3, v3
	s_nop 0
	v_add_f32_e32 v3, 1.0, v3
	v_div_scale_f32 v4, s[6:7], v3, v3, 2.0
	v_rcp_f32_e32 v5, v4
	s_nop 0
	v_fma_f32 v6, -v4, v5, 1.0
	v_fmac_f32_e32 v5, v6, v5
	v_div_scale_f32 v6, vcc, 2.0, v3, 2.0
	v_mul_f32_e32 v7, v6, v5
	v_fma_f32 v8, -v4, v7, v6
	v_fmac_f32_e32 v7, v8, v5
	v_fma_f32 v4, -v4, v7, v6
	v_div_fmas_f32 v4, v4, v5, v7
	v_div_fixup_f32 v3, v4, v3, 2.0
	v_sub_f32_e32 v3, 1.0, v3
	v_mul_f32_e32 v4, 0.5, v244
	v_add_f32_e32 v3, 1.0, v3
	v_fma_mixlo_f16 v3, v4, v3, 0
	ds_write_b16 v2, v3 offset:4672
	v_mul_f32_e32 v3, 0x3d372713, v243
	v_mul_f32_e32 v3, v243, v3
	v_fma_f32 v3, v243, v3, v243
	v_mul_f32_e32 v3, 0x3f4c422a, v3
	v_add_f32_e32 v3, v3, v3
	v_mul_f32_e32 v3, 0x3fb8aa3b, v3
	v_exp_f32_e32 v3, v3
	s_nop 0
	v_add_f32_e32 v3, 1.0, v3
	v_div_scale_f32 v4, s[6:7], v3, v3, 2.0
	v_rcp_f32_e32 v5, v4
	s_nop 0
	v_fma_f32 v6, -v4, v5, 1.0
	v_fmac_f32_e32 v5, v6, v5
	v_div_scale_f32 v6, vcc, 2.0, v3, 2.0
	v_mul_f32_e32 v7, v6, v5
	v_fma_f32 v8, -v4, v7, v6
	v_fmac_f32_e32 v7, v8, v5
	v_fma_f32 v4, -v4, v7, v6
	v_div_fmas_f32 v4, v4, v5, v7
	v_div_fixup_f32 v3, v4, v3, 2.0
	v_sub_f32_e32 v3, 1.0, v3
	v_mul_f32_e32 v4, 0.5, v243
	v_add_f32_e32 v3, 1.0, v3
	v_fma_mixlo_f16 v3, v4, v3, 0
	ds_write_b16 v2, v3 offset:4816
	v_mul_f32_e32 v3, 0x3d372713, v242
	v_mul_f32_e32 v3, v242, v3
	v_fma_f32 v3, v242, v3, v242
	v_mul_f32_e32 v3, 0x3f4c422a, v3
	v_add_f32_e32 v3, v3, v3
	v_mul_f32_e32 v3, 0x3fb8aa3b, v3
	v_exp_f32_e32 v3, v3
	s_nop 0
	v_add_f32_e32 v3, 1.0, v3
	v_div_scale_f32 v4, s[6:7], v3, v3, 2.0
	v_rcp_f32_e32 v5, v4
	s_nop 0
	v_fma_f32 v6, -v4, v5, 1.0
	v_fmac_f32_e32 v5, v6, v5
	v_div_scale_f32 v6, vcc, 2.0, v3, 2.0
	v_mul_f32_e32 v7, v6, v5
	v_fma_f32 v8, -v4, v7, v6
	v_fmac_f32_e32 v7, v8, v5
	v_fma_f32 v4, -v4, v7, v6
	v_div_fmas_f32 v4, v4, v5, v7
	v_div_fixup_f32 v3, v4, v3, 2.0
	v_sub_f32_e32 v3, 1.0, v3
	v_mul_f32_e32 v4, 0.5, v242
	v_add_f32_e32 v3, 1.0, v3
	v_fma_mixlo_f16 v3, v4, v3, 0
	ds_write_b16 v2, v3 offset:4960
	v_mul_f32_e32 v3, 0x3d372713, v241
	v_mul_f32_e32 v3, v241, v3
	v_fma_f32 v3, v241, v3, v241
	v_mul_f32_e32 v3, 0x3f4c422a, v3
	v_add_f32_e32 v3, v3, v3
; DI float gelu_tanh(float x) {
;   float u = 0.7978845608028654f * (x + 0.044715f * x * x * x);
;   float e = __expf(2.f * u);
;   float t = 1.f - 2.f / (e + 1.f);
;   return 0.5f * x * (1.f + t);
; }
; DI void gemm_in_phase(const Params& P, int l, char* smem) {
;     ...
;       if (gel) wave_store_tile([&](int m, int n, int j) { return gelu_tanh(acc[m][n][j]); }, stg, [&](int r) { return base + (size_t)r * ld; }, noscale);
	v_mul_f32_e32 v3, 0x3fb8aa3b, v3
	v_exp_f32_e32 v3, v3
	s_nop 0
	v_add_f32_e32 v3, 1.0, v3
	v_div_scale_f32 v4, s[6:7], v3, v3, 2.0
	v_rcp_f32_e32 v5, v4
	s_nop 0
	v_fma_f32 v6, -v4, v5, 1.0
	v_fmac_f32_e32 v5, v6, v5
	v_div_scale_f32 v6, vcc, 2.0, v3, 2.0
	v_mul_f32_e32 v7, v6, v5
	v_fma_f32 v8, -v4, v7, v6
	v_fmac_f32_e32 v7, v8, v5
	v_fma_f32 v4, -v4, v7, v6
	v_div_fmas_f32 v4, v4, v5, v7
	v_div_fixup_f32 v3, v4, v3, 2.0
	v_sub_f32_e32 v3, 1.0, v3
	v_mul_f32_e32 v4, 0.5, v241
	v_add_f32_e32 v3, 1.0, v3
	v_fma_mixlo_f16 v3, v4, v3, 0
	ds_write_b16 v2, v3 offset:5104
	v_mul_f32_e32 v3, 0x3d372713, v240
	v_mul_f32_e32 v3, v240, v3
	v_fma_f32 v3, v240, v3, v240
	v_mul_f32_e32 v3, 0x3f4c422a, v3
	v_add_f32_e32 v3, v3, v3
	v_mul_f32_e32 v3, 0x3fb8aa3b, v3
	v_exp_f32_e32 v3, v3
	s_nop 0
	v_add_f32_e32 v3, 1.0, v3
	v_div_scale_f32 v4, s[6:7], v3, v3, 2.0
	v_rcp_f32_e32 v5, v4
	s_nop 0
	v_fma_f32 v6, -v4, v5, 1.0
	v_fmac_f32_e32 v5, v6, v5
	v_div_scale_f32 v6, vcc, 2.0, v3, 2.0
	v_mul_f32_e32 v7, v6, v5
	v_fma_f32 v8, -v4, v7, v6
	v_fmac_f32_e32 v7, v8, v5
	v_fma_f32 v4, -v4, v7, v6
	v_div_fmas_f32 v4, v4, v5, v7
	v_div_fixup_f32 v3, v4, v3, 2.0
	v_sub_f32_e32 v3, 1.0, v3
	v_mul_f32_e32 v4, 0.5, v240
	v_add_f32_e32 v3, 1.0, v3
	v_fma_mixlo_f16 v3, v4, v3, 0
	ds_write_b16 v2, v3 offset:4704
	v_mul_f32_e32 v3, 0x3d372713, v239
	v_mul_f32_e32 v3, v239, v3
	v_fma_f32 v3, v239, v3, v239
	v_mul_f32_e32 v3, 0x3f4c422a, v3
	v_add_f32_e32 v3, v3, v3
	v_mul_f32_e32 v3, 0x3fb8aa3b, v3
	v_exp_f32_e32 v3, v3
	s_nop 0
	v_add_f32_e32 v3, 1.0, v3
	v_div_scale_f32 v4, s[6:7], v3, v3, 2.0
	v_rcp_f32_e32 v5, v4
	s_nop 0
	v_fma_f32 v6, -v4, v5, 1.0
	v_fmac_f32_e32 v5, v6, v5
	v_div_scale_f32 v6, vcc, 2.0, v3, 2.0
	v_mul_f32_e32 v7, v6, v5
	v_fma_f32 v8, -v4, v7, v6
	v_fmac_f32_e32 v7, v8, v5
	v_fma_f32 v4, -v4, v7, v6
	v_div_fmas_f32 v4, v4, v5, v7
	v_div_fixup_f32 v3, v4, v3, 2.0
	v_sub_f32_e32 v3, 1.0, v3
	v_mul_f32_e32 v4, 0.5, v239
	v_add_f32_e32 v3, 1.0, v3
	v_fma_mixlo_f16 v3, v4, v3, 0
	ds_write_b16 v2, v3 offset:4848
	v_mul_f32_e32 v3, 0x3d372713, v238
	v_mul_f32_e32 v3, v238, v3
	v_fma_f32 v3, v238, v3, v238
	v_mul_f32_e32 v3, 0x3f4c422a, v3
	v_add_f32_e32 v3, v3, v3
	v_mul_f32_e32 v3, 0x3fb8aa3b, v3
	v_exp_f32_e32 v3, v3
	s_nop 0
	v_add_f32_e32 v3, 1.0, v3
	v_div_scale_f32 v4, s[6:7], v3, v3, 2.0
	v_rcp_f32_e32 v5, v4
	s_nop 0
	v_fma_f32 v6, -v4, v5, 1.0
	v_fmac_f32_e32 v5, v6, v5
	v_div_scale_f32 v6, vcc, 2.0, v3, 2.0
	v_mul_f32_e32 v7, v6, v5
	v_fma_f32 v8, -v4, v7, v6
	v_fmac_f32_e32 v7, v8, v5
	v_fma_f32 v4, -v4, v7, v6
	v_div_fmas_f32 v4, v4, v5, v7
	v_div_fixup_f32 v3, v4, v3, 2.0
	v_sub_f32_e32 v3, 1.0, v3
	v_mul_f32_e32 v4, 0.5, v238
	v_add_f32_e32 v3, 1.0, v3
	v_fma_mixlo_f16 v3, v4, v3, 0
	ds_write_b16 v2, v3 offset:4992
	v_mul_f32_e32 v3, 0x3d372713, v237
	v_mul_f32_e32 v3, v237, v3
	v_fma_f32 v3, v237, v3, v237
	v_mul_f32_e32 v3, 0x3f4c422a, v3
	v_add_f32_e32 v3, v3, v3
	v_mul_f32_e32 v3, 0x3fb8aa3b, v3
	v_exp_f32_e32 v3, v3
	s_nop 0
	v_add_f32_e32 v3, 1.0, v3
	v_div_scale_f32 v4, s[6:7], v3, v3, 2.0
	v_rcp_f32_e32 v5, v4
	s_nop 0
	v_fma_f32 v6, -v4, v5, 1.0
	v_fmac_f32_e32 v5, v6, v5
	v_div_scale_f32 v6, vcc, 2.0, v3, 2.0
	v_mul_f32_e32 v7, v6, v5
	v_fma_f32 v8, -v4, v7, v6
	v_fmac_f32_e32 v7, v8, v5
	v_fma_f32 v4, -v4, v7, v6
	v_div_fmas_f32 v4, v4, v5, v7
	v_div_fixup_f32 v3, v4, v3, 2.0
	v_sub_f32_e32 v3, 1.0, v3
	v_mul_f32_e32 v4, 0.5, v237
	v_add_f32_e32 v3, 1.0, v3
	v_fma_mixlo_f16 v3, v4, v3, 0
	ds_write_b16 v2, v3 offset:5136
	v_mul_f32_e32 v3, 0x3d372713, v236
	v_mul_f32_e32 v3, v236, v3
	v_fma_f32 v3, v236, v3, v236
	v_mul_f32_e32 v3, 0x3f4c422a, v3
	v_add_f32_e32 v3, v3, v3
	v_mul_f32_e32 v3, 0x3fb8aa3b, v3
	v_exp_f32_e32 v3, v3
	s_nop 0
	v_add_f32_e32 v3, 1.0, v3
	v_div_scale_f32 v4, s[6:7], v3, v3, 2.0
	v_rcp_f32_e32 v5, v4
	s_nop 0
	v_fma_f32 v6, -v4, v5, 1.0
	v_fmac_f32_e32 v5, v6, v5
	v_div_scale_f32 v6, vcc, 2.0, v3, 2.0
	v_mul_f32_e32 v7, v6, v5
	v_fma_f32 v8, -v4, v7, v6
	v_fmac_f32_e32 v7, v8, v5
	v_fma_f32 v4, -v4, v7, v6
	v_div_fmas_f32 v4, v4, v5, v7
	v_div_fixup_f32 v3, v4, v3, 2.0
	v_sub_f32_e32 v3, 1.0, v3
	v_mul_f32_e32 v4, 0.5, v236
	v_add_f32_e32 v3, 1.0, v3
	v_fma_mixlo_f16 v3, v4, v3, 0
	ds_write_b16 v2, v3 offset:6912
	v_mul_f32_e32 v3, 0x3d372713, v235
	v_mul_f32_e32 v3, v235, v3
	v_fma_f32 v3, v235, v3, v235
	v_mul_f32_e32 v3, 0x3f4c422a, v3
	v_add_f32_e32 v3, v3, v3
	v_mul_f32_e32 v3, 0x3fb8aa3b, v3
	v_exp_f32_e32 v3, v3
	s_nop 0
	v_add_f32_e32 v3, 1.0, v3
	v_div_scale_f32 v4, s[6:7], v3, v3, 2.0
	v_rcp_f32_e32 v5, v4
	s_nop 0
	v_fma_f32 v6, -v4, v5, 1.0
	v_fmac_f32_e32 v5, v6, v5
	v_div_scale_f32 v6, vcc, 2.0, v3, 2.0
	v_mul_f32_e32 v7, v6, v5
	v_fma_f32 v8, -v4, v7, v6
	v_fmac_f32_e32 v7, v8, v5
	v_fma_f32 v4, -v4, v7, v6
	v_div_fmas_f32 v4, v4, v5, v7
	v_div_fixup_f32 v3, v4, v3, 2.0
	v_sub_f32_e32 v3, 1.0, v3
	v_mul_f32_e32 v4, 0.5, v235
	v_add_f32_e32 v3, 1.0, v3
	v_fma_mixlo_f16 v3, v4, v3, 0
	ds_write_b16 v2, v3 offset:7056
	v_mul_f32_e32 v3, 0x3d372713, v234
	v_mul_f32_e32 v3, v234, v3
	v_fma_f32 v3, v234, v3, v234
	v_mul_f32_e32 v3, 0x3f4c422a, v3
	v_add_f32_e32 v3, v3, v3
	v_mul_f32_e32 v3, 0x3fb8aa3b, v3
	v_exp_f32_e32 v3, v3
	s_nop 0
	v_add_f32_e32 v3, 1.0, v3
	v_div_scale_f32 v4, s[6:7], v3, v3, 2.0
	v_rcp_f32_e32 v5, v4
	s_nop 0
	v_fma_f32 v6, -v4, v5, 1.0
	v_fmac_f32_e32 v5, v6, v5
	v_div_scale_f32 v6, vcc, 2.0, v3, 2.0
	v_mul_f32_e32 v7, v6, v5
	v_fma_f32 v8, -v4, v7, v6
	v_fmac_f32_e32 v7, v8, v5
	v_fma_f32 v4, -v4, v7, v6
	v_div_fmas_f32 v4, v4, v5, v7
	v_div_fixup_f32 v3, v4, v3, 2.0
	v_sub_f32_e32 v3, 1.0, v3
	v_mul_f32_e32 v4, 0.5, v234
	v_add_f32_e32 v3, 1.0, v3
	v_fma_mixlo_f16 v3, v4, v3, 0
; DI float gelu_tanh(float x) {
;   float u = 0.7978845608028654f * (x + 0.044715f * x * x * x);
;   float e = __expf(2.f * u);
;   float t = 1.f - 2.f / (e + 1.f);
;   return 0.5f * x * (1.f + t);
; }
; DI void gemm_in_phase(const Params& P, int l, char* smem) {
;     ...
;       if (gel) wave_store_tile([&](int m, int n, int j) { return gelu_tanh(acc[m][n][j]); }, stg, [&](int r) { return base + (size_t)r * ld; }, noscale);
	ds_write_b16 v2, v3 offset:7200
	v_mul_f32_e32 v3, 0x3d372713, v233
	v_mul_f32_e32 v3, v233, v3
	v_fma_f32 v3, v233, v3, v233
	v_mul_f32_e32 v3, 0x3f4c422a, v3
	v_add_f32_e32 v3, v3, v3
	v_mul_f32_e32 v3, 0x3fb8aa3b, v3
	v_exp_f32_e32 v3, v3
	s_nop 0
	v_add_f32_e32 v3, 1.0, v3
	v_div_scale_f32 v4, s[6:7], v3, v3, 2.0
	v_rcp_f32_e32 v5, v4
	s_nop 0
	v_fma_f32 v6, -v4, v5, 1.0
	v_fmac_f32_e32 v5, v6, v5
	v_div_scale_f32 v6, vcc, 2.0, v3, 2.0
	v_mul_f32_e32 v7, v6, v5
	v_fma_f32 v8, -v4, v7, v6
	v_fmac_f32_e32 v7, v8, v5
	v_fma_f32 v4, -v4, v7, v6
	v_div_fmas_f32 v4, v4, v5, v7
	v_div_fixup_f32 v3, v4, v3, 2.0
	v_sub_f32_e32 v3, 1.0, v3
	v_mul_f32_e32 v4, 0.5, v233
	v_add_f32_e32 v3, 1.0, v3
	v_fma_mixlo_f16 v3, v4, v3, 0
	ds_write_b16 v2, v3 offset:7344
	v_mul_f32_e32 v3, 0x3d372713, v232
	v_mul_f32_e32 v3, v232, v3
	v_fma_f32 v3, v232, v3, v232
	v_mul_f32_e32 v3, 0x3f4c422a, v3
	v_add_f32_e32 v3, v3, v3
	v_mul_f32_e32 v3, 0x3fb8aa3b, v3
	v_exp_f32_e32 v3, v3
	s_nop 0
	v_add_f32_e32 v3, 1.0, v3
	v_div_scale_f32 v4, s[6:7], v3, v3, 2.0
	v_rcp_f32_e32 v5, v4
	s_nop 0
	v_fma_f32 v6, -v4, v5, 1.0
	v_fmac_f32_e32 v5, v6, v5
	v_div_scale_f32 v6, vcc, 2.0, v3, 2.0
	v_mul_f32_e32 v7, v6, v5
	v_fma_f32 v8, -v4, v7, v6
	v_fmac_f32_e32 v7, v8, v5
	v_fma_f32 v4, -v4, v7, v6
	v_div_fmas_f32 v4, v4, v5, v7
	v_div_fixup_f32 v3, v4, v3, 2.0
	v_sub_f32_e32 v3, 1.0, v3
	v_mul_f32_e32 v4, 0.5, v232
	v_add_f32_e32 v3, 1.0, v3
	v_fma_mixlo_f16 v3, v4, v3, 0
	ds_write_b16 v2, v3 offset:6944
	v_mul_f32_e32 v3, 0x3d372713, v231
	v_mul_f32_e32 v3, v231, v3
	v_fma_f32 v3, v231, v3, v231
	v_mul_f32_e32 v3, 0x3f4c422a, v3
	v_add_f32_e32 v3, v3, v3
	v_mul_f32_e32 v3, 0x3fb8aa3b, v3
	v_exp_f32_e32 v3, v3
	s_nop 0
	v_add_f32_e32 v3, 1.0, v3
	v_div_scale_f32 v4, s[6:7], v3, v3, 2.0
	v_rcp_f32_e32 v5, v4
	s_nop 0
	v_fma_f32 v6, -v4, v5, 1.0
	v_fmac_f32_e32 v5, v6, v5
	v_div_scale_f32 v6, vcc, 2.0, v3, 2.0
	v_mul_f32_e32 v7, v6, v5
	v_fma_f32 v8, -v4, v7, v6
	v_fmac_f32_e32 v7, v8, v5
	v_fma_f32 v4, -v4, v7, v6
	v_div_fmas_f32 v4, v4, v5, v7
	v_div_fixup_f32 v3, v4, v3, 2.0
	v_sub_f32_e32 v3, 1.0, v3
	v_mul_f32_e32 v4, 0.5, v231
	v_add_f32_e32 v3, 1.0, v3
	v_fma_mixlo_f16 v3, v4, v3, 0
	ds_write_b16 v2, v3 offset:7088
	v_mul_f32_e32 v3, 0x3d372713, v230
	v_mul_f32_e32 v3, v230, v3
	v_fma_f32 v3, v230, v3, v230
	v_mul_f32_e32 v3, 0x3f4c422a, v3
	v_add_f32_e32 v3, v3, v3
	v_mul_f32_e32 v3, 0x3fb8aa3b, v3
	v_exp_f32_e32 v3, v3
	s_nop 0
	v_add_f32_e32 v3, 1.0, v3
	v_div_scale_f32 v4, s[6:7], v3, v3, 2.0
	v_rcp_f32_e32 v5, v4
	s_nop 0
	v_fma_f32 v6, -v4, v5, 1.0
	v_fmac_f32_e32 v5, v6, v5
	v_div_scale_f32 v6, vcc, 2.0, v3, 2.0
	v_mul_f32_e32 v7, v6, v5
	v_fma_f32 v8, -v4, v7, v6
	v_fmac_f32_e32 v7, v8, v5
	v_fma_f32 v4, -v4, v7, v6
	v_div_fmas_f32 v4, v4, v5, v7
	v_div_fixup_f32 v3, v4, v3, 2.0
	v_sub_f32_e32 v3, 1.0, v3
	v_mul_f32_e32 v4, 0.5, v230
	v_add_f32_e32 v3, 1.0, v3
	v_fma_mixlo_f16 v3, v4, v3, 0
	ds_write_b16 v2, v3 offset:7232
	v_mul_f32_e32 v3, 0x3d372713, v229
	v_mul_f32_e32 v3, v229, v3
	v_fma_f32 v3, v229, v3, v229
	v_mul_f32_e32 v3, 0x3f4c422a, v3
	v_add_f32_e32 v3, v3, v3
	v_mul_f32_e32 v3, 0x3fb8aa3b, v3
	v_exp_f32_e32 v3, v3
	s_nop 0
	v_add_f32_e32 v3, 1.0, v3
	v_div_scale_f32 v4, s[6:7], v3, v3, 2.0
	v_rcp_f32_e32 v5, v4
	s_nop 0
	v_fma_f32 v6, -v4, v5, 1.0
	v_fmac_f32_e32 v5, v6, v5
	v_div_scale_f32 v6, vcc, 2.0, v3, 2.0
	v_mul_f32_e32 v7, v6, v5
	v_fma_f32 v8, -v4, v7, v6
	v_fmac_f32_e32 v7, v8, v5
	v_fma_f32 v4, -v4, v7, v6
	v_div_fmas_f32 v4, v4, v5, v7
	v_div_fixup_f32 v3, v4, v3, 2.0
	v_sub_f32_e32 v3, 1.0, v3
	v_mul_f32_e32 v4, 0.5, v229
	v_add_f32_e32 v3, 1.0, v3
	v_fma_mixlo_f16 v3, v4, v3, 0
	ds_write_b16 v2, v3 offset:7376
	v_mul_f32_e32 v3, 0x3d372713, v228
	v_mul_f32_e32 v3, v228, v3
	v_fma_f32 v3, v228, v3, v228
	v_mul_f32_e32 v3, 0x3f4c422a, v3
	v_add_f32_e32 v3, v3, v3
	v_mul_f32_e32 v3, 0x3fb8aa3b, v3
	v_exp_f32_e32 v3, v3
	s_nop 0
	v_add_f32_e32 v3, 1.0, v3
	v_div_scale_f32 v4, s[6:7], v3, v3, 2.0
	v_rcp_f32_e32 v5, v4
	s_nop 0
	v_fma_f32 v6, -v4, v5, 1.0
	v_fmac_f32_e32 v5, v6, v5
	v_div_scale_f32 v6, vcc, 2.0, v3, 2.0
	v_mul_f32_e32 v7, v6, v5
	v_fma_f32 v8, -v4, v7, v6
	v_fmac_f32_e32 v7, v8, v5
	v_fma_f32 v4, -v4, v7, v6
	v_div_fmas_f32 v4, v4, v5, v7
	v_div_fixup_f32 v3, v4, v3, 2.0
	v_sub_f32_e32 v3, 1.0, v3
	v_mul_f32_e32 v4, 0.5, v228
	v_add_f32_e32 v3, 1.0, v3
	v_fma_mixlo_f16 v3, v4, v3, 0
	ds_write_b16 v2, v3 offset:6976
	v_mul_f32_e32 v3, 0x3d372713, v227
	v_mul_f32_e32 v3, v227, v3
	v_fma_f32 v3, v227, v3, v227
	v_mul_f32_e32 v3, 0x3f4c422a, v3
	v_add_f32_e32 v3, v3, v3
	v_mul_f32_e32 v3, 0x3fb8aa3b, v3
	v_exp_f32_e32 v3, v3
	s_nop 0
	v_add_f32_e32 v3, 1.0, v3
	v_div_scale_f32 v4, s[6:7], v3, v3, 2.0
	v_rcp_f32_e32 v5, v4
	s_nop 0
	v_fma_f32 v6, -v4, v5, 1.0
	v_fmac_f32_e32 v5, v6, v5
	v_div_scale_f32 v6, vcc, 2.0, v3, 2.0
	v_mul_f32_e32 v7, v6, v5
	v_fma_f32 v8, -v4, v7, v6
	v_fmac_f32_e32 v7, v8, v5
	v_fma_f32 v4, -v4, v7, v6
	v_div_fmas_f32 v4, v4, v5, v7
	v_div_fixup_f32 v3, v4, v3, 2.0
	v_sub_f32_e32 v3, 1.0, v3
	v_mul_f32_e32 v4, 0.5, v227
	v_add_f32_e32 v3, 1.0, v3
	v_fma_mixlo_f16 v3, v4, v3, 0
	ds_write_b16 v2, v3 offset:7120
	v_mul_f32_e32 v3, 0x3d372713, v226
	v_mul_f32_e32 v3, v226, v3
	v_fma_f32 v3, v226, v3, v226
	v_mul_f32_e32 v3, 0x3f4c422a, v3
	v_add_f32_e32 v3, v3, v3
	v_mul_f32_e32 v3, 0x3fb8aa3b, v3
	v_exp_f32_e32 v3, v3
	s_nop 0
	v_add_f32_e32 v3, 1.0, v3
	v_div_scale_f32 v4, s[6:7], v3, v3, 2.0
	v_rcp_f32_e32 v5, v4
	s_nop 0
	v_fma_f32 v6, -v4, v5, 1.0
	v_fmac_f32_e32 v5, v6, v5
	v_div_scale_f32 v6, vcc, 2.0, v3, 2.0
	v_mul_f32_e32 v7, v6, v5
	v_fma_f32 v8, -v4, v7, v6
	v_fmac_f32_e32 v7, v8, v5
; #define TIDX tid_opaque()
; DI float gelu_tanh(float x) {
;   float u = 0.7978845608028654f * (x + 0.044715f * x * x * x);
;   float e = __expf(2.f * u);
;   float t = 1.f - 2.f / (e + 1.f);
;   return 0.5f * x * (1.f + t);
; }
; template <class RP, class SC>
; DI void stage_flush(char* stg, int h, RP rowptr, SC rowscale) {
;   const int lane = TIDX & 63;
;   __builtin_amdgcn_wave_barrier();
; #pragma unroll
;   for (int i = 0; i < 8; i++) {
;     const int c = i * 64 + lane, row = c >> 3, c16 = c & 7;
;     h8 v = *(const h8*)(stg + row * 144 + c16 * 16);
;     half_t* d = rowptr(h * 64 + row);
;     if (d) { rowscale(h * 64 + row, v); *(h8*)(d + c16 * 8) = v; }
;   }
;   __builtin_amdgcn_wave_barrier();
; }
	v_fma_f32 v4, -v4, v7, v6
	v_div_fmas_f32 v4, v4, v5, v7
	v_div_fixup_f32 v3, v4, v3, 2.0
	v_sub_f32_e32 v3, 1.0, v3
	v_mul_f32_e32 v4, 0.5, v226
	v_add_f32_e32 v3, 1.0, v3
	v_fma_mixlo_f16 v3, v4, v3, 0
	ds_write_b16 v2, v3 offset:7264
	v_mul_f32_e32 v3, 0x3d372713, v225
	v_mul_f32_e32 v3, v225, v3
	v_fma_f32 v3, v225, v3, v225
	v_mul_f32_e32 v3, 0x3f4c422a, v3
	v_add_f32_e32 v3, v3, v3
	v_mul_f32_e32 v3, 0x3fb8aa3b, v3
	v_exp_f32_e32 v3, v3
	s_nop 0
	v_add_f32_e32 v3, 1.0, v3
	v_div_scale_f32 v4, s[6:7], v3, v3, 2.0
	v_rcp_f32_e32 v5, v4
	s_nop 0
	v_fma_f32 v6, -v4, v5, 1.0
	v_fmac_f32_e32 v5, v6, v5
	v_div_scale_f32 v6, vcc, 2.0, v3, 2.0
	v_mul_f32_e32 v7, v6, v5
	v_fma_f32 v8, -v4, v7, v6
	v_fmac_f32_e32 v7, v8, v5
	v_fma_f32 v4, -v4, v7, v6
	v_div_fmas_f32 v4, v4, v5, v7
	v_div_fixup_f32 v3, v4, v3, 2.0
	v_sub_f32_e32 v3, 1.0, v3
	v_mul_f32_e32 v4, 0.5, v225
	v_add_f32_e32 v3, 1.0, v3
	v_fma_mixlo_f16 v3, v4, v3, 0
	ds_write_b16 v2, v3 offset:7408
	v_mul_f32_e32 v3, 0x3d372713, v224
	v_mul_f32_e32 v3, v224, v3
	v_fma_f32 v3, v224, v3, v224
	v_mul_f32_e32 v3, 0x3f4c422a, v3
	v_add_f32_e32 v3, v3, v3
	v_mul_f32_e32 v3, 0x3fb8aa3b, v3
	v_exp_f32_e32 v3, v3
	s_nop 0
	v_add_f32_e32 v3, 1.0, v3
	v_div_scale_f32 v4, s[6:7], v3, v3, 2.0
	v_rcp_f32_e32 v5, v4
	s_nop 0
	v_fma_f32 v6, -v4, v5, 1.0
	v_fmac_f32_e32 v5, v6, v5
	v_div_scale_f32 v6, vcc, 2.0, v3, 2.0
	v_mul_f32_e32 v7, v6, v5
	v_fma_f32 v8, -v4, v7, v6
	v_fmac_f32_e32 v7, v8, v5
	v_fma_f32 v4, -v4, v7, v6
	v_div_fmas_f32 v4, v4, v5, v7
	v_div_fixup_f32 v3, v4, v3, 2.0
	v_sub_f32_e32 v3, 1.0, v3
	v_mul_f32_e32 v4, 0.5, v224
	v_add_f32_e32 v3, 1.0, v3
	v_fma_mixlo_f16 v3, v4, v3, 0
	ds_write_b16 v2, v3 offset:7008
	v_mul_f32_e32 v3, 0x3d372713, v223
	v_mul_f32_e32 v3, v223, v3
	v_fma_f32 v3, v223, v3, v223
	v_mul_f32_e32 v3, 0x3f4c422a, v3
	v_add_f32_e32 v3, v3, v3
	v_mul_f32_e32 v3, 0x3fb8aa3b, v3
	v_exp_f32_e32 v3, v3
	s_nop 0
	v_add_f32_e32 v3, 1.0, v3
	v_div_scale_f32 v4, s[6:7], v3, v3, 2.0
	v_rcp_f32_e32 v5, v4
	s_nop 0
	v_fma_f32 v6, -v4, v5, 1.0
	v_fmac_f32_e32 v5, v6, v5
	v_div_scale_f32 v6, vcc, 2.0, v3, 2.0
	v_mul_f32_e32 v7, v6, v5
	v_fma_f32 v8, -v4, v7, v6
	v_fmac_f32_e32 v7, v8, v5
	v_fma_f32 v4, -v4, v7, v6
	v_div_fmas_f32 v4, v4, v5, v7
	v_div_fixup_f32 v3, v4, v3, 2.0
	v_sub_f32_e32 v3, 1.0, v3
	v_mul_f32_e32 v4, 0.5, v223
	v_add_f32_e32 v3, 1.0, v3
	v_fma_mixlo_f16 v3, v4, v3, 0
	ds_write_b16 v2, v3 offset:7152
	v_mul_f32_e32 v3, 0x3d372713, v222
	v_mul_f32_e32 v3, v222, v3
	v_fma_f32 v3, v222, v3, v222
	v_mul_f32_e32 v3, 0x3f4c422a, v3
	v_add_f32_e32 v3, v3, v3
	v_mul_f32_e32 v3, 0x3fb8aa3b, v3
	v_exp_f32_e32 v3, v3
	s_nop 0
	v_add_f32_e32 v3, 1.0, v3
	v_div_scale_f32 v4, s[6:7], v3, v3, 2.0
	v_rcp_f32_e32 v5, v4
	s_nop 0
	v_fma_f32 v6, -v4, v5, 1.0
	v_fmac_f32_e32 v5, v6, v5
	v_div_scale_f32 v6, vcc, 2.0, v3, 2.0
	v_mul_f32_e32 v7, v6, v5
	v_fma_f32 v8, -v4, v7, v6
	v_fmac_f32_e32 v7, v8, v5
	v_fma_f32 v4, -v4, v7, v6
	v_div_fmas_f32 v4, v4, v5, v7
	v_div_fixup_f32 v3, v4, v3, 2.0
	v_sub_f32_e32 v3, 1.0, v3
	v_mul_f32_e32 v4, 0.5, v222
	v_add_f32_e32 v3, 1.0, v3
	v_fma_mixlo_f16 v3, v4, v3, 0
	ds_write_b16 v2, v3 offset:7296
	v_mul_f32_e32 v3, 0x3d372713, v221
	v_mul_f32_e32 v3, v221, v3
	v_fma_f32 v3, v221, v3, v221
	v_mul_f32_e32 v3, 0x3f4c422a, v3
	v_add_f32_e32 v3, v3, v3
	v_mul_f32_e32 v3, 0x3fb8aa3b, v3
	v_exp_f32_e32 v3, v3
	s_nop 0
	v_add_f32_e32 v3, 1.0, v3
	v_div_scale_f32 v4, s[6:7], v3, v3, 2.0
	v_rcp_f32_e32 v5, v4
	s_nop 0
	v_fma_f32 v6, -v4, v5, 1.0
	v_fmac_f32_e32 v5, v6, v5
	v_div_scale_f32 v6, vcc, 2.0, v3, 2.0
	v_mul_f32_e32 v7, v6, v5
	v_fma_f32 v8, -v4, v7, v6
	v_fmac_f32_e32 v7, v8, v5
	v_fma_f32 v4, -v4, v7, v6
	v_div_fmas_f32 v4, v4, v5, v7
	v_div_fixup_f32 v3, v4, v3, 2.0
	v_sub_f32_e32 v3, 1.0, v3
	v_mul_f32_e32 v4, 0.5, v221
	v_add_f32_e32 v3, 1.0, v3
	v_fma_mixlo_f16 v3, v4, v3, 0
	ds_write_b16 v2, v3 offset:7440
	v_mov_b32_e32 v3, v172
	s_nop 0
	v_lshlrev_b32_e32 v4, 4, v3
	v_bfe_u32 v3, v3, 3, 3
	v_and_b32_e32 v8, 0x70, v4
	v_mul_u32_u24_e32 v4, s2, v3
	v_lshlrev_b32_e32 v148, 1, v4
	v_lshl_add_u64 v[4:5], v[0:1], 0, v[148:149]
	v_lshl_add_u64 v[10:11], v[4:5], 0, v[8:9]
	v_mul_u32_u24_e32 v4, 0x90, v3
	v_add3_u32 v12, v18, v8, v4
	s_waitcnt vmcnt(0)
	ds_read_b128 v[4:7], v12
	s_waitcnt lgkmcnt(0)
	global_store_dwordx4 v[10:11], v[4:7], off nt
	s_nop 1
	v_or_b32_e32 v4, 8, v3
	v_mul_u32_u24_e32 v4, s2, v4
	v_lshlrev_b32_e32 v148, 1, v4
	v_lshl_add_u64 v[4:5], v[0:1], 0, v[148:149]
	v_lshl_add_u64 v[10:11], v[4:5], 0, v[8:9]
	ds_read_b128 v[4:7], v12 offset:1152
	s_waitcnt lgkmcnt(0)
	global_store_dwordx4 v[10:11], v[4:7], off nt
	s_nop 1
	v_or_b32_e32 v4, 16, v3
	v_mul_u32_u24_e32 v4, s2, v4
	v_lshlrev_b32_e32 v148, 1, v4
	v_lshl_add_u64 v[4:5], v[0:1], 0, v[148:149]
	v_lshl_add_u64 v[10:11], v[4:5], 0, v[8:9]
	ds_read_b128 v[4:7], v12 offset:2304
	s_waitcnt lgkmcnt(0)
	global_store_dwordx4 v[10:11], v[4:7], off nt
	s_nop 1
	v_or_b32_e32 v4, 24, v3
	v_mul_u32_u24_e32 v4, s2, v4
	v_lshlrev_b32_e32 v148, 1, v4
	v_lshl_add_u64 v[4:5], v[0:1], 0, v[148:149]
	v_lshl_add_u64 v[10:11], v[4:5], 0, v[8:9]
	ds_read_b128 v[4:7], v12 offset:3456
	s_waitcnt lgkmcnt(0)
	global_store_dwordx4 v[10:11], v[4:7], off nt
	s_nop 1
	v_or_b32_e32 v4, 32, v3
	v_mul_u32_u24_e32 v4, s2, v4
	v_lshlrev_b32_e32 v148, 1, v4
	v_lshl_add_u64 v[4:5], v[0:1], 0, v[148:149]
	v_lshl_add_u64 v[10:11], v[4:5], 0, v[8:9]
	ds_read_b128 v[4:7], v12 offset:4608
	s_waitcnt lgkmcnt(0)
	global_store_dwordx4 v[10:11], v[4:7], off nt
	s_nop 1
	v_or_b32_e32 v4, 40, v3
	v_mul_u32_u24_e32 v4, s2, v4
	v_lshlrev_b32_e32 v148, 1, v4
	v_lshl_add_u64 v[4:5], v[0:1], 0, v[148:149]
	v_lshl_add_u64 v[10:11], v[4:5], 0, v[8:9]
	ds_read_b128 v[4:7], v12 offset:5760
	s_waitcnt lgkmcnt(0)
; #define TIDX tid_opaque()
; DI float gelu_tanh(float x) {
;   float u = 0.7978845608028654f * (x + 0.044715f * x * x * x);
;   float e = __expf(2.f * u);
;   float t = 1.f - 2.f / (e + 1.f);
;   return 0.5f * x * (1.f + t);
; }
; template <class RP, class SC>
; DI void stage_flush(char* stg, int h, RP rowptr, SC rowscale) {
;   const int lane = TIDX & 63;
;   __builtin_amdgcn_wave_barrier();
; #pragma unroll
;   for (int i = 0; i < 8; i++) {
;     const int c = i * 64 + lane, row = c >> 3, c16 = c & 7;
;     h8 v = *(const h8*)(stg + row * 144 + c16 * 16);
;     half_t* d = rowptr(h * 64 + row);
;     if (d) { rowscale(h * 64 + row, v); *(h8*)(d + c16 * 8) = v; }
;   }
;   __builtin_amdgcn_wave_barrier();
; }
	global_store_dwordx4 v[10:11], v[4:7], off nt
	s_nop 1
	v_or_b32_e32 v4, 48, v3
	v_mul_u32_u24_e32 v4, s2, v4
	v_lshlrev_b32_e32 v148, 1, v4
	v_or_b32_e32 v3, 56, v3
	v_lshl_add_u64 v[4:5], v[0:1], 0, v[148:149]
	v_mul_u32_u24_e32 v3, s2, v3
	v_lshl_add_u64 v[10:11], v[4:5], 0, v[8:9]
	ds_read_b128 v[4:7], v12 offset:6912
	v_lshlrev_b32_e32 v148, 1, v3
	v_mul_f32_e32 v3, 0x3d372713, v220
	v_mul_f32_e32 v3, v220, v3
	v_fma_f32 v3, v220, v3, v220
	v_mul_f32_e32 v3, 0x3f4c422a, v3
	v_add_f32_e32 v3, v3, v3
	s_waitcnt lgkmcnt(0)
	global_store_dwordx4 v[10:11], v[4:7], off nt
	v_mul_f32_e32 v3, 0x3fb8aa3b, v3
	v_exp_f32_e32 v3, v3
	v_lshl_add_u64 v[4:5], v[0:1], 0, v[148:149]
	v_lshl_add_u64 v[8:9], v[4:5], 0, v[8:9]
	ds_read_b128 v[4:7], v12 offset:8064
	v_add_f32_e32 v3, 1.0, v3
	s_waitcnt lgkmcnt(0)
	global_store_dwordx4 v[8:9], v[4:7], off nt
	s_nop 1
	v_div_scale_f32 v4, s[6:7], v3, v3, 2.0
	v_rcp_f32_e32 v5, v4
	s_nop 0
	v_fma_f32 v6, -v4, v5, 1.0
	v_fmac_f32_e32 v5, v6, v5
	v_div_scale_f32 v6, vcc, 2.0, v3, 2.0
	v_mul_f32_e32 v7, v6, v5
	v_fma_f32 v8, -v4, v7, v6
	v_fmac_f32_e32 v7, v8, v5
	v_fma_f32 v4, -v4, v7, v6
	v_div_fmas_f32 v4, v4, v5, v7
	v_div_fixup_f32 v3, v4, v3, 2.0
	v_sub_f32_e32 v3, 1.0, v3
	v_mul_f32_e32 v4, 0.5, v220
	v_add_f32_e32 v3, 1.0, v3
	v_fma_mixlo_f16 v3, v4, v3, 0
	ds_write_b16 v2, v3
	v_mul_f32_e32 v3, 0x3d372713, v219
	v_mul_f32_e32 v3, v219, v3
	v_fma_f32 v3, v219, v3, v219
	v_mul_f32_e32 v3, 0x3f4c422a, v3
	v_add_f32_e32 v3, v3, v3
	v_mul_f32_e32 v3, 0x3fb8aa3b, v3
	v_exp_f32_e32 v3, v3
	s_nop 0
	v_add_f32_e32 v3, 1.0, v3
	v_div_scale_f32 v4, s[6:7], v3, v3, 2.0
	v_rcp_f32_e32 v5, v4
	s_nop 0
	v_fma_f32 v6, -v4, v5, 1.0
	v_fmac_f32_e32 v5, v6, v5
	v_div_scale_f32 v6, vcc, 2.0, v3, 2.0
	v_mul_f32_e32 v7, v6, v5
	v_fma_f32 v8, -v4, v7, v6
	v_fmac_f32_e32 v7, v8, v5
	v_fma_f32 v4, -v4, v7, v6
	v_div_fmas_f32 v4, v4, v5, v7
	v_div_fixup_f32 v3, v4, v3, 2.0
	v_sub_f32_e32 v3, 1.0, v3
	v_mul_f32_e32 v4, 0.5, v219
	v_add_f32_e32 v3, 1.0, v3
	v_fma_mixlo_f16 v3, v4, v3, 0
	ds_write_b16 v2, v3 offset:144
	v_mul_f32_e32 v3, 0x3d372713, v218
	v_mul_f32_e32 v3, v218, v3
	v_fma_f32 v3, v218, v3, v218
	v_mul_f32_e32 v3, 0x3f4c422a, v3
	v_add_f32_e32 v3, v3, v3
	v_mul_f32_e32 v3, 0x3fb8aa3b, v3
	v_exp_f32_e32 v3, v3
	s_nop 0
	v_add_f32_e32 v3, 1.0, v3
	v_div_scale_f32 v4, s[6:7], v3, v3, 2.0
	v_rcp_f32_e32 v5, v4
	s_nop 0
	v_fma_f32 v6, -v4, v5, 1.0
	v_fmac_f32_e32 v5, v6, v5
	v_div_scale_f32 v6, vcc, 2.0, v3, 2.0
	v_mul_f32_e32 v7, v6, v5
	v_fma_f32 v8, -v4, v7, v6
	v_fmac_f32_e32 v7, v8, v5
	v_fma_f32 v4, -v4, v7, v6
	v_div_fmas_f32 v4, v4, v5, v7
	v_div_fixup_f32 v3, v4, v3, 2.0
	v_sub_f32_e32 v3, 1.0, v3
	v_mul_f32_e32 v4, 0.5, v218
	v_add_f32_e32 v3, 1.0, v3
	v_fma_mixlo_f16 v3, v4, v3, 0
	ds_write_b16 v2, v3 offset:288
	v_mul_f32_e32 v3, 0x3d372713, v217
	v_mul_f32_e32 v3, v217, v3
	v_fma_f32 v3, v217, v3, v217
	v_mul_f32_e32 v3, 0x3f4c422a, v3
	v_add_f32_e32 v3, v3, v3
	v_mul_f32_e32 v3, 0x3fb8aa3b, v3
	v_exp_f32_e32 v3, v3
	s_nop 0
	v_add_f32_e32 v3, 1.0, v3
	v_div_scale_f32 v4, s[6:7], v3, v3, 2.0
	v_rcp_f32_e32 v5, v4
	s_nop 0
	v_fma_f32 v6, -v4, v5, 1.0
	v_fmac_f32_e32 v5, v6, v5
	v_div_scale_f32 v6, vcc, 2.0, v3, 2.0
	v_mul_f32_e32 v7, v6, v5
	v_fma_f32 v8, -v4, v7, v6
	v_fmac_f32_e32 v7, v8, v5
	v_fma_f32 v4, -v4, v7, v6
	v_div_fmas_f32 v4, v4, v5, v7
	v_div_fixup_f32 v3, v4, v3, 2.0
	v_sub_f32_e32 v3, 1.0, v3
	v_mul_f32_e32 v4, 0.5, v217
	v_add_f32_e32 v3, 1.0, v3
	v_fma_mixlo_f16 v3, v4, v3, 0
	ds_write_b16 v2, v3 offset:432
	v_mul_f32_e32 v3, 0x3d372713, v216
	v_mul_f32_e32 v3, v216, v3
	v_fma_f32 v3, v216, v3, v216
	v_mul_f32_e32 v3, 0x3f4c422a, v3
	v_add_f32_e32 v3, v3, v3
	v_mul_f32_e32 v3, 0x3fb8aa3b, v3
	v_exp_f32_e32 v3, v3
	s_nop 0
	v_add_f32_e32 v3, 1.0, v3
	v_div_scale_f32 v4, s[6:7], v3, v3, 2.0
	v_rcp_f32_e32 v5, v4
	s_nop 0
	v_fma_f32 v6, -v4, v5, 1.0
	v_fmac_f32_e32 v5, v6, v5
	v_div_scale_f32 v6, vcc, 2.0, v3, 2.0
	v_mul_f32_e32 v7, v6, v5
	v_fma_f32 v8, -v4, v7, v6
	v_fmac_f32_e32 v7, v8, v5
	v_fma_f32 v4, -v4, v7, v6
	v_div_fmas_f32 v4, v4, v5, v7
	v_div_fixup_f32 v3, v4, v3, 2.0
	v_sub_f32_e32 v3, 1.0, v3
	v_mul_f32_e32 v4, 0.5, v216
	v_add_f32_e32 v3, 1.0, v3
	v_fma_mixlo_f16 v3, v4, v3, 0
	ds_write_b16 v2, v3 offset:32
	v_mul_f32_e32 v3, 0x3d372713, v215
	v_mul_f32_e32 v3, v215, v3
	v_fma_f32 v3, v215, v3, v215
	v_mul_f32_e32 v3, 0x3f4c422a, v3
	v_add_f32_e32 v3, v3, v3
	v_mul_f32_e32 v3, 0x3fb8aa3b, v3
	v_exp_f32_e32 v3, v3
	s_nop 0
	v_add_f32_e32 v3, 1.0, v3
	v_div_scale_f32 v4, s[6:7], v3, v3, 2.0
	v_rcp_f32_e32 v5, v4
	s_nop 0
	v_fma_f32 v6, -v4, v5, 1.0
	v_fmac_f32_e32 v5, v6, v5
	v_div_scale_f32 v6, vcc, 2.0, v3, 2.0
	v_mul_f32_e32 v7, v6, v5
	v_fma_f32 v8, -v4, v7, v6
	v_fmac_f32_e32 v7, v8, v5
	v_fma_f32 v4, -v4, v7, v6
	v_div_fmas_f32 v4, v4, v5, v7
	v_div_fixup_f32 v3, v4, v3, 2.0
	v_sub_f32_e32 v3, 1.0, v3
	v_mul_f32_e32 v4, 0.5, v215
	v_add_f32_e32 v3, 1.0, v3
	v_fma_mixlo_f16 v3, v4, v3, 0
	ds_write_b16 v2, v3 offset:176
	v_mul_f32_e32 v3, 0x3d372713, v214
	v_mul_f32_e32 v3, v214, v3
	v_fma_f32 v3, v214, v3, v214
	v_mul_f32_e32 v3, 0x3f4c422a, v3
	v_add_f32_e32 v3, v3, v3
	v_mul_f32_e32 v3, 0x3fb8aa3b, v3
	v_exp_f32_e32 v3, v3
	s_nop 0
	v_add_f32_e32 v3, 1.0, v3
	v_div_scale_f32 v4, s[6:7], v3, v3, 2.0
	v_rcp_f32_e32 v5, v4
	s_nop 0
	v_fma_f32 v6, -v4, v5, 1.0
	v_fmac_f32_e32 v5, v6, v5
	v_div_scale_f32 v6, vcc, 2.0, v3, 2.0
	v_mul_f32_e32 v7, v6, v5
	v_fma_f32 v8, -v4, v7, v6
	v_fmac_f32_e32 v7, v8, v5
	v_fma_f32 v4, -v4, v7, v6
	v_div_fmas_f32 v4, v4, v5, v7
	v_div_fixup_f32 v3, v4, v3, 2.0
	v_sub_f32_e32 v3, 1.0, v3
	v_mul_f32_e32 v4, 0.5, v214
	v_add_f32_e32 v3, 1.0, v3
; DI float gelu_tanh(float x) {
;   float u = 0.7978845608028654f * (x + 0.044715f * x * x * x);
;   float e = __expf(2.f * u);
;   float t = 1.f - 2.f / (e + 1.f);
;   return 0.5f * x * (1.f + t);
; }
; DI void gemm_in_phase(const Params& P, int l, char* smem) {
;     ...
;       if (gel) wave_store_tile([&](int m, int n, int j) { return gelu_tanh(acc[m][n][j]); }, stg, [&](int r) { return base + (size_t)r * ld; }, noscale);
	v_fma_mixlo_f16 v3, v4, v3, 0
	ds_write_b16 v2, v3 offset:320
	v_mul_f32_e32 v3, 0x3d372713, v213
	v_mul_f32_e32 v3, v213, v3
	v_fma_f32 v3, v213, v3, v213
	v_mul_f32_e32 v3, 0x3f4c422a, v3
	v_add_f32_e32 v3, v3, v3
	v_mul_f32_e32 v3, 0x3fb8aa3b, v3
	v_exp_f32_e32 v3, v3
	s_nop 0
	v_add_f32_e32 v3, 1.0, v3
	v_div_scale_f32 v4, s[6:7], v3, v3, 2.0
	v_rcp_f32_e32 v5, v4
	s_nop 0
	v_fma_f32 v6, -v4, v5, 1.0
	v_fmac_f32_e32 v5, v6, v5
	v_div_scale_f32 v6, vcc, 2.0, v3, 2.0
	v_mul_f32_e32 v7, v6, v5
	v_fma_f32 v8, -v4, v7, v6
	v_fmac_f32_e32 v7, v8, v5
	v_fma_f32 v4, -v4, v7, v6
	v_div_fmas_f32 v4, v4, v5, v7
	v_div_fixup_f32 v3, v4, v3, 2.0
	v_sub_f32_e32 v3, 1.0, v3
	v_mul_f32_e32 v4, 0.5, v213
	v_add_f32_e32 v3, 1.0, v3
	v_fma_mixlo_f16 v3, v4, v3, 0
	ds_write_b16 v2, v3 offset:464
	v_mul_f32_e32 v3, 0x3d372713, v212
	v_mul_f32_e32 v3, v212, v3
	v_fma_f32 v3, v212, v3, v212
	v_mul_f32_e32 v3, 0x3f4c422a, v3
	v_add_f32_e32 v3, v3, v3
	v_mul_f32_e32 v3, 0x3fb8aa3b, v3
	v_exp_f32_e32 v3, v3
	s_nop 0
	v_add_f32_e32 v3, 1.0, v3
	v_div_scale_f32 v4, s[6:7], v3, v3, 2.0
	v_rcp_f32_e32 v5, v4
	s_nop 0
	v_fma_f32 v6, -v4, v5, 1.0
	v_fmac_f32_e32 v5, v6, v5
	v_div_scale_f32 v6, vcc, 2.0, v3, 2.0
	v_mul_f32_e32 v7, v6, v5
	v_fma_f32 v8, -v4, v7, v6
	v_fmac_f32_e32 v7, v8, v5
	v_fma_f32 v4, -v4, v7, v6
	v_div_fmas_f32 v4, v4, v5, v7
	v_div_fixup_f32 v3, v4, v3, 2.0
	v_sub_f32_e32 v3, 1.0, v3
	v_mul_f32_e32 v4, 0.5, v212
	v_add_f32_e32 v3, 1.0, v3
	v_fma_mixlo_f16 v3, v4, v3, 0
	ds_write_b16 v2, v3 offset:64
	v_mul_f32_e32 v3, 0x3d372713, v211
	v_mul_f32_e32 v3, v211, v3
	v_fma_f32 v3, v211, v3, v211
	v_mul_f32_e32 v3, 0x3f4c422a, v3
	v_add_f32_e32 v3, v3, v3
	v_mul_f32_e32 v3, 0x3fb8aa3b, v3
	v_exp_f32_e32 v3, v3
	s_nop 0
	v_add_f32_e32 v3, 1.0, v3
	v_div_scale_f32 v4, s[6:7], v3, v3, 2.0
	v_rcp_f32_e32 v5, v4
	s_nop 0
	v_fma_f32 v6, -v4, v5, 1.0
	v_fmac_f32_e32 v5, v6, v5
	v_div_scale_f32 v6, vcc, 2.0, v3, 2.0
	v_mul_f32_e32 v7, v6, v5
	v_fma_f32 v8, -v4, v7, v6
	v_fmac_f32_e32 v7, v8, v5
	v_fma_f32 v4, -v4, v7, v6
	v_div_fmas_f32 v4, v4, v5, v7
	v_div_fixup_f32 v3, v4, v3, 2.0
	v_sub_f32_e32 v3, 1.0, v3
	v_mul_f32_e32 v4, 0.5, v211
	v_add_f32_e32 v3, 1.0, v3
	v_fma_mixlo_f16 v3, v4, v3, 0
	ds_write_b16 v2, v3 offset:208
	v_mul_f32_e32 v3, 0x3d372713, v210
	v_mul_f32_e32 v3, v210, v3
	v_fma_f32 v3, v210, v3, v210
	v_mul_f32_e32 v3, 0x3f4c422a, v3
	v_add_f32_e32 v3, v3, v3
	v_mul_f32_e32 v3, 0x3fb8aa3b, v3
	v_exp_f32_e32 v3, v3
	s_nop 0
	v_add_f32_e32 v3, 1.0, v3
	v_div_scale_f32 v4, s[6:7], v3, v3, 2.0
	v_rcp_f32_e32 v5, v4
	s_nop 0
	v_fma_f32 v6, -v4, v5, 1.0
	v_fmac_f32_e32 v5, v6, v5
	v_div_scale_f32 v6, vcc, 2.0, v3, 2.0
	v_mul_f32_e32 v7, v6, v5
	v_fma_f32 v8, -v4, v7, v6
	v_fmac_f32_e32 v7, v8, v5
	v_fma_f32 v4, -v4, v7, v6
	v_div_fmas_f32 v4, v4, v5, v7
	v_div_fixup_f32 v3, v4, v3, 2.0
	v_sub_f32_e32 v3, 1.0, v3
	v_mul_f32_e32 v4, 0.5, v210
	v_add_f32_e32 v3, 1.0, v3
	v_fma_mixlo_f16 v3, v4, v3, 0
	ds_write_b16 v2, v3 offset:352
	v_mul_f32_e32 v3, 0x3d372713, v209
	v_mul_f32_e32 v3, v209, v3
	v_fma_f32 v3, v209, v3, v209
	v_mul_f32_e32 v3, 0x3f4c422a, v3
	v_add_f32_e32 v3, v3, v3
	v_mul_f32_e32 v3, 0x3fb8aa3b, v3
	v_exp_f32_e32 v3, v3
	s_nop 0
	v_add_f32_e32 v3, 1.0, v3
	v_div_scale_f32 v4, s[6:7], v3, v3, 2.0
	v_rcp_f32_e32 v5, v4
	s_nop 0
	v_fma_f32 v6, -v4, v5, 1.0
	v_fmac_f32_e32 v5, v6, v5
	v_div_scale_f32 v6, vcc, 2.0, v3, 2.0
	v_mul_f32_e32 v7, v6, v5
	v_fma_f32 v8, -v4, v7, v6
	v_fmac_f32_e32 v7, v8, v5
	v_fma_f32 v4, -v4, v7, v6
	v_div_fmas_f32 v4, v4, v5, v7
	v_div_fixup_f32 v3, v4, v3, 2.0
	v_sub_f32_e32 v3, 1.0, v3
	v_mul_f32_e32 v4, 0.5, v209
	v_add_f32_e32 v3, 1.0, v3
	v_fma_mixlo_f16 v3, v4, v3, 0
	ds_write_b16 v2, v3 offset:496
	v_mul_f32_e32 v3, 0x3d372713, v208
	v_mul_f32_e32 v3, v208, v3
	v_fma_f32 v3, v208, v3, v208
	v_mul_f32_e32 v3, 0x3f4c422a, v3
	v_add_f32_e32 v3, v3, v3
	v_mul_f32_e32 v3, 0x3fb8aa3b, v3
	v_exp_f32_e32 v3, v3
	s_nop 0
	v_add_f32_e32 v3, 1.0, v3
	v_div_scale_f32 v4, s[6:7], v3, v3, 2.0
	v_rcp_f32_e32 v5, v4
	s_nop 0
	v_fma_f32 v6, -v4, v5, 1.0
	v_fmac_f32_e32 v5, v6, v5
	v_div_scale_f32 v6, vcc, 2.0, v3, 2.0
	v_mul_f32_e32 v7, v6, v5
	v_fma_f32 v8, -v4, v7, v6
	v_fmac_f32_e32 v7, v8, v5
	v_fma_f32 v4, -v4, v7, v6
	v_div_fmas_f32 v4, v4, v5, v7
	v_div_fixup_f32 v3, v4, v3, 2.0
	v_sub_f32_e32 v3, 1.0, v3
	v_mul_f32_e32 v4, 0.5, v208
	v_add_f32_e32 v3, 1.0, v3
	v_fma_mixlo_f16 v3, v4, v3, 0
	ds_write_b16 v2, v3 offset:96
	v_mul_f32_e32 v3, 0x3d372713, v207
	v_mul_f32_e32 v3, v207, v3
	v_fma_f32 v3, v207, v3, v207
	v_mul_f32_e32 v3, 0x3f4c422a, v3
	v_add_f32_e32 v3, v3, v3
	v_mul_f32_e32 v3, 0x3fb8aa3b, v3
	v_exp_f32_e32 v3, v3
	s_nop 0
	v_add_f32_e32 v3, 1.0, v3
	v_div_scale_f32 v4, s[6:7], v3, v3, 2.0
	v_rcp_f32_e32 v5, v4
	s_nop 0
	v_fma_f32 v6, -v4, v5, 1.0
	v_fmac_f32_e32 v5, v6, v5
	v_div_scale_f32 v6, vcc, 2.0, v3, 2.0
	v_mul_f32_e32 v7, v6, v5
	v_fma_f32 v8, -v4, v7, v6
	v_fmac_f32_e32 v7, v8, v5
	v_fma_f32 v4, -v4, v7, v6
	v_div_fmas_f32 v4, v4, v5, v7
	v_div_fixup_f32 v3, v4, v3, 2.0
	v_sub_f32_e32 v3, 1.0, v3
	v_mul_f32_e32 v4, 0.5, v207
	v_add_f32_e32 v3, 1.0, v3
	v_fma_mixlo_f16 v3, v4, v3, 0
	ds_write_b16 v2, v3 offset:240
	v_mul_f32_e32 v3, 0x3d372713, v206
	v_mul_f32_e32 v3, v206, v3
	v_fma_f32 v3, v206, v3, v206
	v_mul_f32_e32 v3, 0x3f4c422a, v3
	v_add_f32_e32 v3, v3, v3
	v_mul_f32_e32 v3, 0x3fb8aa3b, v3
	v_exp_f32_e32 v3, v3
	s_nop 0
	v_add_f32_e32 v3, 1.0, v3
	v_div_scale_f32 v4, s[6:7], v3, v3, 2.0
	v_rcp_f32_e32 v5, v4
	s_nop 0
	v_fma_f32 v6, -v4, v5, 1.0
	v_fmac_f32_e32 v5, v6, v5
	v_div_scale_f32 v6, vcc, 2.0, v3, 2.0
	v_mul_f32_e32 v7, v6, v5
	v_fma_f32 v8, -v4, v7, v6
; DI float gelu_tanh(float x) {
;   float u = 0.7978845608028654f * (x + 0.044715f * x * x * x);
;   float e = __expf(2.f * u);
;   float t = 1.f - 2.f / (e + 1.f);
;   return 0.5f * x * (1.f + t);
; }
; DI void gemm_in_phase(const Params& P, int l, char* smem) {
;     ...
;       if (gel) wave_store_tile([&](int m, int n, int j) { return gelu_tanh(acc[m][n][j]); }, stg, [&](int r) { return base + (size_t)r * ld; }, noscale);
	v_fmac_f32_e32 v7, v8, v5
	v_fma_f32 v4, -v4, v7, v6
	v_div_fmas_f32 v4, v4, v5, v7
	v_div_fixup_f32 v3, v4, v3, 2.0
	v_sub_f32_e32 v3, 1.0, v3
	v_mul_f32_e32 v4, 0.5, v206
	v_add_f32_e32 v3, 1.0, v3
	v_fma_mixlo_f16 v3, v4, v3, 0
	ds_write_b16 v2, v3 offset:384
	v_mul_f32_e32 v3, 0x3d372713, v205
	v_mul_f32_e32 v3, v205, v3
	v_fma_f32 v3, v205, v3, v205
	v_mul_f32_e32 v3, 0x3f4c422a, v3
	v_add_f32_e32 v3, v3, v3
	v_mul_f32_e32 v3, 0x3fb8aa3b, v3
	v_exp_f32_e32 v3, v3
	s_nop 0
	v_add_f32_e32 v3, 1.0, v3
	v_div_scale_f32 v4, s[6:7], v3, v3, 2.0
	v_rcp_f32_e32 v5, v4
	s_nop 0
	v_fma_f32 v6, -v4, v5, 1.0
	v_fmac_f32_e32 v5, v6, v5
	v_div_scale_f32 v6, vcc, 2.0, v3, 2.0
	v_mul_f32_e32 v7, v6, v5
	v_fma_f32 v8, -v4, v7, v6
	v_fmac_f32_e32 v7, v8, v5
	v_fma_f32 v4, -v4, v7, v6
	v_div_fmas_f32 v4, v4, v5, v7
	v_div_fixup_f32 v3, v4, v3, 2.0
	v_sub_f32_e32 v3, 1.0, v3
	v_mul_f32_e32 v4, 0.5, v205
	v_add_f32_e32 v3, 1.0, v3
	v_fma_mixlo_f16 v3, v4, v3, 0
	ds_write_b16 v2, v3 offset:528
	v_mul_f32_e32 v3, 0x3d372713, v204
	v_mul_f32_e32 v3, v204, v3
	v_fma_f32 v3, v204, v3, v204
	v_mul_f32_e32 v3, 0x3f4c422a, v3
	v_add_f32_e32 v3, v3, v3
	v_mul_f32_e32 v3, 0x3fb8aa3b, v3
	v_exp_f32_e32 v3, v3
	s_nop 0
	v_add_f32_e32 v3, 1.0, v3
	v_div_scale_f32 v4, s[6:7], v3, v3, 2.0
	v_rcp_f32_e32 v5, v4
	s_nop 0
	v_fma_f32 v6, -v4, v5, 1.0
	v_fmac_f32_e32 v5, v6, v5
	v_div_scale_f32 v6, vcc, 2.0, v3, 2.0
	v_mul_f32_e32 v7, v6, v5
	v_fma_f32 v8, -v4, v7, v6
	v_fmac_f32_e32 v7, v8, v5
	v_fma_f32 v4, -v4, v7, v6
	v_div_fmas_f32 v4, v4, v5, v7
	v_div_fixup_f32 v3, v4, v3, 2.0
	v_sub_f32_e32 v3, 1.0, v3
	v_mul_f32_e32 v4, 0.5, v204
	v_add_f32_e32 v3, 1.0, v3
	v_fma_mixlo_f16 v3, v4, v3, 0
	ds_write_b16 v2, v3 offset:2304
	v_mul_f32_e32 v3, 0x3d372713, v203
	v_mul_f32_e32 v3, v203, v3
	v_fma_f32 v3, v203, v3, v203
	v_mul_f32_e32 v3, 0x3f4c422a, v3
	v_add_f32_e32 v3, v3, v3
	v_mul_f32_e32 v3, 0x3fb8aa3b, v3
	v_exp_f32_e32 v3, v3
	s_nop 0
	v_add_f32_e32 v3, 1.0, v3
	v_div_scale_f32 v4, s[6:7], v3, v3, 2.0
	v_rcp_f32_e32 v5, v4
	s_nop 0
	v_fma_f32 v6, -v4, v5, 1.0
	v_fmac_f32_e32 v5, v6, v5
	v_div_scale_f32 v6, vcc, 2.0, v3, 2.0
	v_mul_f32_e32 v7, v6, v5
	v_fma_f32 v8, -v4, v7, v6
	v_fmac_f32_e32 v7, v8, v5
	v_fma_f32 v4, -v4, v7, v6
	v_div_fmas_f32 v4, v4, v5, v7
	v_div_fixup_f32 v3, v4, v3, 2.0
	v_sub_f32_e32 v3, 1.0, v3
	v_mul_f32_e32 v4, 0.5, v203
	v_add_f32_e32 v3, 1.0, v3
	v_fma_mixlo_f16 v3, v4, v3, 0
	ds_write_b16 v2, v3 offset:2448
	v_mul_f32_e32 v3, 0x3d372713, v202
	v_mul_f32_e32 v3, v202, v3
	v_fma_f32 v3, v202, v3, v202
	v_mul_f32_e32 v3, 0x3f4c422a, v3
	v_add_f32_e32 v3, v3, v3
	v_mul_f32_e32 v3, 0x3fb8aa3b, v3
	v_exp_f32_e32 v3, v3
	s_nop 0
	v_add_f32_e32 v3, 1.0, v3
	v_div_scale_f32 v4, s[6:7], v3, v3, 2.0
	v_rcp_f32_e32 v5, v4
	s_nop 0
	v_fma_f32 v6, -v4, v5, 1.0
	v_fmac_f32_e32 v5, v6, v5
	v_div_scale_f32 v6, vcc, 2.0, v3, 2.0
	v_mul_f32_e32 v7, v6, v5
	v_fma_f32 v8, -v4, v7, v6
	v_fmac_f32_e32 v7, v8, v5
	v_fma_f32 v4, -v4, v7, v6
	v_div_fmas_f32 v4, v4, v5, v7
	v_div_fixup_f32 v3, v4, v3, 2.0
	v_sub_f32_e32 v3, 1.0, v3
	v_mul_f32_e32 v4, 0.5, v202
	v_add_f32_e32 v3, 1.0, v3
	v_fma_mixlo_f16 v3, v4, v3, 0
	ds_write_b16 v2, v3 offset:2592
	v_mul_f32_e32 v3, 0x3d372713, v201
	v_mul_f32_e32 v3, v201, v3
	v_fma_f32 v3, v201, v3, v201
	v_mul_f32_e32 v3, 0x3f4c422a, v3
	v_add_f32_e32 v3, v3, v3
	v_mul_f32_e32 v3, 0x3fb8aa3b, v3
	v_exp_f32_e32 v3, v3
	s_nop 0
	v_add_f32_e32 v3, 1.0, v3
	v_div_scale_f32 v4, s[6:7], v3, v3, 2.0
	v_rcp_f32_e32 v5, v4
	s_nop 0
	v_fma_f32 v6, -v4, v5, 1.0
	v_fmac_f32_e32 v5, v6, v5
	v_div_scale_f32 v6, vcc, 2.0, v3, 2.0
	v_mul_f32_e32 v7, v6, v5
	v_fma_f32 v8, -v4, v7, v6
	v_fmac_f32_e32 v7, v8, v5
	v_fma_f32 v4, -v4, v7, v6
	v_div_fmas_f32 v4, v4, v5, v7
	v_div_fixup_f32 v3, v4, v3, 2.0
	v_sub_f32_e32 v3, 1.0, v3
	v_mul_f32_e32 v4, 0.5, v201
	v_add_f32_e32 v3, 1.0, v3
	v_fma_mixlo_f16 v3, v4, v3, 0
	ds_write_b16 v2, v3 offset:2736
	v_mul_f32_e32 v3, 0x3d372713, v200
	v_mul_f32_e32 v3, v200, v3
	v_fma_f32 v3, v200, v3, v200
	v_mul_f32_e32 v3, 0x3f4c422a, v3
	v_add_f32_e32 v3, v3, v3
	v_mul_f32_e32 v3, 0x3fb8aa3b, v3
	v_exp_f32_e32 v3, v3
	s_nop 0
	v_add_f32_e32 v3, 1.0, v3
	v_div_scale_f32 v4, s[6:7], v3, v3, 2.0
	v_rcp_f32_e32 v5, v4
	s_nop 0
	v_fma_f32 v6, -v4, v5, 1.0
	v_fmac_f32_e32 v5, v6, v5
	v_div_scale_f32 v6, vcc, 2.0, v3, 2.0
	v_mul_f32_e32 v7, v6, v5
	v_fma_f32 v8, -v4, v7, v6
	v_fmac_f32_e32 v7, v8, v5
	v_fma_f32 v4, -v4, v7, v6
	v_div_fmas_f32 v4, v4, v5, v7
	v_div_fixup_f32 v3, v4, v3, 2.0
	v_sub_f32_e32 v3, 1.0, v3
	v_mul_f32_e32 v4, 0.5, v200
	v_add_f32_e32 v3, 1.0, v3
	v_fma_mixlo_f16 v3, v4, v3, 0
	ds_write_b16 v2, v3 offset:2336
	v_mul_f32_e32 v3, 0x3d372713, v199
	v_mul_f32_e32 v3, v199, v3
	v_fma_f32 v3, v199, v3, v199
	v_mul_f32_e32 v3, 0x3f4c422a, v3
	v_add_f32_e32 v3, v3, v3
	v_mul_f32_e32 v3, 0x3fb8aa3b, v3
	v_exp_f32_e32 v3, v3
	s_nop 0
	v_add_f32_e32 v3, 1.0, v3
	v_div_scale_f32 v4, s[6:7], v3, v3, 2.0
	v_rcp_f32_e32 v5, v4
	s_nop 0
	v_fma_f32 v6, -v4, v5, 1.0
	v_fmac_f32_e32 v5, v6, v5
	v_div_scale_f32 v6, vcc, 2.0, v3, 2.0
	v_mul_f32_e32 v7, v6, v5
	v_fma_f32 v8, -v4, v7, v6
	v_fmac_f32_e32 v7, v8, v5
	v_fma_f32 v4, -v4, v7, v6
	v_div_fmas_f32 v4, v4, v5, v7
	v_div_fixup_f32 v3, v4, v3, 2.0
	v_sub_f32_e32 v3, 1.0, v3
	v_mul_f32_e32 v4, 0.5, v199
	v_add_f32_e32 v3, 1.0, v3
	v_fma_mixlo_f16 v3, v4, v3, 0
	ds_write_b16 v2, v3 offset:2480
	v_mul_f32_e32 v3, 0x3d372713, v198
	v_mul_f32_e32 v3, v198, v3
	v_fma_f32 v3, v198, v3, v198
	v_mul_f32_e32 v3, 0x3f4c422a, v3
	v_add_f32_e32 v3, v3, v3
	v_mul_f32_e32 v3, 0x3fb8aa3b, v3
	v_exp_f32_e32 v3, v3
	s_nop 0
	v_add_f32_e32 v3, 1.0, v3
	v_div_scale_f32 v4, s[6:7], v3, v3, 2.0
; DI float gelu_tanh(float x) {
;   float u = 0.7978845608028654f * (x + 0.044715f * x * x * x);
;   float e = __expf(2.f * u);
;   float t = 1.f - 2.f / (e + 1.f);
;   return 0.5f * x * (1.f + t);
; }
; DI void gemm_in_phase(const Params& P, int l, char* smem) {
;     ...
;       if (gel) wave_store_tile([&](int m, int n, int j) { return gelu_tanh(acc[m][n][j]); }, stg, [&](int r) { return base + (size_t)r * ld; }, noscale);
	v_rcp_f32_e32 v5, v4
	s_nop 0
	v_fma_f32 v6, -v4, v5, 1.0
	v_fmac_f32_e32 v5, v6, v5
	v_div_scale_f32 v6, vcc, 2.0, v3, 2.0
	v_mul_f32_e32 v7, v6, v5
	v_fma_f32 v8, -v4, v7, v6
	v_fmac_f32_e32 v7, v8, v5
	v_fma_f32 v4, -v4, v7, v6
	v_div_fmas_f32 v4, v4, v5, v7
	v_div_fixup_f32 v3, v4, v3, 2.0
	v_sub_f32_e32 v3, 1.0, v3
	v_mul_f32_e32 v4, 0.5, v198
	v_add_f32_e32 v3, 1.0, v3
	v_fma_mixlo_f16 v3, v4, v3, 0
	ds_write_b16 v2, v3 offset:2624
	v_mul_f32_e32 v3, 0x3d372713, v197
	v_mul_f32_e32 v3, v197, v3
	v_fma_f32 v3, v197, v3, v197
	v_mul_f32_e32 v3, 0x3f4c422a, v3
	v_add_f32_e32 v3, v3, v3
	v_mul_f32_e32 v3, 0x3fb8aa3b, v3
	v_exp_f32_e32 v3, v3
	s_nop 0
	v_add_f32_e32 v3, 1.0, v3
	v_div_scale_f32 v4, s[6:7], v3, v3, 2.0
	v_rcp_f32_e32 v5, v4
	s_nop 0
	v_fma_f32 v6, -v4, v5, 1.0
	v_fmac_f32_e32 v5, v6, v5
	v_div_scale_f32 v6, vcc, 2.0, v3, 2.0
	v_mul_f32_e32 v7, v6, v5
	v_fma_f32 v8, -v4, v7, v6
	v_fmac_f32_e32 v7, v8, v5
	v_fma_f32 v4, -v4, v7, v6
	v_div_fmas_f32 v4, v4, v5, v7
	v_div_fixup_f32 v3, v4, v3, 2.0
	v_sub_f32_e32 v3, 1.0, v3
	v_mul_f32_e32 v4, 0.5, v197
	v_add_f32_e32 v3, 1.0, v3
	v_fma_mixlo_f16 v3, v4, v3, 0
	ds_write_b16 v2, v3 offset:2768
	v_mul_f32_e32 v3, 0x3d372713, v171
	v_mul_f32_e32 v3, v171, v3
	v_fma_f32 v3, v171, v3, v171
	v_mul_f32_e32 v3, 0x3f4c422a, v3
	v_add_f32_e32 v3, v3, v3
	v_mul_f32_e32 v3, 0x3fb8aa3b, v3
	v_exp_f32_e32 v3, v3
	s_nop 0
	v_add_f32_e32 v3, 1.0, v3
	v_div_scale_f32 v4, s[6:7], v3, v3, 2.0
	v_rcp_f32_e32 v5, v4
	s_nop 0
	v_fma_f32 v6, -v4, v5, 1.0
	v_fmac_f32_e32 v5, v6, v5
	v_div_scale_f32 v6, vcc, 2.0, v3, 2.0
	v_mul_f32_e32 v7, v6, v5
	v_fma_f32 v8, -v4, v7, v6
	v_fmac_f32_e32 v7, v8, v5
	v_fma_f32 v4, -v4, v7, v6
	v_div_fmas_f32 v4, v4, v5, v7
	v_div_fixup_f32 v3, v4, v3, 2.0
	v_sub_f32_e32 v3, 1.0, v3
	v_mul_f32_e32 v4, 0.5, v171
	v_add_f32_e32 v3, 1.0, v3
	v_fma_mixlo_f16 v3, v4, v3, 0
	ds_write_b16 v2, v3 offset:2368
	v_mul_f32_e32 v3, 0x3d372713, v170
	v_mul_f32_e32 v3, v170, v3
	v_fma_f32 v3, v170, v3, v170
	v_mul_f32_e32 v3, 0x3f4c422a, v3
	v_add_f32_e32 v3, v3, v3
	v_mul_f32_e32 v3, 0x3fb8aa3b, v3
	v_exp_f32_e32 v3, v3
	s_nop 0
	v_add_f32_e32 v3, 1.0, v3
	v_div_scale_f32 v4, s[6:7], v3, v3, 2.0
	v_rcp_f32_e32 v5, v4
	s_nop 0
	v_fma_f32 v6, -v4, v5, 1.0
	v_fmac_f32_e32 v5, v6, v5
	v_div_scale_f32 v6, vcc, 2.0, v3, 2.0
	v_mul_f32_e32 v7, v6, v5
	v_fma_f32 v8, -v4, v7, v6
	v_fmac_f32_e32 v7, v8, v5
	v_fma_f32 v4, -v4, v7, v6
	v_div_fmas_f32 v4, v4, v5, v7
	v_div_fixup_f32 v3, v4, v3, 2.0
	v_sub_f32_e32 v3, 1.0, v3
	v_mul_f32_e32 v4, 0.5, v170
	v_add_f32_e32 v3, 1.0, v3
	v_fma_mixlo_f16 v3, v4, v3, 0
	ds_write_b16 v2, v3 offset:2512
	v_mul_f32_e32 v3, 0x3d372713, v169
	v_mul_f32_e32 v3, v169, v3
	v_fma_f32 v3, v169, v3, v169
	v_mul_f32_e32 v3, 0x3f4c422a, v3
	v_add_f32_e32 v3, v3, v3
	v_mul_f32_e32 v3, 0x3fb8aa3b, v3
	v_exp_f32_e32 v3, v3
	s_nop 0
	v_add_f32_e32 v3, 1.0, v3
	v_div_scale_f32 v4, s[6:7], v3, v3, 2.0
	v_rcp_f32_e32 v5, v4
	s_nop 0
	v_fma_f32 v6, -v4, v5, 1.0
	v_fmac_f32_e32 v5, v6, v5
	v_div_scale_f32 v6, vcc, 2.0, v3, 2.0
	v_mul_f32_e32 v7, v6, v5
	v_fma_f32 v8, -v4, v7, v6
	v_fmac_f32_e32 v7, v8, v5
	v_fma_f32 v4, -v4, v7, v6
	v_div_fmas_f32 v4, v4, v5, v7
	v_div_fixup_f32 v3, v4, v3, 2.0
	v_sub_f32_e32 v3, 1.0, v3
	v_mul_f32_e32 v4, 0.5, v169
	v_add_f32_e32 v3, 1.0, v3
	v_fma_mixlo_f16 v3, v4, v3, 0
	ds_write_b16 v2, v3 offset:2656
	v_mul_f32_e32 v3, 0x3d372713, v168
	v_mul_f32_e32 v3, v168, v3
	v_fma_f32 v3, v168, v3, v168
	v_mul_f32_e32 v3, 0x3f4c422a, v3
	v_add_f32_e32 v3, v3, v3
	v_mul_f32_e32 v3, 0x3fb8aa3b, v3
	v_exp_f32_e32 v3, v3
	s_nop 0
	v_add_f32_e32 v3, 1.0, v3
	v_div_scale_f32 v4, s[6:7], v3, v3, 2.0
	v_rcp_f32_e32 v5, v4
	s_nop 0
	v_fma_f32 v6, -v4, v5, 1.0
	v_fmac_f32_e32 v5, v6, v5
	v_div_scale_f32 v6, vcc, 2.0, v3, 2.0
	v_mul_f32_e32 v7, v6, v5
	v_fma_f32 v8, -v4, v7, v6
	v_fmac_f32_e32 v7, v8, v5
	v_fma_f32 v4, -v4, v7, v6
	v_div_fmas_f32 v4, v4, v5, v7
	v_div_fixup_f32 v3, v4, v3, 2.0
	v_sub_f32_e32 v3, 1.0, v3
	v_mul_f32_e32 v4, 0.5, v168
	v_add_f32_e32 v3, 1.0, v3
	v_fma_mixlo_f16 v3, v4, v3, 0
	ds_write_b16 v2, v3 offset:2800
	v_mul_f32_e32 v3, 0x3d372713, v167
	v_mul_f32_e32 v3, v167, v3
	v_fma_f32 v3, v167, v3, v167
	v_mul_f32_e32 v3, 0x3f4c422a, v3
	v_add_f32_e32 v3, v3, v3
	v_mul_f32_e32 v3, 0x3fb8aa3b, v3
	v_exp_f32_e32 v3, v3
	s_nop 0
	v_add_f32_e32 v3, 1.0, v3
	v_div_scale_f32 v4, s[6:7], v3, v3, 2.0
	v_rcp_f32_e32 v5, v4
	s_nop 0
	v_fma_f32 v6, -v4, v5, 1.0
	v_fmac_f32_e32 v5, v6, v5
	v_div_scale_f32 v6, vcc, 2.0, v3, 2.0
	v_mul_f32_e32 v7, v6, v5
	v_fma_f32 v8, -v4, v7, v6
	v_fmac_f32_e32 v7, v8, v5
	v_fma_f32 v4, -v4, v7, v6
	v_div_fmas_f32 v4, v4, v5, v7
	v_div_fixup_f32 v3, v4, v3, 2.0
	v_sub_f32_e32 v3, 1.0, v3
	v_mul_f32_e32 v4, 0.5, v167
	v_add_f32_e32 v3, 1.0, v3
	v_fma_mixlo_f16 v3, v4, v3, 0
	ds_write_b16 v2, v3 offset:2400
	v_mul_f32_e32 v3, 0x3d372713, v166
	v_mul_f32_e32 v3, v166, v3
	v_fma_f32 v3, v166, v3, v166
	v_mul_f32_e32 v3, 0x3f4c422a, v3
	v_add_f32_e32 v3, v3, v3
	v_mul_f32_e32 v3, 0x3fb8aa3b, v3
	v_exp_f32_e32 v3, v3
	s_nop 0
	v_add_f32_e32 v3, 1.0, v3
	v_div_scale_f32 v4, s[6:7], v3, v3, 2.0
	v_rcp_f32_e32 v5, v4
	s_nop 0
	v_fma_f32 v6, -v4, v5, 1.0
	v_fmac_f32_e32 v5, v6, v5
	v_div_scale_f32 v6, vcc, 2.0, v3, 2.0
	v_mul_f32_e32 v7, v6, v5
	v_fma_f32 v8, -v4, v7, v6
	v_fmac_f32_e32 v7, v8, v5
	v_fma_f32 v4, -v4, v7, v6
	v_div_fmas_f32 v4, v4, v5, v7
	v_div_fixup_f32 v3, v4, v3, 2.0
	v_sub_f32_e32 v3, 1.0, v3
	v_mul_f32_e32 v4, 0.5, v166
	v_add_f32_e32 v3, 1.0, v3
	v_fma_mixlo_f16 v3, v4, v3, 0
	ds_write_b16 v2, v3 offset:2544
	v_mul_f32_e32 v3, 0x3d372713, v165
	v_mul_f32_e32 v3, v165, v3
	v_fma_f32 v3, v165, v3, v165
; DI float gelu_tanh(float x) {
;   float u = 0.7978845608028654f * (x + 0.044715f * x * x * x);
;   float e = __expf(2.f * u);
;   float t = 1.f - 2.f / (e + 1.f);
;   return 0.5f * x * (1.f + t);
; }
; DI void gemm_in_phase(const Params& P, int l, char* smem) {
;     ...
;       if (gel) wave_store_tile([&](int m, int n, int j) { return gelu_tanh(acc[m][n][j]); }, stg, [&](int r) { return base + (size_t)r * ld; }, noscale);
	v_mul_f32_e32 v3, 0x3f4c422a, v3
	v_add_f32_e32 v3, v3, v3
	v_mul_f32_e32 v3, 0x3fb8aa3b, v3
	v_exp_f32_e32 v3, v3
	s_nop 0
	v_add_f32_e32 v3, 1.0, v3
	v_div_scale_f32 v4, s[6:7], v3, v3, 2.0
	v_rcp_f32_e32 v5, v4
	s_nop 0
	v_fma_f32 v6, -v4, v5, 1.0
	v_fmac_f32_e32 v5, v6, v5
	v_div_scale_f32 v6, vcc, 2.0, v3, 2.0
	v_mul_f32_e32 v7, v6, v5
	v_fma_f32 v8, -v4, v7, v6
	v_fmac_f32_e32 v7, v8, v5
	v_fma_f32 v4, -v4, v7, v6
	v_div_fmas_f32 v4, v4, v5, v7
	v_div_fixup_f32 v3, v4, v3, 2.0
	v_sub_f32_e32 v3, 1.0, v3
	v_mul_f32_e32 v4, 0.5, v165
	v_add_f32_e32 v3, 1.0, v3
	v_fma_mixlo_f16 v3, v4, v3, 0
	ds_write_b16 v2, v3 offset:2688
	v_mul_f32_e32 v3, 0x3d372713, v164
	v_mul_f32_e32 v3, v164, v3
	v_fma_f32 v3, v164, v3, v164
	v_mul_f32_e32 v3, 0x3f4c422a, v3
	v_add_f32_e32 v3, v3, v3
	v_mul_f32_e32 v3, 0x3fb8aa3b, v3
	v_exp_f32_e32 v3, v3
	s_nop 0
	v_add_f32_e32 v3, 1.0, v3
	v_div_scale_f32 v4, s[6:7], v3, v3, 2.0
	v_rcp_f32_e32 v5, v4
	s_nop 0
	v_fma_f32 v6, -v4, v5, 1.0
	v_fmac_f32_e32 v5, v6, v5
	v_div_scale_f32 v6, vcc, 2.0, v3, 2.0
	v_mul_f32_e32 v7, v6, v5
	v_fma_f32 v8, -v4, v7, v6
	v_fmac_f32_e32 v7, v8, v5
	v_fma_f32 v4, -v4, v7, v6
	v_div_fmas_f32 v4, v4, v5, v7
	v_div_fixup_f32 v3, v4, v3, 2.0
	v_sub_f32_e32 v3, 1.0, v3
	v_mul_f32_e32 v4, 0.5, v164
	v_add_f32_e32 v3, 1.0, v3
	v_fma_mixlo_f16 v3, v4, v3, 0
	ds_write_b16 v2, v3 offset:2832
	v_mul_f32_e32 v3, 0x3d372713, v163
	v_mul_f32_e32 v3, v163, v3
	v_fma_f32 v3, v163, v3, v163
	v_mul_f32_e32 v3, 0x3f4c422a, v3
	v_add_f32_e32 v3, v3, v3
	v_mul_f32_e32 v3, 0x3fb8aa3b, v3
	v_exp_f32_e32 v3, v3
	s_nop 0
	v_add_f32_e32 v3, 1.0, v3
	v_div_scale_f32 v4, s[6:7], v3, v3, 2.0
	v_rcp_f32_e32 v5, v4
	s_nop 0
	v_fma_f32 v6, -v4, v5, 1.0
	v_fmac_f32_e32 v5, v6, v5
	v_div_scale_f32 v6, vcc, 2.0, v3, 2.0
	v_mul_f32_e32 v7, v6, v5
	v_fma_f32 v8, -v4, v7, v6
	v_fmac_f32_e32 v7, v8, v5
	v_fma_f32 v4, -v4, v7, v6
	v_div_fmas_f32 v4, v4, v5, v7
	v_div_fixup_f32 v3, v4, v3, 2.0
	v_sub_f32_e32 v3, 1.0, v3
	v_mul_f32_e32 v4, 0.5, v163
	v_add_f32_e32 v3, 1.0, v3
	v_fma_mixlo_f16 v3, v4, v3, 0
	ds_write_b16 v2, v3 offset:4608
	v_mul_f32_e32 v3, 0x3d372713, v162
	v_mul_f32_e32 v3, v162, v3
	v_fma_f32 v3, v162, v3, v162
	v_mul_f32_e32 v3, 0x3f4c422a, v3
	v_add_f32_e32 v3, v3, v3
	v_mul_f32_e32 v3, 0x3fb8aa3b, v3
	v_exp_f32_e32 v3, v3
	s_nop 0
	v_add_f32_e32 v3, 1.0, v3
	v_div_scale_f32 v4, s[6:7], v3, v3, 2.0
	v_rcp_f32_e32 v5, v4
	s_nop 0
	v_fma_f32 v6, -v4, v5, 1.0
	v_fmac_f32_e32 v5, v6, v5
	v_div_scale_f32 v6, vcc, 2.0, v3, 2.0
	v_mul_f32_e32 v7, v6, v5
	v_fma_f32 v8, -v4, v7, v6
	v_fmac_f32_e32 v7, v8, v5
	v_fma_f32 v4, -v4, v7, v6
	v_div_fmas_f32 v4, v4, v5, v7
	v_div_fixup_f32 v3, v4, v3, 2.0
	v_sub_f32_e32 v3, 1.0, v3
	v_mul_f32_e32 v4, 0.5, v162
	v_add_f32_e32 v3, 1.0, v3
	v_fma_mixlo_f16 v3, v4, v3, 0
	ds_write_b16 v2, v3 offset:4752
	v_mul_f32_e32 v3, 0x3d372713, v161
	v_mul_f32_e32 v3, v161, v3
	v_fma_f32 v3, v161, v3, v161
	v_mul_f32_e32 v3, 0x3f4c422a, v3
	v_add_f32_e32 v3, v3, v3
	v_mul_f32_e32 v3, 0x3fb8aa3b, v3
	v_exp_f32_e32 v3, v3
	s_nop 0
	v_add_f32_e32 v3, 1.0, v3
	v_div_scale_f32 v4, s[6:7], v3, v3, 2.0
	v_rcp_f32_e32 v5, v4
	s_nop 0
	v_fma_f32 v6, -v4, v5, 1.0
	v_fmac_f32_e32 v5, v6, v5
	v_div_scale_f32 v6, vcc, 2.0, v3, 2.0
	v_mul_f32_e32 v7, v6, v5
	v_fma_f32 v8, -v4, v7, v6
	v_fmac_f32_e32 v7, v8, v5
	v_fma_f32 v4, -v4, v7, v6
	v_div_fmas_f32 v4, v4, v5, v7
	v_div_fixup_f32 v3, v4, v3, 2.0
	v_sub_f32_e32 v3, 1.0, v3
	v_mul_f32_e32 v4, 0.5, v161
	v_add_f32_e32 v3, 1.0, v3
	v_fma_mixlo_f16 v3, v4, v3, 0
	ds_write_b16 v2, v3 offset:4896
	v_mul_f32_e32 v3, 0x3d372713, v160
	v_mul_f32_e32 v3, v160, v3
	v_fma_f32 v3, v160, v3, v160
	v_mul_f32_e32 v3, 0x3f4c422a, v3
	v_add_f32_e32 v3, v3, v3
	v_mul_f32_e32 v3, 0x3fb8aa3b, v3
	v_exp_f32_e32 v3, v3
	s_nop 0
	v_add_f32_e32 v3, 1.0, v3
	v_div_scale_f32 v4, s[6:7], v3, v3, 2.0
	v_rcp_f32_e32 v5, v4
	s_nop 0
	v_fma_f32 v6, -v4, v5, 1.0
	v_fmac_f32_e32 v5, v6, v5
	v_div_scale_f32 v6, vcc, 2.0, v3, 2.0
	v_mul_f32_e32 v7, v6, v5
	v_fma_f32 v8, -v4, v7, v6
	v_fmac_f32_e32 v7, v8, v5
	v_fma_f32 v4, -v4, v7, v6
	v_div_fmas_f32 v4, v4, v5, v7
	v_div_fixup_f32 v3, v4, v3, 2.0
	v_sub_f32_e32 v3, 1.0, v3
	v_mul_f32_e32 v4, 0.5, v160
	v_add_f32_e32 v3, 1.0, v3
	v_fma_mixlo_f16 v3, v4, v3, 0
	ds_write_b16 v2, v3 offset:5040
	v_mul_f32_e32 v3, 0x3d372713, v159
	v_mul_f32_e32 v3, v159, v3
	v_fma_f32 v3, v159, v3, v159
	v_mul_f32_e32 v3, 0x3f4c422a, v3
	v_add_f32_e32 v3, v3, v3
	v_mul_f32_e32 v3, 0x3fb8aa3b, v3
	v_exp_f32_e32 v3, v3
	s_nop 0
	v_add_f32_e32 v3, 1.0, v3
	v_div_scale_f32 v4, s[6:7], v3, v3, 2.0
	v_rcp_f32_e32 v5, v4
	s_nop 0
	v_fma_f32 v6, -v4, v5, 1.0
	v_fmac_f32_e32 v5, v6, v5
	v_div_scale_f32 v6, vcc, 2.0, v3, 2.0
	v_mul_f32_e32 v7, v6, v5
	v_fma_f32 v8, -v4, v7, v6
	v_fmac_f32_e32 v7, v8, v5
	v_fma_f32 v4, -v4, v7, v6
	v_div_fmas_f32 v4, v4, v5, v7
	v_div_fixup_f32 v3, v4, v3, 2.0
	v_sub_f32_e32 v3, 1.0, v3
	v_mul_f32_e32 v4, 0.5, v159
	v_add_f32_e32 v3, 1.0, v3
	v_fma_mixlo_f16 v3, v4, v3, 0
	ds_write_b16 v2, v3 offset:4640
	v_mul_f32_e32 v3, 0x3d372713, v158
	v_mul_f32_e32 v3, v158, v3
	v_fma_f32 v3, v158, v3, v158
	v_mul_f32_e32 v3, 0x3f4c422a, v3
	v_add_f32_e32 v3, v3, v3
	v_mul_f32_e32 v3, 0x3fb8aa3b, v3
	v_exp_f32_e32 v3, v3
	s_nop 0
	v_add_f32_e32 v3, 1.0, v3
	v_div_scale_f32 v4, s[6:7], v3, v3, 2.0
	v_rcp_f32_e32 v5, v4
	s_nop 0
	v_fma_f32 v6, -v4, v5, 1.0
	v_fmac_f32_e32 v5, v6, v5
	v_div_scale_f32 v6, vcc, 2.0, v3, 2.0
	v_mul_f32_e32 v7, v6, v5
	v_fma_f32 v8, -v4, v7, v6
	v_fmac_f32_e32 v7, v8, v5
	v_fma_f32 v4, -v4, v7, v6
	v_div_fmas_f32 v4, v4, v5, v7
	v_div_fixup_f32 v3, v4, v3, 2.0
	v_sub_f32_e32 v3, 1.0, v3
; DI float gelu_tanh(float x) {
;   float u = 0.7978845608028654f * (x + 0.044715f * x * x * x);
;   float e = __expf(2.f * u);
;   float t = 1.f - 2.f / (e + 1.f);
;   return 0.5f * x * (1.f + t);
; }
; DI void gemm_in_phase(const Params& P, int l, char* smem) {
;     ...
;       if (gel) wave_store_tile([&](int m, int n, int j) { return gelu_tanh(acc[m][n][j]); }, stg, [&](int r) { return base + (size_t)r * ld; }, noscale);
	v_mul_f32_e32 v4, 0.5, v158
	v_add_f32_e32 v3, 1.0, v3
	v_fma_mixlo_f16 v3, v4, v3, 0
	ds_write_b16 v2, v3 offset:4784
	v_mul_f32_e32 v3, 0x3d372713, v157
	v_mul_f32_e32 v3, v157, v3
	v_fma_f32 v3, v157, v3, v157
	v_mul_f32_e32 v3, 0x3f4c422a, v3
	v_add_f32_e32 v3, v3, v3
	v_mul_f32_e32 v3, 0x3fb8aa3b, v3
	v_exp_f32_e32 v3, v3
	s_nop 0
	v_add_f32_e32 v3, 1.0, v3
	v_div_scale_f32 v4, s[6:7], v3, v3, 2.0
	v_rcp_f32_e32 v5, v4
	s_nop 0
	v_fma_f32 v6, -v4, v5, 1.0
	v_fmac_f32_e32 v5, v6, v5
	v_div_scale_f32 v6, vcc, 2.0, v3, 2.0
	v_mul_f32_e32 v7, v6, v5
	v_fma_f32 v8, -v4, v7, v6
	v_fmac_f32_e32 v7, v8, v5
	v_fma_f32 v4, -v4, v7, v6
	v_div_fmas_f32 v4, v4, v5, v7
	v_div_fixup_f32 v3, v4, v3, 2.0
	v_sub_f32_e32 v3, 1.0, v3
	v_mul_f32_e32 v4, 0.5, v157
	v_add_f32_e32 v3, 1.0, v3
	v_fma_mixlo_f16 v3, v4, v3, 0
	ds_write_b16 v2, v3 offset:4928
	v_mul_f32_e32 v3, 0x3d372713, v156
	v_mul_f32_e32 v3, v156, v3
	v_fma_f32 v3, v156, v3, v156
	v_mul_f32_e32 v3, 0x3f4c422a, v3
	v_add_f32_e32 v3, v3, v3
	v_mul_f32_e32 v3, 0x3fb8aa3b, v3
	v_exp_f32_e32 v3, v3
	s_nop 0
	v_add_f32_e32 v3, 1.0, v3
	v_div_scale_f32 v4, s[6:7], v3, v3, 2.0
	v_rcp_f32_e32 v5, v4
	s_nop 0
	v_fma_f32 v6, -v4, v5, 1.0
	v_fmac_f32_e32 v5, v6, v5
	v_div_scale_f32 v6, vcc, 2.0, v3, 2.0
	v_mul_f32_e32 v7, v6, v5
	v_fma_f32 v8, -v4, v7, v6
	v_fmac_f32_e32 v7, v8, v5
	v_fma_f32 v4, -v4, v7, v6
	v_div_fmas_f32 v4, v4, v5, v7
	v_div_fixup_f32 v3, v4, v3, 2.0
	v_sub_f32_e32 v3, 1.0, v3
	v_mul_f32_e32 v4, 0.5, v156
	v_add_f32_e32 v3, 1.0, v3
	v_fma_mixlo_f16 v3, v4, v3, 0
	ds_write_b16 v2, v3 offset:5072
	v_mul_f32_e32 v3, 0x3d372713, v155
	v_mul_f32_e32 v3, v155, v3
	v_fma_f32 v3, v155, v3, v155
	v_mul_f32_e32 v3, 0x3f4c422a, v3
	v_add_f32_e32 v3, v3, v3
	v_mul_f32_e32 v3, 0x3fb8aa3b, v3
	v_exp_f32_e32 v3, v3
	s_nop 0
	v_add_f32_e32 v3, 1.0, v3
	v_div_scale_f32 v4, s[6:7], v3, v3, 2.0
	v_rcp_f32_e32 v5, v4
	s_nop 0
	v_fma_f32 v6, -v4, v5, 1.0
	v_fmac_f32_e32 v5, v6, v5
	v_div_scale_f32 v6, vcc, 2.0, v3, 2.0
	v_mul_f32_e32 v7, v6, v5
	v_fma_f32 v8, -v4, v7, v6
	v_fmac_f32_e32 v7, v8, v5
	v_fma_f32 v4, -v4, v7, v6
	v_div_fmas_f32 v4, v4, v5, v7
	v_div_fixup_f32 v3, v4, v3, 2.0
	v_sub_f32_e32 v3, 1.0, v3
	v_mul_f32_e32 v4, 0.5, v155
	v_add_f32_e32 v3, 1.0, v3
	v_fma_mixlo_f16 v3, v4, v3, 0
	ds_write_b16 v2, v3 offset:4672
	v_mul_f32_e32 v3, 0x3d372713, v154
	v_mul_f32_e32 v3, v154, v3
	v_fma_f32 v3, v154, v3, v154
	v_mul_f32_e32 v3, 0x3f4c422a, v3
	v_add_f32_e32 v3, v3, v3
	v_mul_f32_e32 v3, 0x3fb8aa3b, v3
	v_exp_f32_e32 v3, v3
	s_nop 0
	v_add_f32_e32 v3, 1.0, v3
	v_div_scale_f32 v4, s[6:7], v3, v3, 2.0
	v_rcp_f32_e32 v5, v4
	s_nop 0
	v_fma_f32 v6, -v4, v5, 1.0
	v_fmac_f32_e32 v5, v6, v5
	v_div_scale_f32 v6, vcc, 2.0, v3, 2.0
	v_mul_f32_e32 v7, v6, v5
	v_fma_f32 v8, -v4, v7, v6
	v_fmac_f32_e32 v7, v8, v5
	v_fma_f32 v4, -v4, v7, v6
	v_div_fmas_f32 v4, v4, v5, v7
	v_div_fixup_f32 v3, v4, v3, 2.0
	v_sub_f32_e32 v3, 1.0, v3
	v_mul_f32_e32 v4, 0.5, v154
	v_add_f32_e32 v3, 1.0, v3
	v_fma_mixlo_f16 v3, v4, v3, 0
	ds_write_b16 v2, v3 offset:4816
	v_mul_f32_e32 v3, 0x3d372713, v153
	v_mul_f32_e32 v3, v153, v3
	v_fma_f32 v3, v153, v3, v153
	v_mul_f32_e32 v3, 0x3f4c422a, v3
	v_add_f32_e32 v3, v3, v3
	v_mul_f32_e32 v3, 0x3fb8aa3b, v3
	v_exp_f32_e32 v3, v3
	s_nop 0
	v_add_f32_e32 v3, 1.0, v3
	v_div_scale_f32 v4, s[6:7], v3, v3, 2.0
	v_rcp_f32_e32 v5, v4
	s_nop 0
	v_fma_f32 v6, -v4, v5, 1.0
	v_fmac_f32_e32 v5, v6, v5
	v_div_scale_f32 v6, vcc, 2.0, v3, 2.0
	v_mul_f32_e32 v7, v6, v5
	v_fma_f32 v8, -v4, v7, v6
	v_fmac_f32_e32 v7, v8, v5
	v_fma_f32 v4, -v4, v7, v6
	v_div_fmas_f32 v4, v4, v5, v7
	v_div_fixup_f32 v3, v4, v3, 2.0
	v_sub_f32_e32 v3, 1.0, v3
	v_mul_f32_e32 v4, 0.5, v153
	v_add_f32_e32 v3, 1.0, v3
	v_fma_mixlo_f16 v3, v4, v3, 0
	ds_write_b16 v2, v3 offset:4960
	v_mul_f32_e32 v3, 0x3d372713, v152
	v_mul_f32_e32 v3, v152, v3
	v_fma_f32 v3, v152, v3, v152
	v_mul_f32_e32 v3, 0x3f4c422a, v3
	v_add_f32_e32 v3, v3, v3
	v_mul_f32_e32 v3, 0x3fb8aa3b, v3
	v_exp_f32_e32 v3, v3
	s_nop 0
	v_add_f32_e32 v3, 1.0, v3
	v_div_scale_f32 v4, s[6:7], v3, v3, 2.0
	v_rcp_f32_e32 v5, v4
	s_nop 0
	v_fma_f32 v6, -v4, v5, 1.0
	v_fmac_f32_e32 v5, v6, v5
	v_div_scale_f32 v6, vcc, 2.0, v3, 2.0
	v_mul_f32_e32 v7, v6, v5
	v_fma_f32 v8, -v4, v7, v6
	v_fmac_f32_e32 v7, v8, v5
	v_fma_f32 v4, -v4, v7, v6
	v_div_fmas_f32 v4, v4, v5, v7
	v_div_fixup_f32 v3, v4, v3, 2.0
	v_sub_f32_e32 v3, 1.0, v3
	v_mul_f32_e32 v4, 0.5, v152
	v_add_f32_e32 v3, 1.0, v3
	v_fma_mixlo_f16 v3, v4, v3, 0
	ds_write_b16 v2, v3 offset:5104
	v_mul_f32_e32 v3, 0x3d372713, v151
	v_mul_f32_e32 v3, v151, v3
	v_fma_f32 v3, v151, v3, v151
	v_mul_f32_e32 v3, 0x3f4c422a, v3
	v_add_f32_e32 v3, v3, v3
	v_mul_f32_e32 v3, 0x3fb8aa3b, v3
	v_exp_f32_e32 v3, v3
	s_nop 0
	v_add_f32_e32 v3, 1.0, v3
	v_div_scale_f32 v4, s[6:7], v3, v3, 2.0
	v_rcp_f32_e32 v5, v4
	s_nop 0
	v_fma_f32 v6, -v4, v5, 1.0
	v_fmac_f32_e32 v5, v6, v5
	v_div_scale_f32 v6, vcc, 2.0, v3, 2.0
	v_mul_f32_e32 v7, v6, v5
	v_fma_f32 v8, -v4, v7, v6
	v_fmac_f32_e32 v7, v8, v5
	v_fma_f32 v4, -v4, v7, v6
	v_div_fmas_f32 v4, v4, v5, v7
	v_div_fixup_f32 v3, v4, v3, 2.0
	v_sub_f32_e32 v3, 1.0, v3
	v_mul_f32_e32 v4, 0.5, v151
	v_add_f32_e32 v3, 1.0, v3
	v_fma_mixlo_f16 v3, v4, v3, 0
	ds_write_b16 v2, v3 offset:4704
	v_mul_f32_e32 v3, 0x3d372713, v150
	v_mul_f32_e32 v3, v150, v3
	v_fma_f32 v3, v150, v3, v150
	v_mul_f32_e32 v3, 0x3f4c422a, v3
	v_add_f32_e32 v3, v3, v3
	v_mul_f32_e32 v3, 0x3fb8aa3b, v3
	v_exp_f32_e32 v3, v3
	s_nop 0
	v_add_f32_e32 v3, 1.0, v3
	v_div_scale_f32 v4, s[6:7], v3, v3, 2.0
	v_rcp_f32_e32 v5, v4
	s_nop 0
	v_fma_f32 v6, -v4, v5, 1.0
	v_fmac_f32_e32 v5, v6, v5
	v_div_scale_f32 v6, vcc, 2.0, v3, 2.0
; DI float gelu_tanh(float x) {
;   float u = 0.7978845608028654f * (x + 0.044715f * x * x * x);
;   float e = __expf(2.f * u);
;   float t = 1.f - 2.f / (e + 1.f);
;   return 0.5f * x * (1.f + t);
; }
; DI void gemm_in_phase(const Params& P, int l, char* smem) {
;     ...
;       if (gel) wave_store_tile([&](int m, int n, int j) { return gelu_tanh(acc[m][n][j]); }, stg, [&](int r) { return base + (size_t)r * ld; }, noscale);
	v_mul_f32_e32 v7, v6, v5
	v_fma_f32 v8, -v4, v7, v6
	v_fmac_f32_e32 v7, v8, v5
	v_fma_f32 v4, -v4, v7, v6
	v_div_fmas_f32 v4, v4, v5, v7
	v_div_fixup_f32 v3, v4, v3, 2.0
	v_sub_f32_e32 v3, 1.0, v3
	v_mul_f32_e32 v4, 0.5, v150
	v_add_f32_e32 v3, 1.0, v3
	v_fma_mixlo_f16 v3, v4, v3, 0
	ds_write_b16 v2, v3 offset:4848
	v_mul_f32_e32 v3, 0x3d372713, v147
	v_mul_f32_e32 v3, v147, v3
	v_fma_f32 v3, v147, v3, v147
	v_mul_f32_e32 v3, 0x3f4c422a, v3
	v_add_f32_e32 v3, v3, v3
	v_mul_f32_e32 v3, 0x3fb8aa3b, v3
	v_exp_f32_e32 v3, v3
	s_nop 0
	v_add_f32_e32 v3, 1.0, v3
	v_div_scale_f32 v4, s[6:7], v3, v3, 2.0
	v_rcp_f32_e32 v5, v4
	s_nop 0
	v_fma_f32 v6, -v4, v5, 1.0
	v_fmac_f32_e32 v5, v6, v5
	v_div_scale_f32 v6, vcc, 2.0, v3, 2.0
	v_mul_f32_e32 v7, v6, v5
	v_fma_f32 v8, -v4, v7, v6
	v_fmac_f32_e32 v7, v8, v5
	v_fma_f32 v4, -v4, v7, v6
	v_div_fmas_f32 v4, v4, v5, v7
	v_div_fixup_f32 v3, v4, v3, 2.0
	v_sub_f32_e32 v3, 1.0, v3
	v_mul_f32_e32 v4, 0.5, v147
	v_add_f32_e32 v3, 1.0, v3
	v_fma_mixlo_f16 v3, v4, v3, 0
	ds_write_b16 v2, v3 offset:4992
	v_mul_f32_e32 v3, 0x3d372713, v146
	v_mul_f32_e32 v3, v146, v3
	v_fma_f32 v3, v146, v3, v146
	v_mul_f32_e32 v3, 0x3f4c422a, v3
	v_add_f32_e32 v3, v3, v3
	v_mul_f32_e32 v3, 0x3fb8aa3b, v3
	v_exp_f32_e32 v3, v3
	s_nop 0
	v_add_f32_e32 v3, 1.0, v3
	v_div_scale_f32 v4, s[6:7], v3, v3, 2.0
	v_rcp_f32_e32 v5, v4
	s_nop 0
	v_fma_f32 v6, -v4, v5, 1.0
	v_fmac_f32_e32 v5, v6, v5
	v_div_scale_f32 v6, vcc, 2.0, v3, 2.0
	v_mul_f32_e32 v7, v6, v5
	v_fma_f32 v8, -v4, v7, v6
	v_fmac_f32_e32 v7, v8, v5
	v_fma_f32 v4, -v4, v7, v6
	v_div_fmas_f32 v4, v4, v5, v7
	v_div_fixup_f32 v3, v4, v3, 2.0
	v_sub_f32_e32 v3, 1.0, v3
	v_mul_f32_e32 v4, 0.5, v146
	v_add_f32_e32 v3, 1.0, v3
	v_fma_mixlo_f16 v3, v4, v3, 0
	ds_write_b16 v2, v3 offset:5136
	v_mul_f32_e32 v3, 0x3d372713, v145
	v_mul_f32_e32 v3, v145, v3
	v_fma_f32 v3, v145, v3, v145
	v_mul_f32_e32 v3, 0x3f4c422a, v3
	v_add_f32_e32 v3, v3, v3
	v_mul_f32_e32 v3, 0x3fb8aa3b, v3
	v_exp_f32_e32 v3, v3
	s_nop 0
	v_add_f32_e32 v3, 1.0, v3
	v_div_scale_f32 v4, s[6:7], v3, v3, 2.0
	v_rcp_f32_e32 v5, v4
	s_nop 0
	v_fma_f32 v6, -v4, v5, 1.0
	v_fmac_f32_e32 v5, v6, v5
	v_div_scale_f32 v6, vcc, 2.0, v3, 2.0
	v_mul_f32_e32 v7, v6, v5
	v_fma_f32 v8, -v4, v7, v6
	v_fmac_f32_e32 v7, v8, v5
	v_fma_f32 v4, -v4, v7, v6
	v_div_fmas_f32 v4, v4, v5, v7
	v_div_fixup_f32 v3, v4, v3, 2.0
	v_sub_f32_e32 v3, 1.0, v3
	v_mul_f32_e32 v4, 0.5, v145
	v_add_f32_e32 v3, 1.0, v3
	v_fma_mixlo_f16 v3, v4, v3, 0
	ds_write_b16 v2, v3 offset:6912
	v_mul_f32_e32 v3, 0x3d372713, v144
	v_mul_f32_e32 v3, v144, v3
	v_fma_f32 v3, v144, v3, v144
	v_mul_f32_e32 v3, 0x3f4c422a, v3
	v_add_f32_e32 v3, v3, v3
	v_mul_f32_e32 v3, 0x3fb8aa3b, v3
	v_exp_f32_e32 v3, v3
	s_nop 0
	v_add_f32_e32 v3, 1.0, v3
	v_div_scale_f32 v4, s[6:7], v3, v3, 2.0
	v_rcp_f32_e32 v5, v4
	s_nop 0
	v_fma_f32 v6, -v4, v5, 1.0
	v_fmac_f32_e32 v5, v6, v5
	v_div_scale_f32 v6, vcc, 2.0, v3, 2.0
	v_mul_f32_e32 v7, v6, v5
	v_fma_f32 v8, -v4, v7, v6
	v_fmac_f32_e32 v7, v8, v5
	v_fma_f32 v4, -v4, v7, v6
	v_div_fmas_f32 v4, v4, v5, v7
	v_div_fixup_f32 v3, v4, v3, 2.0
	v_sub_f32_e32 v3, 1.0, v3
	v_mul_f32_e32 v4, 0.5, v144
	v_add_f32_e32 v3, 1.0, v3
	v_fma_mixlo_f16 v3, v4, v3, 0
	ds_write_b16 v2, v3 offset:7056
	v_mul_f32_e32 v3, 0x3d372713, v143
	v_mul_f32_e32 v3, v143, v3
	v_fma_f32 v3, v143, v3, v143
	v_mul_f32_e32 v3, 0x3f4c422a, v3
	v_add_f32_e32 v3, v3, v3
	v_mul_f32_e32 v3, 0x3fb8aa3b, v3
	v_exp_f32_e32 v3, v3
	s_nop 0
	v_add_f32_e32 v3, 1.0, v3
	v_div_scale_f32 v4, s[6:7], v3, v3, 2.0
	v_rcp_f32_e32 v5, v4
	s_nop 0
	v_fma_f32 v6, -v4, v5, 1.0
	v_fmac_f32_e32 v5, v6, v5
	v_div_scale_f32 v6, vcc, 2.0, v3, 2.0
	v_mul_f32_e32 v7, v6, v5
	v_fma_f32 v8, -v4, v7, v6
	v_fmac_f32_e32 v7, v8, v5
	v_fma_f32 v4, -v4, v7, v6
	v_div_fmas_f32 v4, v4, v5, v7
	v_div_fixup_f32 v3, v4, v3, 2.0
	v_sub_f32_e32 v3, 1.0, v3
	v_mul_f32_e32 v4, 0.5, v143
	v_add_f32_e32 v3, 1.0, v3
	v_fma_mixlo_f16 v3, v4, v3, 0
	ds_write_b16 v2, v3 offset:7200
	v_mul_f32_e32 v3, 0x3d372713, v142
	v_mul_f32_e32 v3, v142, v3
	v_fma_f32 v3, v142, v3, v142
	v_mul_f32_e32 v3, 0x3f4c422a, v3
	v_add_f32_e32 v3, v3, v3
	v_mul_f32_e32 v3, 0x3fb8aa3b, v3
	v_exp_f32_e32 v3, v3
	s_nop 0
	v_add_f32_e32 v3, 1.0, v3
	v_div_scale_f32 v4, s[6:7], v3, v3, 2.0
	v_rcp_f32_e32 v5, v4
	s_nop 0
	v_fma_f32 v6, -v4, v5, 1.0
	v_fmac_f32_e32 v5, v6, v5
	v_div_scale_f32 v6, vcc, 2.0, v3, 2.0
	v_mul_f32_e32 v7, v6, v5
	v_fma_f32 v8, -v4, v7, v6
	v_fmac_f32_e32 v7, v8, v5
	v_fma_f32 v4, -v4, v7, v6
	v_div_fmas_f32 v4, v4, v5, v7
	v_div_fixup_f32 v3, v4, v3, 2.0
	v_sub_f32_e32 v3, 1.0, v3
	v_mul_f32_e32 v4, 0.5, v142
	v_add_f32_e32 v3, 1.0, v3
	v_fma_mixlo_f16 v3, v4, v3, 0
	ds_write_b16 v2, v3 offset:7344
	v_mul_f32_e32 v3, 0x3d372713, v141
	v_mul_f32_e32 v3, v141, v3
	v_fma_f32 v3, v141, v3, v141
	v_mul_f32_e32 v3, 0x3f4c422a, v3
	v_add_f32_e32 v3, v3, v3
	v_mul_f32_e32 v3, 0x3fb8aa3b, v3
	v_exp_f32_e32 v3, v3
	s_nop 0
	v_add_f32_e32 v3, 1.0, v3
	v_div_scale_f32 v4, s[6:7], v3, v3, 2.0
	v_rcp_f32_e32 v5, v4
	s_nop 0
	v_fma_f32 v6, -v4, v5, 1.0
	v_fmac_f32_e32 v5, v6, v5
	v_div_scale_f32 v6, vcc, 2.0, v3, 2.0
	v_mul_f32_e32 v7, v6, v5
	v_fma_f32 v8, -v4, v7, v6
	v_fmac_f32_e32 v7, v8, v5
	v_fma_f32 v4, -v4, v7, v6
	v_div_fmas_f32 v4, v4, v5, v7
	v_div_fixup_f32 v3, v4, v3, 2.0
	v_sub_f32_e32 v3, 1.0, v3
	v_mul_f32_e32 v4, 0.5, v141
	v_add_f32_e32 v3, 1.0, v3
	v_fma_mixlo_f16 v3, v4, v3, 0
	ds_write_b16 v2, v3 offset:6944
	v_mul_f32_e32 v3, 0x3d372713, v140
	v_mul_f32_e32 v3, v140, v3
	v_fma_f32 v3, v140, v3, v140
	v_mul_f32_e32 v3, 0x3f4c422a, v3
	v_add_f32_e32 v3, v3, v3
	v_mul_f32_e32 v3, 0x3fb8aa3b, v3
	v_exp_f32_e32 v3, v3
; DI float gelu_tanh(float x) {
;   float u = 0.7978845608028654f * (x + 0.044715f * x * x * x);
;   float e = __expf(2.f * u);
;   float t = 1.f - 2.f / (e + 1.f);
;   return 0.5f * x * (1.f + t);
; }
; DI void gemm_in_phase(const Params& P, int l, char* smem) {
;     ...
;       if (gel) wave_store_tile([&](int m, int n, int j) { return gelu_tanh(acc[m][n][j]); }, stg, [&](int r) { return base + (size_t)r * ld; }, noscale);
	s_nop 0
	v_add_f32_e32 v3, 1.0, v3
	v_div_scale_f32 v4, s[6:7], v3, v3, 2.0
	v_rcp_f32_e32 v5, v4
	s_nop 0
	v_fma_f32 v6, -v4, v5, 1.0
	v_fmac_f32_e32 v5, v6, v5
	v_div_scale_f32 v6, vcc, 2.0, v3, 2.0
	v_mul_f32_e32 v7, v6, v5
	v_fma_f32 v8, -v4, v7, v6
	v_fmac_f32_e32 v7, v8, v5
	v_fma_f32 v4, -v4, v7, v6
	v_div_fmas_f32 v4, v4, v5, v7
	v_div_fixup_f32 v3, v4, v3, 2.0
	v_sub_f32_e32 v3, 1.0, v3
	v_mul_f32_e32 v4, 0.5, v140
	v_add_f32_e32 v3, 1.0, v3
	v_fma_mixlo_f16 v3, v4, v3, 0
	ds_write_b16 v2, v3 offset:7088
	v_mul_f32_e32 v3, 0x3d372713, v138
	v_mul_f32_e32 v3, v138, v3
	v_fma_f32 v3, v138, v3, v138
	v_mul_f32_e32 v3, 0x3f4c422a, v3
	v_add_f32_e32 v3, v3, v3
	v_mul_f32_e32 v3, 0x3fb8aa3b, v3
	v_exp_f32_e32 v3, v3
	s_nop 0
	v_add_f32_e32 v3, 1.0, v3
	v_div_scale_f32 v4, s[6:7], v3, v3, 2.0
	v_rcp_f32_e32 v5, v4
	s_nop 0
	v_fma_f32 v6, -v4, v5, 1.0
	v_fmac_f32_e32 v5, v6, v5
	v_div_scale_f32 v6, vcc, 2.0, v3, 2.0
	v_mul_f32_e32 v7, v6, v5
	v_fma_f32 v8, -v4, v7, v6
	v_fmac_f32_e32 v7, v8, v5
	v_fma_f32 v4, -v4, v7, v6
	v_div_fmas_f32 v4, v4, v5, v7
	v_div_fixup_f32 v3, v4, v3, 2.0
	v_sub_f32_e32 v3, 1.0, v3
	v_mul_f32_e32 v4, 0.5, v138
	v_add_f32_e32 v3, 1.0, v3
	v_fma_mixlo_f16 v3, v4, v3, 0
	ds_write_b16 v2, v3 offset:7232
	v_mul_f32_e32 v3, 0x3d372713, v137
	v_mul_f32_e32 v3, v137, v3
	v_fma_f32 v3, v137, v3, v137
	v_mul_f32_e32 v3, 0x3f4c422a, v3
	v_add_f32_e32 v3, v3, v3
	v_mul_f32_e32 v3, 0x3fb8aa3b, v3
	v_exp_f32_e32 v3, v3
	s_nop 0
	v_add_f32_e32 v3, 1.0, v3
	v_div_scale_f32 v4, s[6:7], v3, v3, 2.0
	v_rcp_f32_e32 v5, v4
	s_nop 0
	v_fma_f32 v6, -v4, v5, 1.0
	v_fmac_f32_e32 v5, v6, v5
	v_div_scale_f32 v6, vcc, 2.0, v3, 2.0
	v_mul_f32_e32 v7, v6, v5
	v_fma_f32 v8, -v4, v7, v6
	v_fmac_f32_e32 v7, v8, v5
	v_fma_f32 v4, -v4, v7, v6
	v_div_fmas_f32 v4, v4, v5, v7
	v_div_fixup_f32 v3, v4, v3, 2.0
	v_sub_f32_e32 v3, 1.0, v3
	v_mul_f32_e32 v4, 0.5, v137
	v_add_f32_e32 v3, 1.0, v3
	v_fma_mixlo_f16 v3, v4, v3, 0
	ds_write_b16 v2, v3 offset:7376
	v_mul_f32_e32 v3, 0x3d372713, v136
	v_mul_f32_e32 v3, v136, v3
	v_fma_f32 v3, v136, v3, v136
	v_mul_f32_e32 v3, 0x3f4c422a, v3
	v_add_f32_e32 v3, v3, v3
	v_mul_f32_e32 v3, 0x3fb8aa3b, v3
	v_exp_f32_e32 v3, v3
	s_nop 0
	v_add_f32_e32 v3, 1.0, v3
	v_div_scale_f32 v4, s[6:7], v3, v3, 2.0
	v_rcp_f32_e32 v5, v4
	s_nop 0
	v_fma_f32 v6, -v4, v5, 1.0
	v_fmac_f32_e32 v5, v6, v5
	v_div_scale_f32 v6, vcc, 2.0, v3, 2.0
	v_mul_f32_e32 v7, v6, v5
	v_fma_f32 v8, -v4, v7, v6
	v_fmac_f32_e32 v7, v8, v5
	v_fma_f32 v4, -v4, v7, v6
	v_div_fmas_f32 v4, v4, v5, v7
	v_div_fixup_f32 v3, v4, v3, 2.0
	v_sub_f32_e32 v3, 1.0, v3
	v_mul_f32_e32 v4, 0.5, v136
	v_add_f32_e32 v3, 1.0, v3
	v_fma_mixlo_f16 v3, v4, v3, 0
	ds_write_b16 v2, v3 offset:6976
	v_mul_f32_e32 v3, 0x3d372713, v135
	v_mul_f32_e32 v3, v135, v3
	v_fma_f32 v3, v135, v3, v135
	v_mul_f32_e32 v3, 0x3f4c422a, v3
	v_add_f32_e32 v3, v3, v3
	v_mul_f32_e32 v3, 0x3fb8aa3b, v3
	v_exp_f32_e32 v3, v3
	s_nop 0
	v_add_f32_e32 v3, 1.0, v3
	v_div_scale_f32 v4, s[6:7], v3, v3, 2.0
	v_rcp_f32_e32 v5, v4
	s_nop 0
	v_fma_f32 v6, -v4, v5, 1.0
	v_fmac_f32_e32 v5, v6, v5
	v_div_scale_f32 v6, vcc, 2.0, v3, 2.0
	v_mul_f32_e32 v7, v6, v5
	v_fma_f32 v8, -v4, v7, v6
	v_fmac_f32_e32 v7, v8, v5
	v_fma_f32 v4, -v4, v7, v6
	v_div_fmas_f32 v4, v4, v5, v7
	v_div_fixup_f32 v3, v4, v3, 2.0
	v_sub_f32_e32 v3, 1.0, v3
	v_mul_f32_e32 v4, 0.5, v135
	v_add_f32_e32 v3, 1.0, v3
	v_fma_mixlo_f16 v3, v4, v3, 0
	ds_write_b16 v2, v3 offset:7120
	v_mul_f32_e32 v3, 0x3d372713, v134
	v_mul_f32_e32 v3, v134, v3
	v_fma_f32 v3, v134, v3, v134
	v_mul_f32_e32 v3, 0x3f4c422a, v3
	v_add_f32_e32 v3, v3, v3
	v_mul_f32_e32 v3, 0x3fb8aa3b, v3
	v_exp_f32_e32 v3, v3
	s_nop 0
	v_add_f32_e32 v3, 1.0, v3
	v_div_scale_f32 v4, s[6:7], v3, v3, 2.0
	v_rcp_f32_e32 v5, v4
	s_nop 0
	v_fma_f32 v6, -v4, v5, 1.0
	v_fmac_f32_e32 v5, v6, v5
	v_div_scale_f32 v6, vcc, 2.0, v3, 2.0
	v_mul_f32_e32 v7, v6, v5
	v_fma_f32 v8, -v4, v7, v6
	v_fmac_f32_e32 v7, v8, v5
	v_fma_f32 v4, -v4, v7, v6
	v_div_fmas_f32 v4, v4, v5, v7
	v_div_fixup_f32 v3, v4, v3, 2.0
	v_sub_f32_e32 v3, 1.0, v3
	v_mul_f32_e32 v4, 0.5, v134
	v_add_f32_e32 v3, 1.0, v3
	v_fma_mixlo_f16 v3, v4, v3, 0
	ds_write_b16 v2, v3 offset:7264
	v_mul_f32_e32 v3, 0x3d372713, v133
	v_mul_f32_e32 v3, v133, v3
	v_fma_f32 v3, v133, v3, v133
	v_mul_f32_e32 v3, 0x3f4c422a, v3
	v_add_f32_e32 v3, v3, v3
	v_mul_f32_e32 v3, 0x3fb8aa3b, v3
	v_exp_f32_e32 v3, v3
	s_nop 0
	v_add_f32_e32 v3, 1.0, v3
	v_div_scale_f32 v4, s[6:7], v3, v3, 2.0
	v_rcp_f32_e32 v5, v4
	s_nop 0
	v_fma_f32 v6, -v4, v5, 1.0
	v_fmac_f32_e32 v5, v6, v5
	v_div_scale_f32 v6, vcc, 2.0, v3, 2.0
	v_mul_f32_e32 v7, v6, v5
	v_fma_f32 v8, -v4, v7, v6
	v_fmac_f32_e32 v7, v8, v5
	v_fma_f32 v4, -v4, v7, v6
	v_div_fmas_f32 v4, v4, v5, v7
	v_div_fixup_f32 v3, v4, v3, 2.0
	v_sub_f32_e32 v3, 1.0, v3
	v_mul_f32_e32 v4, 0.5, v133
	v_add_f32_e32 v3, 1.0, v3
	v_fma_mixlo_f16 v3, v4, v3, 0
	ds_write_b16 v2, v3 offset:7408
	v_mul_f32_e32 v3, 0x3d372713, v132
	v_mul_f32_e32 v3, v132, v3
	v_fma_f32 v3, v132, v3, v132
	v_mul_f32_e32 v3, 0x3f4c422a, v3
	v_add_f32_e32 v3, v3, v3
	v_mul_f32_e32 v3, 0x3fb8aa3b, v3
	v_exp_f32_e32 v3, v3
	s_nop 0
	v_add_f32_e32 v3, 1.0, v3
	v_div_scale_f32 v4, s[6:7], v3, v3, 2.0
; #define TIDX tid_opaque()
; DI float gelu_tanh(float x) {
;   float u = 0.7978845608028654f * (x + 0.044715f * x * x * x);
;   float e = __expf(2.f * u);
;   float t = 1.f - 2.f / (e + 1.f);
;   return 0.5f * x * (1.f + t);
; }
; template <class RP, class SC>
; DI void stage_flush(char* stg, int h, RP rowptr, SC rowscale) {
;   const int lane = TIDX & 63;
;   __builtin_amdgcn_wave_barrier();
; #pragma unroll
;   for (int i = 0; i < 8; i++) {
;     const int c = i * 64 + lane, row = c >> 3, c16 = c & 7;
;     h8 v = *(const h8*)(stg + row * 144 + c16 * 16);
;     half_t* d = rowptr(h * 64 + row);
;     if (d) { rowscale(h * 64 + row, v); *(h8*)(d + c16 * 8) = v; }
;   }
;   __builtin_amdgcn_wave_barrier();
; }
	v_rcp_f32_e32 v5, v4
	s_nop 0
	v_fma_f32 v6, -v4, v5, 1.0
	v_fmac_f32_e32 v5, v6, v5
	v_div_scale_f32 v6, vcc, 2.0, v3, 2.0
	v_mul_f32_e32 v7, v6, v5
	v_fma_f32 v8, -v4, v7, v6
	v_fmac_f32_e32 v7, v8, v5
	v_fma_f32 v4, -v4, v7, v6
	v_div_fmas_f32 v4, v4, v5, v7
	v_div_fixup_f32 v3, v4, v3, 2.0
	v_sub_f32_e32 v3, 1.0, v3
	v_mul_f32_e32 v4, 0.5, v132
	v_add_f32_e32 v3, 1.0, v3
	v_fma_mixlo_f16 v3, v4, v3, 0
	ds_write_b16 v2, v3 offset:7008
	v_mul_f32_e32 v3, 0x3d372713, v131
	v_mul_f32_e32 v3, v131, v3
	v_fma_f32 v3, v131, v3, v131
	v_mul_f32_e32 v3, 0x3f4c422a, v3
	v_add_f32_e32 v3, v3, v3
	v_mul_f32_e32 v3, 0x3fb8aa3b, v3
	v_exp_f32_e32 v3, v3
	s_nop 0
	v_add_f32_e32 v3, 1.0, v3
	v_div_scale_f32 v4, s[6:7], v3, v3, 2.0
	v_rcp_f32_e32 v5, v4
	s_nop 0
	v_fma_f32 v6, -v4, v5, 1.0
	v_fmac_f32_e32 v5, v6, v5
	v_div_scale_f32 v6, vcc, 2.0, v3, 2.0
	v_mul_f32_e32 v7, v6, v5
	v_fma_f32 v8, -v4, v7, v6
	v_fmac_f32_e32 v7, v8, v5
	v_fma_f32 v4, -v4, v7, v6
	v_div_fmas_f32 v4, v4, v5, v7
	v_div_fixup_f32 v3, v4, v3, 2.0
	v_sub_f32_e32 v3, 1.0, v3
	v_mul_f32_e32 v4, 0.5, v131
	v_add_f32_e32 v3, 1.0, v3
	v_fma_mixlo_f16 v3, v4, v3, 0
	ds_write_b16 v2, v3 offset:7152
	v_mul_f32_e32 v3, 0x3d372713, v130
	v_mul_f32_e32 v3, v130, v3
	v_fma_f32 v3, v130, v3, v130
	v_mul_f32_e32 v3, 0x3f4c422a, v3
	v_add_f32_e32 v3, v3, v3
	v_mul_f32_e32 v3, 0x3fb8aa3b, v3
	v_exp_f32_e32 v3, v3
	s_nop 0
	v_add_f32_e32 v3, 1.0, v3
	v_div_scale_f32 v4, s[6:7], v3, v3, 2.0
	v_rcp_f32_e32 v5, v4
	s_nop 0
	v_fma_f32 v6, -v4, v5, 1.0
	v_fmac_f32_e32 v5, v6, v5
	v_div_scale_f32 v6, vcc, 2.0, v3, 2.0
	v_mul_f32_e32 v7, v6, v5
	v_fma_f32 v8, -v4, v7, v6
	v_fmac_f32_e32 v7, v8, v5
	v_fma_f32 v4, -v4, v7, v6
	v_div_fmas_f32 v4, v4, v5, v7
	v_div_fixup_f32 v3, v4, v3, 2.0
	v_sub_f32_e32 v3, 1.0, v3
	v_mul_f32_e32 v4, 0.5, v130
	v_add_f32_e32 v3, 1.0, v3
	v_fma_mixlo_f16 v3, v4, v3, 0
	ds_write_b16 v2, v3 offset:7296
	v_mul_f32_e32 v3, 0x3d372713, v129
	v_mul_f32_e32 v3, v129, v3
	v_fma_f32 v3, v129, v3, v129
	v_mul_f32_e32 v3, 0x3f4c422a, v3
	v_add_f32_e32 v3, v3, v3
	v_mul_f32_e32 v3, 0x3fb8aa3b, v3
	v_exp_f32_e32 v3, v3
	s_nop 0
	v_add_f32_e32 v3, 1.0, v3
	v_div_scale_f32 v4, s[6:7], v3, v3, 2.0
	v_rcp_f32_e32 v5, v4
	s_nop 0
	v_fma_f32 v6, -v4, v5, 1.0
	v_fmac_f32_e32 v5, v6, v5
	v_div_scale_f32 v6, vcc, 2.0, v3, 2.0
	v_mul_f32_e32 v7, v6, v5
	v_fma_f32 v8, -v4, v7, v6
	v_fmac_f32_e32 v7, v8, v5
	v_fma_f32 v4, -v4, v7, v6
	v_div_fmas_f32 v4, v4, v5, v7
	v_div_fixup_f32 v3, v4, v3, 2.0
	v_sub_f32_e32 v3, 1.0, v3
	v_mul_f32_e32 v4, 0.5, v129
	v_add_f32_e32 v3, 1.0, v3
	v_fma_mixlo_f16 v3, v4, v3, 0
	ds_write_b16 v2, v3 offset:7440
	v_mov_b32_e32 v2, v172
	v_mov_b32_e32 v7, v149
	v_bfe_u32 v10, v2, 3, 3
	v_lshlrev_b32_e32 v3, 4, v2
	v_or_b32_e32 v2, 64, v10
	v_mul_u32_u24_e32 v2, s2, v2
	v_lshlrev_b32_e32 v148, 1, v2
	v_and_b32_e32 v6, 0x70, v3
	v_lshl_add_u64 v[2:3], v[0:1], 0, v[148:149]
	v_lshl_add_u64 v[8:9], v[2:3], 0, v[6:7]
	v_mul_u32_u24_e32 v2, 0x90, v10
	v_add3_u32 v11, v18, v6, v2
	ds_read_b128 v[2:5], v11
	s_waitcnt lgkmcnt(0)
	global_store_dwordx4 v[8:9], v[2:5], off nt
	s_nop 1
	v_or_b32_e32 v2, 0x48, v10
	v_mul_u32_u24_e32 v2, s2, v2
	v_lshlrev_b32_e32 v148, 1, v2
	v_lshl_add_u64 v[2:3], v[0:1], 0, v[148:149]
	v_lshl_add_u64 v[8:9], v[2:3], 0, v[6:7]
	ds_read_b128 v[2:5], v11 offset:1152
	s_waitcnt lgkmcnt(0)
	global_store_dwordx4 v[8:9], v[2:5], off nt
	s_nop 1
	v_or_b32_e32 v2, 0x50, v10
	v_mul_u32_u24_e32 v2, s2, v2
	v_lshlrev_b32_e32 v148, 1, v2
	v_lshl_add_u64 v[2:3], v[0:1], 0, v[148:149]
	v_lshl_add_u64 v[8:9], v[2:3], 0, v[6:7]
	ds_read_b128 v[2:5], v11 offset:2304
	s_waitcnt lgkmcnt(0)
	global_store_dwordx4 v[8:9], v[2:5], off nt
	s_nop 1
	v_or_b32_e32 v2, 0x58, v10
	v_mul_u32_u24_e32 v2, s2, v2
	v_lshlrev_b32_e32 v148, 1, v2
	v_lshl_add_u64 v[2:3], v[0:1], 0, v[148:149]
	v_lshl_add_u64 v[8:9], v[2:3], 0, v[6:7]
	ds_read_b128 v[2:5], v11 offset:3456
	s_waitcnt lgkmcnt(0)
	global_store_dwordx4 v[8:9], v[2:5], off nt
	s_nop 1
	v_or_b32_e32 v2, 0x60, v10
	v_mul_u32_u24_e32 v2, s2, v2
	v_lshlrev_b32_e32 v148, 1, v2
	v_lshl_add_u64 v[2:3], v[0:1], 0, v[148:149]
	v_lshl_add_u64 v[8:9], v[2:3], 0, v[6:7]
	ds_read_b128 v[2:5], v11 offset:4608
	s_waitcnt lgkmcnt(0)
	global_store_dwordx4 v[8:9], v[2:5], off nt
	s_nop 1
	v_or_b32_e32 v2, 0x68, v10
	v_mul_u32_u24_e32 v2, s2, v2
	v_lshlrev_b32_e32 v148, 1, v2
	v_lshl_add_u64 v[2:3], v[0:1], 0, v[148:149]
	v_lshl_add_u64 v[8:9], v[2:3], 0, v[6:7]
	ds_read_b128 v[2:5], v11 offset:5760
	s_waitcnt lgkmcnt(0)
	global_store_dwordx4 v[8:9], v[2:5], off nt
	s_nop 1
	v_or_b32_e32 v2, 0x70, v10
	v_mul_u32_u24_e32 v2, s2, v2
	v_lshlrev_b32_e32 v148, 1, v2
	v_lshl_add_u64 v[2:3], v[0:1], 0, v[148:149]
	v_lshl_add_u64 v[8:9], v[2:3], 0, v[6:7]
	ds_read_b128 v[2:5], v11 offset:6912
	s_waitcnt lgkmcnt(0)
	global_store_dwordx4 v[8:9], v[2:5], off nt
	s_nop 1
	v_or_b32_e32 v2, 0x78, v10
	v_mul_u32_u24_e32 v2, s2, v2
	v_lshlrev_b32_e32 v148, 1, v2
	v_lshl_add_u64 v[0:1], v[0:1], 0, v[148:149]
	v_lshl_add_u64 v[4:5], v[0:1], 0, v[6:7]
	ds_read_b128 v[0:3], v11 offset:8064
	s_waitcnt lgkmcnt(0)
	global_store_dwordx4 v[4:5], v[0:3], off nt
	s_branch .LBB0_224

; #define TIDX tid_opaque()
; DI float sigmoidf_(float x) { return 1.f / (1.f + __expf(-x)); }
; DI void moe_e1_phase(const Params& P, int l, char* smem, int* tb) {
;     ...
;     {
;       const int tid2 = TIDX, lane2 = tid2 & 63, wave2 = tid2 >> 6, fr2 = lane2 & 15, fq2 = lane2 >> 4, wr2 = wave2 >> 1, wc2 = wave2 & 1;
;       char* stg = smem + 98304 + wave2 * 12288;
;       half_t* Hd = P.H + ((size_t)rt * 256 + wr2 * 128) * 512 + nt * 64 + wc2 * 32;
; #pragma unroll
;       for (int h = 0; h < 2; h++) {
; #pragma unroll
;         for (int ml = 0; ml < 4; ml++)
; #pragma unroll
;           for (int n = 0; n < 2; n++)
; #pragma unroll
;             for (int j = 0; j < 4; j++) {
;               float a1 = acc[h * 4 + ml][n][j], a3 = acc[h * 4 + ml][n + 2][j];
;               *(half_t*)(stg + (ml * 16 + fq2 * 4 + j) * 80 + (n * 16 + fr2) * 2) = (half_t)(a1 * sigmoidf_(a1) * a3);
;             }
.LBB0_568:
	v_mov_b32_e32 v8, v172
	s_movk_i32 s2, 0x3000
	v_lshrrev_b32_e32 v2, 6, v8
	v_mul_lo_u32 v2, v2, s2
	s_ashr_i32 s5, s4, 31
	v_mul_f32_e32 v39, 0xbfb8aa3b, v194
	v_add_u32_e32 v33, 0x18000, v2
	v_and_b32_e32 v2, 0xffffff80, v8
	s_lshl_b64 s[2:3], s[4:5], 18
	v_readlane_b32 s4, v255, 62
	v_exp_f32_e32 v39, v39
	v_ashrrev_i32_e32 v3, 31, v2
	v_readlane_b32 s5, v255, 63
	s_add_u32 s2, s4, s2
	s_addc_u32 s3, s5, s3
	v_lshlrev_b64 v[2:3], 10, v[2:3]
	v_lshl_add_u64 v[2:3], s[2:3], 0, v[2:3]
	s_lshl_b32 s2, s28, 6
	s_ashr_i32 s3, s2, 31
	v_add_f32_e32 v39, 1.0, v39
	v_lshl_add_u64 v[2:3], s[2:3], 1, v[2:3]
	v_div_scale_f32 v41, s[2:3], v39, v39, 1.0
	v_rcp_f32_e32 v43, v41
	v_lshrrev_b32_e32 v11, 2, v8
	v_and_b32_e32 v35, 12, v11
	v_lshlrev_b32_e32 v11, 1, v8
	v_fma_f32 v45, -v41, v43, 1.0
	v_fmac_f32_e32 v43, v45, v43
	v_div_scale_f32 v45, vcc, 1.0, v39, 1.0
	v_mul_f32_e32 v47, v45, v43
	v_fma_f32 v58, -v41, v47, v45
	v_fmac_f32_e32 v47, v58, v43
	v_fma_f32 v41, -v41, v47, v45
	v_div_fmas_f32 v41, v41, v43, v47
	v_div_fixup_f32 v39, v41, v39, 1.0
	v_and_b32_e32 v148, 64, v8
	v_and_b32_e32 v37, 30, v11
	v_lshlrev_b32_e32 v11, 4, v8
	v_mul_f32_e32 v39, v194, v39
	v_lshl_add_u64 v[2:3], v[2:3], 0, v[148:149]
	v_and_b32_e32 v148, 48, v11
	v_fma_mixlo_f16 v39, v9, v39, 0
	v_mul_u32_u24_e32 v9, 0x50, v35
	v_or_b32_e32 v11, v33, v148
	v_or3_b32 v9, v33, v37, v9
	v_mul_f32_e32 v33, 0xbfb8aa3b, v193
	v_exp_f32_e32 v33, v33
	s_waitcnt vmcnt(0)
	ds_write_b16 v9, v39
	v_and_b32_e32 v10, 60, v8
	v_bfe_u32 v8, v8, 2, 4
	v_add_f32_e32 v33, 1.0, v33
	v_div_scale_f32 v35, s[2:3], v33, v33, 1.0
	v_rcp_f32_e32 v37, v35
	s_movk_i32 s4, 0x50
	v_mad_u32_u24 v8, v8, s4, v11
	v_lshl_add_u64 v[2:3], v[2:3], 0, v[148:149]
	v_fma_f32 v39, -v35, v37, 1.0
	v_fmac_f32_e32 v37, v39, v37
	v_div_scale_f32 v39, vcc, 1.0, v33, 1.0
	v_mul_f32_e32 v41, v39, v37
	v_fma_f32 v43, -v35, v41, v39
	v_fmac_f32_e32 v41, v43, v37
	v_fma_f32 v35, -v35, v41, v39
	v_div_fmas_f32 v35, v35, v37, v41
	v_div_fixup_f32 v33, v35, v33, 1.0
	v_mul_f32_e32 v33, v193, v33
	v_fma_mixlo_f16 v33, v192, v33, 0
	ds_write_b16 v9, v33 offset:80
	v_mul_f32_e32 v33, 0xbfb8aa3b, v191
	v_exp_f32_e32 v33, v33
	v_lshlrev_b32_e32 v148, 8, v10
	s_mov_b32 s33, 0x10000
	v_readlane_b32 s29, v255, 60
	v_add_f32_e32 v33, 1.0, v33
	v_div_scale_f32 v35, s[2:3], v33, v33, 1.0
	v_rcp_f32_e32 v37, v35
	s_nop 0
	v_fma_f32 v39, -v35, v37, 1.0
	v_fmac_f32_e32 v37, v39, v37
	v_div_scale_f32 v39, vcc, 1.0, v33, 1.0
	v_mul_f32_e32 v41, v39, v37
	v_fma_f32 v43, -v35, v41, v39
	v_fmac_f32_e32 v41, v43, v37
	v_fma_f32 v35, -v35, v41, v39
	v_div_fmas_f32 v35, v35, v37, v41
	v_div_fixup_f32 v33, v35, v33, 1.0
	v_mul_f32_e32 v33, v191, v33
	v_fma_mixlo_f16 v33, v190, v33, 0
	ds_write_b16 v9, v33 offset:160
	v_mul_f32_e32 v33, 0xbfb8aa3b, v189
	v_exp_f32_e32 v33, v33
	s_nop 0
	v_add_f32_e32 v33, 1.0, v33
	v_div_scale_f32 v35, s[2:3], v33, v33, 1.0
	v_rcp_f32_e32 v37, v35
	s_nop 0
	v_fma_f32 v39, -v35, v37, 1.0
	v_fmac_f32_e32 v37, v39, v37
	v_div_scale_f32 v39, vcc, 1.0, v33, 1.0
	v_mul_f32_e32 v41, v39, v37
	v_fma_f32 v43, -v35, v41, v39
	v_fmac_f32_e32 v41, v43, v37
	v_fma_f32 v35, -v35, v41, v39
	v_div_fmas_f32 v35, v35, v37, v41
	v_div_fixup_f32 v33, v35, v33, 1.0
	v_mul_f32_e32 v33, v189, v33
	v_fma_mixlo_f16 v33, v188, v33, 0
	ds_write_b16 v9, v33 offset:240
	v_mul_f32_e32 v33, 0xbfb8aa3b, v187
	v_exp_f32_e32 v33, v33
	s_nop 0
	v_add_f32_e32 v33, 1.0, v33
	v_div_scale_f32 v35, s[2:3], v33, v33, 1.0
	v_rcp_f32_e32 v37, v35
	s_nop 0
	v_fma_f32 v39, -v35, v37, 1.0
	v_fmac_f32_e32 v37, v39, v37
	v_div_scale_f32 v39, vcc, 1.0, v33, 1.0
	v_mul_f32_e32 v41, v39, v37
	v_fma_f32 v43, -v35, v41, v39
	v_fmac_f32_e32 v41, v43, v37
	v_fma_f32 v35, -v35, v41, v39
	v_div_fmas_f32 v35, v35, v37, v41
	v_div_fixup_f32 v33, v35, v33, 1.0
	v_mul_f32_e32 v33, v187, v33
	v_fma_mixlo_f16 v33, v186, v33, 0
	ds_write_b16 v9, v33 offset:32
	v_mul_f32_e32 v33, 0xbfb8aa3b, v185
	v_exp_f32_e32 v33, v33
	s_nop 0
	v_add_f32_e32 v33, 1.0, v33
	v_div_scale_f32 v35, s[2:3], v33, v33, 1.0
	v_rcp_f32_e32 v37, v35
	s_nop 0
	v_fma_f32 v39, -v35, v37, 1.0
	v_fmac_f32_e32 v37, v39, v37
	v_div_scale_f32 v39, vcc, 1.0, v33, 1.0
	v_mul_f32_e32 v41, v39, v37
	v_fma_f32 v43, -v35, v41, v39
	v_fmac_f32_e32 v41, v43, v37
	v_fma_f32 v35, -v35, v41, v39
	v_div_fmas_f32 v35, v35, v37, v41
	v_div_fixup_f32 v33, v35, v33, 1.0
	v_mul_f32_e32 v33, v185, v33
	v_fma_mixlo_f16 v33, v184, v33, 0
	ds_write_b16 v9, v33 offset:112
	v_mul_f32_e32 v33, 0xbfb8aa3b, v183
	v_exp_f32_e32 v33, v33
	s_nop 0
	v_add_f32_e32 v33, 1.0, v33
	v_div_scale_f32 v35, s[2:3], v33, v33, 1.0
	v_rcp_f32_e32 v37, v35
	s_nop 0
	v_fma_f32 v39, -v35, v37, 1.0
	v_fmac_f32_e32 v37, v39, v37
	v_div_scale_f32 v39, vcc, 1.0, v33, 1.0
	v_mul_f32_e32 v41, v39, v37
	v_fma_f32 v43, -v35, v41, v39
	v_fmac_f32_e32 v41, v43, v37
	v_fma_f32 v35, -v35, v41, v39
	v_div_fmas_f32 v35, v35, v37, v41
	v_div_fixup_f32 v33, v35, v33, 1.0
	v_mul_f32_e32 v33, v183, v33
	v_fma_mixlo_f16 v33, v182, v33, 0
	ds_write_b16 v9, v33 offset:192
	v_mul_f32_e32 v33, 0xbfb8aa3b, v181
	v_exp_f32_e32 v33, v33
	s_nop 0
	v_add_f32_e32 v33, 1.0, v33
	v_div_scale_f32 v35, s[2:3], v33, v33, 1.0
	v_rcp_f32_e32 v37, v35
	s_nop 0
	v_fma_f32 v39, -v35, v37, 1.0
	v_fmac_f32_e32 v37, v39, v37
	v_div_scale_f32 v39, vcc, 1.0, v33, 1.0
	v_mul_f32_e32 v41, v39, v37
	v_fma_f32 v43, -v35, v41, v39
	v_fmac_f32_e32 v41, v43, v37
	v_fma_f32 v35, -v35, v41, v39
	v_div_fmas_f32 v35, v35, v37, v41
	v_div_fixup_f32 v33, v35, v33, 1.0
	v_mul_f32_e32 v33, v181, v33
	v_fma_mixlo_f16 v33, v180, v33, 0
	ds_write_b16 v9, v33 offset:272
	v_mul_f32_e32 v33, 0xbfb8aa3b, v179
; DI float sigmoidf_(float x) { return 1.f / (1.f + __expf(-x)); }
; DI void moe_e1_phase(const Params& P, int l, char* smem, int* tb) {
;     ...
;       for (int h = 0; h < 2; h++) {
; #pragma unroll
;         for (int ml = 0; ml < 4; ml++)
; #pragma unroll
;           for (int n = 0; n < 2; n++)
; #pragma unroll
;             for (int j = 0; j < 4; j++) {
;               float a1 = acc[h * 4 + ml][n][j], a3 = acc[h * 4 + ml][n + 2][j];
;               *(half_t*)(stg + (ml * 16 + fq2 * 4 + j) * 80 + (n * 16 + fr2) * 2) = (half_t)(a1 * sigmoidf_(a1) * a3);
;             }
	v_exp_f32_e32 v33, v33
	s_nop 0
	v_add_f32_e32 v33, 1.0, v33
	v_div_scale_f32 v35, s[2:3], v33, v33, 1.0
	v_rcp_f32_e32 v37, v35
	s_nop 0
	v_fma_f32 v39, -v35, v37, 1.0
	v_fmac_f32_e32 v37, v39, v37
	v_div_scale_f32 v39, vcc, 1.0, v33, 1.0
	v_mul_f32_e32 v41, v39, v37
	v_fma_f32 v43, -v35, v41, v39
	v_fmac_f32_e32 v41, v43, v37
	v_fma_f32 v35, -v35, v41, v39
	v_div_fmas_f32 v35, v35, v37, v41
	v_div_fixup_f32 v33, v35, v33, 1.0
	v_mul_f32_e32 v33, v179, v33
	v_fma_mixlo_f16 v33, v176, v33, 0
	ds_write_b16 v9, v33 offset:1280
	v_mul_f32_e32 v33, 0xbfb8aa3b, v175
	v_exp_f32_e32 v33, v33
	s_nop 0
	v_add_f32_e32 v33, 1.0, v33
	v_div_scale_f32 v35, s[2:3], v33, v33, 1.0
	v_rcp_f32_e32 v37, v35
	s_nop 0
	v_fma_f32 v39, -v35, v37, 1.0
	v_fmac_f32_e32 v37, v39, v37
	v_div_scale_f32 v39, vcc, 1.0, v33, 1.0
	v_mul_f32_e32 v41, v39, v37
	v_fma_f32 v43, -v35, v41, v39
	v_fmac_f32_e32 v41, v43, v37
	v_fma_f32 v35, -v35, v41, v39
	v_div_fmas_f32 v35, v35, v37, v41
	v_div_fixup_f32 v33, v35, v33, 1.0
	v_mul_f32_e32 v33, v175, v33
	v_fma_mixlo_f16 v33, v174, v33, 0
	ds_write_b16 v9, v33 offset:1360
	v_mul_f32_e32 v33, 0xbfb8aa3b, v173
	v_exp_f32_e32 v33, v33
	s_nop 0
	v_add_f32_e32 v33, 1.0, v33
	v_div_scale_f32 v35, s[2:3], v33, v33, 1.0
	v_rcp_f32_e32 v37, v35
	s_nop 0
	v_fma_f32 v39, -v35, v37, 1.0
	v_fmac_f32_e32 v37, v39, v37
	v_div_scale_f32 v39, vcc, 1.0, v33, 1.0
	v_mul_f32_e32 v41, v39, v37
	v_fma_f32 v43, -v35, v41, v39
	v_fmac_f32_e32 v41, v43, v37
	v_fma_f32 v35, -v35, v41, v39
	v_div_fmas_f32 v35, v35, v37, v41
	v_div_fixup_f32 v33, v35, v33, 1.0
	v_mul_f32_e32 v33, v173, v33
	v_fma_mixlo_f16 v33, v171, v33, 0
	ds_write_b16 v9, v33 offset:1440
	v_mul_f32_e32 v33, 0xbfb8aa3b, v170
	v_exp_f32_e32 v33, v33
	s_nop 0
	v_add_f32_e32 v33, 1.0, v33
	v_div_scale_f32 v35, s[2:3], v33, v33, 1.0
	v_rcp_f32_e32 v37, v35
	s_nop 0
	v_fma_f32 v39, -v35, v37, 1.0
	v_fmac_f32_e32 v37, v39, v37
	v_div_scale_f32 v39, vcc, 1.0, v33, 1.0
	v_mul_f32_e32 v41, v39, v37
	v_fma_f32 v43, -v35, v41, v39
	v_fmac_f32_e32 v41, v43, v37
	v_fma_f32 v35, -v35, v41, v39
	v_div_fmas_f32 v35, v35, v37, v41
	v_div_fixup_f32 v33, v35, v33, 1.0
	v_mul_f32_e32 v33, v170, v33
	v_fma_mixlo_f16 v33, v169, v33, 0
	ds_write_b16 v9, v33 offset:1520
	v_mul_f32_e32 v33, 0xbfb8aa3b, v168
	v_exp_f32_e32 v33, v33
	s_nop 0
	v_add_f32_e32 v33, 1.0, v33
	v_div_scale_f32 v35, s[2:3], v33, v33, 1.0
	v_rcp_f32_e32 v37, v35
	s_nop 0
	v_fma_f32 v39, -v35, v37, 1.0
	v_fmac_f32_e32 v37, v39, v37
	v_div_scale_f32 v39, vcc, 1.0, v33, 1.0
	v_mul_f32_e32 v41, v39, v37
	v_fma_f32 v43, -v35, v41, v39
	v_fmac_f32_e32 v41, v43, v37
	v_fma_f32 v35, -v35, v41, v39
	v_div_fmas_f32 v35, v35, v37, v41
	v_div_fixup_f32 v33, v35, v33, 1.0
	v_mul_f32_e32 v33, v168, v33
	v_fma_mixlo_f16 v33, v167, v33, 0
	ds_write_b16 v9, v33 offset:1312
	v_mul_f32_e32 v33, 0xbfb8aa3b, v166
	v_exp_f32_e32 v33, v33
	s_nop 0
	v_add_f32_e32 v33, 1.0, v33
	v_div_scale_f32 v35, s[2:3], v33, v33, 1.0
	v_rcp_f32_e32 v37, v35
	s_nop 0
	v_fma_f32 v39, -v35, v37, 1.0
	v_fmac_f32_e32 v37, v39, v37
	v_div_scale_f32 v39, vcc, 1.0, v33, 1.0
	v_mul_f32_e32 v41, v39, v37
	v_fma_f32 v43, -v35, v41, v39
	v_fmac_f32_e32 v41, v43, v37
	v_fma_f32 v35, -v35, v41, v39
	v_div_fmas_f32 v35, v35, v37, v41
	v_div_fixup_f32 v33, v35, v33, 1.0
	v_mul_f32_e32 v33, v166, v33
	v_fma_mixlo_f16 v33, v165, v33, 0
	ds_write_b16 v9, v33 offset:1392
	v_mul_f32_e32 v33, 0xbfb8aa3b, v164
	v_exp_f32_e32 v33, v33
	s_nop 0
	v_add_f32_e32 v33, 1.0, v33
	v_div_scale_f32 v35, s[2:3], v33, v33, 1.0
	v_rcp_f32_e32 v37, v35
	s_nop 0
	v_fma_f32 v39, -v35, v37, 1.0
	v_fmac_f32_e32 v37, v39, v37
	v_div_scale_f32 v39, vcc, 1.0, v33, 1.0
	v_mul_f32_e32 v41, v39, v37
	v_fma_f32 v43, -v35, v41, v39
	v_fmac_f32_e32 v41, v43, v37
	v_fma_f32 v35, -v35, v41, v39
	v_div_fmas_f32 v35, v35, v37, v41
	v_div_fixup_f32 v33, v35, v33, 1.0
	v_mul_f32_e32 v33, v164, v33
	v_fma_mixlo_f16 v33, v163, v33, 0
	ds_write_b16 v9, v33 offset:1472
	v_mul_f32_e32 v33, 0xbfb8aa3b, v162
	v_exp_f32_e32 v33, v33
	s_nop 0
	v_add_f32_e32 v33, 1.0, v33
	v_div_scale_f32 v35, s[2:3], v33, v33, 1.0
	v_rcp_f32_e32 v37, v35
	s_nop 0
	v_fma_f32 v39, -v35, v37, 1.0
	v_fmac_f32_e32 v37, v39, v37
	v_div_scale_f32 v39, vcc, 1.0, v33, 1.0
	v_mul_f32_e32 v41, v39, v37
	v_fma_f32 v43, -v35, v41, v39
	v_fmac_f32_e32 v41, v43, v37
	v_fma_f32 v35, -v35, v41, v39
	v_div_fmas_f32 v35, v35, v37, v41
	v_div_fixup_f32 v33, v35, v33, 1.0
	v_mul_f32_e32 v33, v162, v33
	v_fma_mixlo_f16 v33, v161, v33, 0
	ds_write_b16 v9, v33 offset:1552
	v_mul_f32_e32 v33, 0xbfb8aa3b, v160
	v_exp_f32_e32 v33, v33
	s_nop 0
	v_add_f32_e32 v33, 1.0, v33
	v_div_scale_f32 v35, s[2:3], v33, v33, 1.0
	v_rcp_f32_e32 v37, v35
	s_nop 0
	v_fma_f32 v39, -v35, v37, 1.0
	v_fmac_f32_e32 v37, v39, v37
	v_div_scale_f32 v39, vcc, 1.0, v33, 1.0
	v_mul_f32_e32 v41, v39, v37
	v_fma_f32 v43, -v35, v41, v39
	v_fmac_f32_e32 v41, v43, v37
	v_fma_f32 v35, -v35, v41, v39
	v_div_fmas_f32 v35, v35, v37, v41
	v_div_fixup_f32 v33, v35, v33, 1.0
	v_mul_f32_e32 v33, v160, v33
	v_fma_mixlo_f16 v33, v159, v33, 0
	ds_write_b16 v9, v33 offset:2560
	v_mul_f32_e32 v33, 0xbfb8aa3b, v158
	v_exp_f32_e32 v33, v33
	s_nop 0
	v_add_f32_e32 v33, 1.0, v33
	v_div_scale_f32 v35, s[2:3], v33, v33, 1.0
	v_rcp_f32_e32 v37, v35
	s_nop 0
	v_fma_f32 v39, -v35, v37, 1.0
	v_fmac_f32_e32 v37, v39, v37
	v_div_scale_f32 v39, vcc, 1.0, v33, 1.0
	v_mul_f32_e32 v41, v39, v37
	v_fma_f32 v43, -v35, v41, v39
	v_fmac_f32_e32 v41, v43, v37
	v_fma_f32 v35, -v35, v41, v39
	v_div_fmas_f32 v35, v35, v37, v41
	v_div_fixup_f32 v33, v35, v33, 1.0
	v_mul_f32_e32 v33, v158, v33
	v_fma_mixlo_f16 v33, v157, v33, 0
	ds_write_b16 v9, v33 offset:2640
; DI float sigmoidf_(float x) { return 1.f / (1.f + __expf(-x)); }
; DI void moe_e1_phase(const Params& P, int l, char* smem, int* tb) {
;     ...
;       for (int h = 0; h < 2; h++) {
; #pragma unroll
;         for (int ml = 0; ml < 4; ml++)
; #pragma unroll
;           for (int n = 0; n < 2; n++)
; #pragma unroll
;             for (int j = 0; j < 4; j++) {
;               float a1 = acc[h * 4 + ml][n][j], a3 = acc[h * 4 + ml][n + 2][j];
;               *(half_t*)(stg + (ml * 16 + fq2 * 4 + j) * 80 + (n * 16 + fr2) * 2) = (half_t)(a1 * sigmoidf_(a1) * a3);
;             }
	v_mul_f32_e32 v33, 0xbfb8aa3b, v156
	v_exp_f32_e32 v33, v33
	s_nop 0
	v_add_f32_e32 v33, 1.0, v33
	v_div_scale_f32 v35, s[2:3], v33, v33, 1.0
	v_rcp_f32_e32 v37, v35
	s_nop 0
	v_fma_f32 v39, -v35, v37, 1.0
	v_fmac_f32_e32 v37, v39, v37
	v_div_scale_f32 v39, vcc, 1.0, v33, 1.0
	v_mul_f32_e32 v41, v39, v37
	v_fma_f32 v43, -v35, v41, v39
	v_fmac_f32_e32 v41, v43, v37
	v_fma_f32 v35, -v35, v41, v39
	v_div_fmas_f32 v35, v35, v37, v41
	v_div_fixup_f32 v33, v35, v33, 1.0
	v_mul_f32_e32 v33, v156, v33
	v_fma_mixlo_f16 v23, v23, v33, 0
	ds_write_b16 v9, v23 offset:2720
	v_mul_f32_e32 v23, 0xbfb8aa3b, v19
	v_exp_f32_e32 v23, v23
	s_nop 0
	v_add_f32_e32 v23, 1.0, v23
	v_div_scale_f32 v33, s[2:3], v23, v23, 1.0
	v_rcp_f32_e32 v35, v33
	s_nop 0
	v_fma_f32 v37, -v33, v35, 1.0
	v_fmac_f32_e32 v35, v37, v35
	v_div_scale_f32 v37, vcc, 1.0, v23, 1.0
	v_mul_f32_e32 v39, v37, v35
	v_fma_f32 v41, -v33, v39, v37
	v_fmac_f32_e32 v39, v41, v35
	v_fma_f32 v33, -v33, v39, v37
	v_div_fmas_f32 v33, v33, v35, v39
	v_div_fixup_f32 v23, v33, v23, 1.0
	v_mul_f32_e32 v19, v19, v23
	v_fma_mixlo_f16 v18, v18, v19, 0
	ds_write_b16 v9, v18 offset:2800
	v_mul_f32_e32 v18, 0xbfb8aa3b, v17
	v_exp_f32_e32 v18, v18
	s_nop 0
	v_add_f32_e32 v18, 1.0, v18
	v_div_scale_f32 v19, s[2:3], v18, v18, 1.0
	v_rcp_f32_e32 v23, v19
	s_nop 0
	v_fma_f32 v33, -v19, v23, 1.0
	v_fmac_f32_e32 v23, v33, v23
	v_div_scale_f32 v33, vcc, 1.0, v18, 1.0
	v_mul_f32_e32 v35, v33, v23
	v_fma_f32 v37, -v19, v35, v33
	v_fmac_f32_e32 v35, v37, v23
	v_fma_f32 v19, -v19, v35, v33
	v_div_fmas_f32 v19, v19, v23, v35
	v_div_fixup_f32 v18, v19, v18, 1.0
	v_mul_f32_e32 v17, v17, v18
	v_fma_mixlo_f16 v16, v16, v17, 0
	ds_write_b16 v9, v16 offset:2592
	v_mul_f32_e32 v16, 0xbfb8aa3b, v15
	v_exp_f32_e32 v16, v16
	s_nop 0
	v_add_f32_e32 v16, 1.0, v16
	v_div_scale_f32 v17, s[2:3], v16, v16, 1.0
	v_rcp_f32_e32 v18, v17
	s_nop 0
	v_fma_f32 v19, -v17, v18, 1.0
	v_fmac_f32_e32 v18, v19, v18
	v_div_scale_f32 v19, vcc, 1.0, v16, 1.0
	v_mul_f32_e32 v23, v19, v18
	v_fma_f32 v33, -v17, v23, v19
	v_fmac_f32_e32 v23, v33, v18
	v_fma_f32 v17, -v17, v23, v19
	v_div_fmas_f32 v17, v17, v18, v23
	v_div_fixup_f32 v16, v17, v16, 1.0
	v_mul_f32_e32 v15, v15, v16
	v_fma_mixlo_f16 v14, v14, v15, 0
	ds_write_b16 v9, v14 offset:2672
	v_mul_f32_e32 v14, 0xbfb8aa3b, v13
	v_exp_f32_e32 v14, v14
	s_nop 0
	v_add_f32_e32 v14, 1.0, v14
	v_div_scale_f32 v15, s[2:3], v14, v14, 1.0
	v_rcp_f32_e32 v16, v15
	s_nop 0
	v_fma_f32 v17, -v15, v16, 1.0
	v_fmac_f32_e32 v16, v17, v16
	v_div_scale_f32 v17, vcc, 1.0, v14, 1.0
	v_mul_f32_e32 v18, v17, v16
	v_fma_f32 v19, -v15, v18, v17
	v_fmac_f32_e32 v18, v19, v16
	v_fma_f32 v15, -v15, v18, v17
	v_div_fmas_f32 v15, v15, v16, v18
	v_div_fixup_f32 v14, v15, v14, 1.0
	v_mul_f32_e32 v13, v13, v14
	v_fma_mixlo_f16 v12, v12, v13, 0
	ds_write_b16 v9, v12 offset:2752
	v_mul_f32_e32 v12, 0xbfb8aa3b, v1
	v_exp_f32_e32 v12, v12
	v_or_b32_e32 v18, 0xc0, v10
	v_add_f32_e32 v12, 1.0, v12
	v_div_scale_f32 v13, s[2:3], v12, v12, 1.0
	v_rcp_f32_e32 v14, v13
	s_nop 0
	v_fma_f32 v15, -v13, v14, 1.0
	v_fmac_f32_e32 v14, v15, v14
	v_div_scale_f32 v15, vcc, 1.0, v12, 1.0
	v_mul_f32_e32 v16, v15, v14
	v_fma_f32 v17, -v13, v16, v15
	v_fmac_f32_e32 v16, v17, v14
	v_fma_f32 v13, -v13, v16, v15
	v_div_fmas_f32 v13, v13, v14, v16
	v_div_fixup_f32 v12, v13, v12, 1.0
	v_mul_f32_e32 v1, v1, v12
	v_fma_mixlo_f16 v0, v0, v1, 0
	ds_write_b16 v9, v0 offset:2832
	v_mul_f32_e32 v0, 0xbfb8aa3b, v7
	v_exp_f32_e32 v0, v0
	s_nop 0
	v_add_f32_e32 v0, 1.0, v0
	v_div_scale_f32 v1, s[2:3], v0, v0, 1.0
	v_rcp_f32_e32 v12, v1
	s_nop 0
	v_fma_f32 v13, -v1, v12, 1.0
	v_fmac_f32_e32 v12, v13, v12
	v_div_scale_f32 v13, vcc, 1.0, v0, 1.0
	v_mul_f32_e32 v14, v13, v12
	v_fma_f32 v15, -v1, v14, v13
	v_fmac_f32_e32 v14, v15, v12
	v_fma_f32 v1, -v1, v14, v13
	v_div_fmas_f32 v1, v1, v12, v14
	v_div_fixup_f32 v0, v1, v0, 1.0
	v_mul_f32_e32 v0, v7, v0
	v_fma_mixlo_f16 v0, v155, v0, 0
	ds_write_b16 v9, v0 offset:3840
	v_mul_f32_e32 v0, 0xbfb8aa3b, v6
	v_exp_f32_e32 v0, v0
	s_nop 0
	v_add_f32_e32 v0, 1.0, v0
	v_div_scale_f32 v1, s[2:3], v0, v0, 1.0
	v_rcp_f32_e32 v7, v1
	s_nop 0
	v_fma_f32 v12, -v1, v7, 1.0
	v_fmac_f32_e32 v7, v12, v7
	v_div_scale_f32 v12, vcc, 1.0, v0, 1.0
	v_mul_f32_e32 v13, v12, v7
	v_fma_f32 v14, -v1, v13, v12
	v_fmac_f32_e32 v13, v14, v7
	v_fma_f32 v1, -v1, v13, v12
	v_div_fmas_f32 v1, v1, v7, v13
	v_div_fixup_f32 v0, v1, v0, 1.0
	v_mul_f32_e32 v0, v6, v0
	v_fma_mixlo_f16 v0, v154, v0, 0
	ds_write_b16 v9, v0 offset:3920
	v_mul_f32_e32 v0, 0xbfb8aa3b, v5
	v_exp_f32_e32 v0, v0
	s_nop 0
	v_add_f32_e32 v0, 1.0, v0
	v_div_scale_f32 v1, s[2:3], v0, v0, 1.0
	v_rcp_f32_e32 v6, v1
	s_nop 0
	v_fma_f32 v7, -v1, v6, 1.0
	v_fmac_f32_e32 v6, v7, v6
	v_div_scale_f32 v7, vcc, 1.0, v0, 1.0
	v_mul_f32_e32 v12, v7, v6
	v_fma_f32 v13, -v1, v12, v7
	v_fmac_f32_e32 v12, v13, v6
	v_fma_f32 v1, -v1, v12, v7
	v_div_fmas_f32 v1, v1, v6, v12
	v_div_fixup_f32 v0, v1, v0, 1.0
	v_mul_f32_e32 v0, v5, v0
	v_fma_mixlo_f16 v0, v153, v0, 0
	ds_write_b16 v9, v0 offset:4000
	v_mul_f32_e32 v0, 0xbfb8aa3b, v4
	v_exp_f32_e32 v0, v0
	s_nop 0
	v_add_f32_e32 v0, 1.0, v0
	v_div_scale_f32 v1, s[2:3], v0, v0, 1.0
	v_rcp_f32_e32 v5, v1
	s_nop 0
	v_fma_f32 v6, -v1, v5, 1.0
	v_fmac_f32_e32 v5, v6, v5
	v_div_scale_f32 v6, vcc, 1.0, v0, 1.0
	v_mul_f32_e32 v7, v6, v5
	v_fma_f32 v12, -v1, v7, v6
	v_fmac_f32_e32 v7, v12, v5
	v_fma_f32 v1, -v1, v7, v6
	v_div_fmas_f32 v1, v1, v5, v7
	v_div_fixup_f32 v0, v1, v0, 1.0
	v_mul_f32_e32 v0, v4, v0
	v_fma_mixlo_f16 v0, v152, v0, 0
	ds_write_b16 v9, v0 offset:4080
	v_mul_f32_e32 v0, 0xbfb8aa3b, v151
	v_exp_f32_e32 v0, v0
	s_nop 0
	v_add_f32_e32 v0, 1.0, v0
; DI float sigmoidf_(float x) { return 1.f / (1.f + __expf(-x)); }
; DI void moe_e1_phase(const Params& P, int l, char* smem, int* tb) {
;     ...
;       for (int h = 0; h < 2; h++) {
; #pragma unroll
;         for (int ml = 0; ml < 4; ml++)
; #pragma unroll
;           for (int n = 0; n < 2; n++)
; #pragma unroll
;             for (int j = 0; j < 4; j++) {
;               float a1 = acc[h * 4 + ml][n][j], a3 = acc[h * 4 + ml][n + 2][j];
;               *(half_t*)(stg + (ml * 16 + fq2 * 4 + j) * 80 + (n * 16 + fr2) * 2) = (half_t)(a1 * sigmoidf_(a1) * a3);
;             }
;         __builtin_amdgcn_wave_barrier();
; #pragma unroll
;         for (int i = 0; i < 4; i++) {
;           const int c = i * 64 + lane2, row = c >> 2, c16 = c & 3;
;           h8 v = *(const h8*)(stg + row * 80 + c16 * 16);
;           *(h8*)(Hd + (size_t)(h * 64 + row) * 512 + c16 * 8) = v;
;         }
;         __builtin_amdgcn_wave_barrier();
	v_div_scale_f32 v1, s[2:3], v0, v0, 1.0
	v_rcp_f32_e32 v4, v1
	s_nop 0
	v_fma_f32 v5, -v1, v4, 1.0
	v_fmac_f32_e32 v4, v5, v4
	v_div_scale_f32 v5, vcc, 1.0, v0, 1.0
	v_mul_f32_e32 v6, v5, v4
	v_fma_f32 v7, -v1, v6, v5
	v_fmac_f32_e32 v6, v7, v4
	v_fma_f32 v1, -v1, v6, v5
	v_div_fmas_f32 v1, v1, v4, v6
	v_div_fixup_f32 v0, v1, v0, 1.0
	v_mul_f32_e32 v0, v151, v0
	v_fma_mixlo_f16 v0, v150, v0, 0
	ds_write_b16 v9, v0 offset:3872
	v_mul_f32_e32 v0, 0xbfb8aa3b, v22
	v_exp_f32_e32 v0, v0
	s_nop 0
	v_add_f32_e32 v0, 1.0, v0
	v_div_scale_f32 v1, s[2:3], v0, v0, 1.0
	v_rcp_f32_e32 v4, v1
	s_nop 0
	v_fma_f32 v5, -v1, v4, 1.0
	v_fmac_f32_e32 v4, v5, v4
	v_div_scale_f32 v5, vcc, 1.0, v0, 1.0
	v_mul_f32_e32 v6, v5, v4
	v_fma_f32 v7, -v1, v6, v5
	v_fmac_f32_e32 v6, v7, v4
	v_fma_f32 v1, -v1, v6, v5
	v_div_fmas_f32 v1, v1, v4, v6
	v_div_fixup_f32 v0, v1, v0, 1.0
	v_mul_f32_e32 v0, v22, v0
	v_fma_mixlo_f16 v0, v147, v0, 0
	ds_write_b16 v9, v0 offset:3952
	v_mul_f32_e32 v0, 0xbfb8aa3b, v21
	v_exp_f32_e32 v0, v0
	s_nop 0
	v_add_f32_e32 v0, 1.0, v0
	v_div_scale_f32 v1, s[2:3], v0, v0, 1.0
	v_rcp_f32_e32 v4, v1
	s_nop 0
	v_fma_f32 v5, -v1, v4, 1.0
	v_fmac_f32_e32 v4, v5, v4
	v_div_scale_f32 v5, vcc, 1.0, v0, 1.0
	v_mul_f32_e32 v6, v5, v4
	v_fma_f32 v7, -v1, v6, v5
	v_fmac_f32_e32 v6, v7, v4
	v_fma_f32 v1, -v1, v6, v5
	v_div_fmas_f32 v1, v1, v4, v6
	v_div_fixup_f32 v0, v1, v0, 1.0
	v_mul_f32_e32 v0, v21, v0
	v_fma_mixlo_f16 v0, v146, v0, 0
	ds_write_b16 v9, v0 offset:4032
	v_mul_f32_e32 v0, 0xbfb8aa3b, v20
	v_exp_f32_e32 v0, v0
	s_nop 0
	v_add_f32_e32 v0, 1.0, v0
	v_div_scale_f32 v1, s[2:3], v0, v0, 1.0
	v_rcp_f32_e32 v4, v1
	s_nop 0
	v_fma_f32 v5, -v1, v4, 1.0
	v_fmac_f32_e32 v4, v5, v4
	v_div_scale_f32 v5, vcc, 1.0, v0, 1.0
	v_mul_f32_e32 v6, v5, v4
	v_fma_f32 v7, -v1, v6, v5
	v_fmac_f32_e32 v6, v7, v4
	v_fma_f32 v1, -v1, v6, v5
	v_div_fmas_f32 v1, v1, v4, v6
	v_div_fixup_f32 v0, v1, v0, 1.0
	v_mul_f32_e32 v0, v20, v0
	v_fma_mixlo_f16 v0, v145, v0, 0
	ds_write_b16 v9, v0 offset:4112
	ds_read_b128 v[4:7], v8
	v_lshl_add_u64 v[0:1], v[2:3], 0, v[148:149]
	s_waitcnt lgkmcnt(0)
	global_store_dwordx4 v[0:1], v[4:7], off nt
	s_nop 1
	v_or_b32_e32 v4, 64, v10
	v_lshrrev_b32_e32 v5, 2, v4
	v_mad_u32_u24 v12, v5, s4, v11
	ds_read_b128 v[14:17], v12
	v_or_b32_e32 v6, 0x80, v10
	v_lshlrev_b32_e32 v148, 8, v4
	v_lshrrev_b32_e32 v7, 2, v6
	v_lshl_add_u64 v[4:5], v[2:3], 0, v[148:149]
	v_mad_u32_u24 v13, v7, s4, v11
	s_waitcnt lgkmcnt(0)
	global_store_dwordx4 v[4:5], v[14:17], off nt
	ds_read_b128 v[14:17], v13
	v_lshlrev_b32_e32 v148, 8, v6
	v_lshrrev_b32_e32 v10, 2, v18
	v_lshl_add_u64 v[6:7], v[2:3], 0, v[148:149]
	v_mad_u32_u24 v10, v10, s4, v11
	v_mul_f32_e32 v11, 0xbfb8aa3b, v144
	s_waitcnt lgkmcnt(0)
	global_store_dwordx4 v[6:7], v[14:17], off nt
	ds_read_b128 v[14:17], v10
	v_exp_f32_e32 v11, v11
	v_lshlrev_b32_e32 v148, 8, v18
	v_lshl_add_u64 v[2:3], v[2:3], 0, v[148:149]
	v_add_f32_e32 v11, 1.0, v11
	s_waitcnt lgkmcnt(0)
	global_store_dwordx4 v[2:3], v[14:17], off nt
	s_nop 1
	v_div_scale_f32 v14, s[2:3], v11, v11, 1.0
	v_rcp_f32_e32 v15, v14
	s_nop 0
	v_fma_f32 v16, -v14, v15, 1.0
	v_fmac_f32_e32 v15, v16, v15
	v_div_scale_f32 v16, vcc, 1.0, v11, 1.0
	v_mul_f32_e32 v17, v16, v15
	v_fma_f32 v18, -v14, v17, v16
	v_fmac_f32_e32 v17, v18, v15
	v_fma_f32 v14, -v14, v17, v16
	v_div_fmas_f32 v14, v14, v15, v17
	v_div_fixup_f32 v11, v14, v11, 1.0
	v_mul_f32_e32 v11, v144, v11
	v_fma_mixlo_f16 v11, v143, v11, 0
	ds_write_b16 v9, v11
	v_mul_f32_e32 v11, 0xbfb8aa3b, v142
	v_exp_f32_e32 v11, v11
	s_nop 0
	v_add_f32_e32 v11, 1.0, v11
	v_div_scale_f32 v14, s[2:3], v11, v11, 1.0
	v_rcp_f32_e32 v15, v14
	s_nop 0
	v_fma_f32 v16, -v14, v15, 1.0
	v_fmac_f32_e32 v15, v16, v15
	v_div_scale_f32 v16, vcc, 1.0, v11, 1.0
	v_mul_f32_e32 v17, v16, v15
	v_fma_f32 v18, -v14, v17, v16
	v_fmac_f32_e32 v17, v18, v15
	v_fma_f32 v14, -v14, v17, v16
	v_div_fmas_f32 v14, v14, v15, v17
	v_div_fixup_f32 v11, v14, v11, 1.0
	v_mul_f32_e32 v11, v142, v11
	v_fma_mixlo_f16 v11, v141, v11, 0
	ds_write_b16 v9, v11 offset:80
	v_mul_f32_e32 v11, 0xbfb8aa3b, v140
	v_exp_f32_e32 v11, v11
	s_nop 0
	v_add_f32_e32 v11, 1.0, v11
	v_div_scale_f32 v14, s[2:3], v11, v11, 1.0
	v_rcp_f32_e32 v15, v14
	s_nop 0
	v_fma_f32 v16, -v14, v15, 1.0
	v_fmac_f32_e32 v15, v16, v15
	v_div_scale_f32 v16, vcc, 1.0, v11, 1.0
	v_mul_f32_e32 v17, v16, v15
	v_fma_f32 v18, -v14, v17, v16
	v_fmac_f32_e32 v17, v18, v15
	v_fma_f32 v14, -v14, v17, v16
	v_div_fmas_f32 v14, v14, v15, v17
	v_div_fixup_f32 v11, v14, v11, 1.0
	v_mul_f32_e32 v11, v140, v11
	v_fma_mixlo_f16 v11, v139, v11, 0
	ds_write_b16 v9, v11 offset:160
	v_mul_f32_e32 v11, 0xbfb8aa3b, v138
	v_exp_f32_e32 v11, v11
	s_nop 0
	v_add_f32_e32 v11, 1.0, v11
	v_div_scale_f32 v14, s[2:3], v11, v11, 1.0
	v_rcp_f32_e32 v15, v14
	s_nop 0
	v_fma_f32 v16, -v14, v15, 1.0
	v_fmac_f32_e32 v15, v16, v15
	v_div_scale_f32 v16, vcc, 1.0, v11, 1.0
	v_mul_f32_e32 v17, v16, v15
	v_fma_f32 v18, -v14, v17, v16
	v_fmac_f32_e32 v17, v18, v15
	v_fma_f32 v14, -v14, v17, v16
	v_div_fmas_f32 v14, v14, v15, v17
	v_div_fixup_f32 v11, v14, v11, 1.0
	v_mul_f32_e32 v11, v138, v11
	v_fma_mixlo_f16 v11, v137, v11, 0
	ds_write_b16 v9, v11 offset:240
	v_mul_f32_e32 v11, 0xbfb8aa3b, v136
	v_exp_f32_e32 v11, v11
	s_nop 0
	v_add_f32_e32 v11, 1.0, v11
	v_div_scale_f32 v14, s[2:3], v11, v11, 1.0
	v_rcp_f32_e32 v15, v14
	s_nop 0
	v_fma_f32 v16, -v14, v15, 1.0
	v_fmac_f32_e32 v15, v16, v15
	v_div_scale_f32 v16, vcc, 1.0, v11, 1.0
	v_mul_f32_e32 v17, v16, v15
	v_fma_f32 v18, -v14, v17, v16
	v_fmac_f32_e32 v17, v18, v15
	v_fma_f32 v14, -v14, v17, v16
	v_div_fmas_f32 v14, v14, v15, v17
	v_div_fixup_f32 v11, v14, v11, 1.0
; DI float sigmoidf_(float x) { return 1.f / (1.f + __expf(-x)); }
; DI void moe_e1_phase(const Params& P, int l, char* smem, int* tb) {
;     ...
;       for (int h = 0; h < 2; h++) {
; #pragma unroll
;         for (int ml = 0; ml < 4; ml++)
; #pragma unroll
;           for (int n = 0; n < 2; n++)
; #pragma unroll
;             for (int j = 0; j < 4; j++) {
;               float a1 = acc[h * 4 + ml][n][j], a3 = acc[h * 4 + ml][n + 2][j];
;               *(half_t*)(stg + (ml * 16 + fq2 * 4 + j) * 80 + (n * 16 + fr2) * 2) = (half_t)(a1 * sigmoidf_(a1) * a3);
;             }
	v_mul_f32_e32 v11, v136, v11
	v_fma_mixlo_f16 v11, v135, v11, 0
	ds_write_b16 v9, v11 offset:32
	v_mul_f32_e32 v11, 0xbfb8aa3b, v134
	v_exp_f32_e32 v11, v11
	s_nop 0
	v_add_f32_e32 v11, 1.0, v11
	v_div_scale_f32 v14, s[2:3], v11, v11, 1.0
	v_rcp_f32_e32 v15, v14
	s_nop 0
	v_fma_f32 v16, -v14, v15, 1.0
	v_fmac_f32_e32 v15, v16, v15
	v_div_scale_f32 v16, vcc, 1.0, v11, 1.0
	v_mul_f32_e32 v17, v16, v15
	v_fma_f32 v18, -v14, v17, v16
	v_fmac_f32_e32 v17, v18, v15
	v_fma_f32 v14, -v14, v17, v16
	v_div_fmas_f32 v14, v14, v15, v17
	v_div_fixup_f32 v11, v14, v11, 1.0
	v_mul_f32_e32 v11, v134, v11
	v_fma_mixlo_f16 v11, v133, v11, 0
	ds_write_b16 v9, v11 offset:112
	v_mul_f32_e32 v11, 0xbfb8aa3b, v132
	v_exp_f32_e32 v11, v11
	s_nop 0
	v_add_f32_e32 v11, 1.0, v11
	v_div_scale_f32 v14, s[2:3], v11, v11, 1.0
	v_rcp_f32_e32 v15, v14
	s_nop 0
	v_fma_f32 v16, -v14, v15, 1.0
	v_fmac_f32_e32 v15, v16, v15
	v_div_scale_f32 v16, vcc, 1.0, v11, 1.0
	v_mul_f32_e32 v17, v16, v15
	v_fma_f32 v18, -v14, v17, v16
	v_fmac_f32_e32 v17, v18, v15
	v_fma_f32 v14, -v14, v17, v16
	v_div_fmas_f32 v14, v14, v15, v17
	v_div_fixup_f32 v11, v14, v11, 1.0
	v_mul_f32_e32 v11, v132, v11
	v_fma_mixlo_f16 v11, v131, v11, 0
	ds_write_b16 v9, v11 offset:192
	v_mul_f32_e32 v11, 0xbfb8aa3b, v130
	v_exp_f32_e32 v11, v11
	s_nop 0
	v_add_f32_e32 v11, 1.0, v11
	v_div_scale_f32 v14, s[2:3], v11, v11, 1.0
	v_rcp_f32_e32 v15, v14
	s_nop 0
	v_fma_f32 v16, -v14, v15, 1.0
	v_fmac_f32_e32 v15, v16, v15
	v_div_scale_f32 v16, vcc, 1.0, v11, 1.0
	v_mul_f32_e32 v17, v16, v15
	v_fma_f32 v18, -v14, v17, v16
	v_fmac_f32_e32 v17, v18, v15
	v_fma_f32 v14, -v14, v17, v16
	v_div_fmas_f32 v14, v14, v15, v17
	v_div_fixup_f32 v11, v14, v11, 1.0
	v_mul_f32_e32 v11, v130, v11
	v_fma_mixlo_f16 v11, v129, v11, 0
	ds_write_b16 v9, v11 offset:272
	v_mul_f32_e32 v11, 0xbfb8aa3b, v128
	v_exp_f32_e32 v11, v11
	s_nop 0
	v_add_f32_e32 v11, 1.0, v11
	v_div_scale_f32 v14, s[2:3], v11, v11, 1.0
	v_rcp_f32_e32 v15, v14
	s_nop 0
	v_fma_f32 v16, -v14, v15, 1.0
	v_fmac_f32_e32 v15, v16, v15
	v_div_scale_f32 v16, vcc, 1.0, v11, 1.0
	v_mul_f32_e32 v17, v16, v15
	v_fma_f32 v18, -v14, v17, v16
	v_fmac_f32_e32 v17, v18, v15
	v_fma_f32 v14, -v14, v17, v16
	v_div_fmas_f32 v14, v14, v15, v17
	v_div_fixup_f32 v11, v14, v11, 1.0
	v_mul_f32_e32 v11, v128, v11
	v_fma_mixlo_f16 v11, v127, v11, 0
	ds_write_b16 v9, v11 offset:1280
	v_mul_f32_e32 v11, 0xbfb8aa3b, v126
	v_exp_f32_e32 v11, v11
	s_nop 0
	v_add_f32_e32 v11, 1.0, v11
	v_div_scale_f32 v14, s[2:3], v11, v11, 1.0
	v_rcp_f32_e32 v15, v14
	s_nop 0
	v_fma_f32 v16, -v14, v15, 1.0
	v_fmac_f32_e32 v15, v16, v15
	v_div_scale_f32 v16, vcc, 1.0, v11, 1.0
	v_mul_f32_e32 v17, v16, v15
	v_fma_f32 v18, -v14, v17, v16
	v_fmac_f32_e32 v17, v18, v15
	v_fma_f32 v14, -v14, v17, v16
	v_div_fmas_f32 v14, v14, v15, v17
	v_div_fixup_f32 v11, v14, v11, 1.0
	v_mul_f32_e32 v11, v126, v11
	v_fma_mixlo_f16 v11, v125, v11, 0
	ds_write_b16 v9, v11 offset:1360
	v_mul_f32_e32 v11, 0xbfb8aa3b, v124
	v_exp_f32_e32 v11, v11
	s_nop 0
	v_add_f32_e32 v11, 1.0, v11
	v_div_scale_f32 v14, s[2:3], v11, v11, 1.0
	v_rcp_f32_e32 v15, v14
	s_nop 0
	v_fma_f32 v16, -v14, v15, 1.0
	v_fmac_f32_e32 v15, v16, v15
	v_div_scale_f32 v16, vcc, 1.0, v11, 1.0
	v_mul_f32_e32 v17, v16, v15
	v_fma_f32 v18, -v14, v17, v16
	v_fmac_f32_e32 v17, v18, v15
	v_fma_f32 v14, -v14, v17, v16
	v_div_fmas_f32 v14, v14, v15, v17
	v_div_fixup_f32 v11, v14, v11, 1.0
	v_mul_f32_e32 v11, v124, v11
	v_fma_mixlo_f16 v11, v123, v11, 0
	ds_write_b16 v9, v11 offset:1440
	v_mul_f32_e32 v11, 0xbfb8aa3b, v122
	v_exp_f32_e32 v11, v11
	s_nop 0
	v_add_f32_e32 v11, 1.0, v11
	v_div_scale_f32 v14, s[2:3], v11, v11, 1.0
	v_rcp_f32_e32 v15, v14
	s_nop 0
	v_fma_f32 v16, -v14, v15, 1.0
	v_fmac_f32_e32 v15, v16, v15
	v_div_scale_f32 v16, vcc, 1.0, v11, 1.0
	v_mul_f32_e32 v17, v16, v15
	v_fma_f32 v18, -v14, v17, v16
	v_fmac_f32_e32 v17, v18, v15
	v_fma_f32 v14, -v14, v17, v16
	v_div_fmas_f32 v14, v14, v15, v17
	v_div_fixup_f32 v11, v14, v11, 1.0
	v_mul_f32_e32 v11, v122, v11
	v_fma_mixlo_f16 v11, v121, v11, 0
	ds_write_b16 v9, v11 offset:1520
	v_mul_f32_e32 v11, 0xbfb8aa3b, v120
	v_exp_f32_e32 v11, v11
	s_nop 0
	v_add_f32_e32 v11, 1.0, v11
	v_div_scale_f32 v14, s[2:3], v11, v11, 1.0
	v_rcp_f32_e32 v15, v14
	s_nop 0
	v_fma_f32 v16, -v14, v15, 1.0
	v_fmac_f32_e32 v15, v16, v15
	v_div_scale_f32 v16, vcc, 1.0, v11, 1.0
	v_mul_f32_e32 v17, v16, v15
	v_fma_f32 v18, -v14, v17, v16
	v_fmac_f32_e32 v17, v18, v15
	v_fma_f32 v14, -v14, v17, v16
	v_div_fmas_f32 v14, v14, v15, v17
	v_div_fixup_f32 v11, v14, v11, 1.0
	v_mul_f32_e32 v11, v120, v11
	v_fma_mixlo_f16 v11, v119, v11, 0
	ds_write_b16 v9, v11 offset:1312
	v_mul_f32_e32 v11, 0xbfb8aa3b, v118
	v_exp_f32_e32 v11, v11
	s_nop 0
	v_add_f32_e32 v11, 1.0, v11
	v_div_scale_f32 v14, s[2:3], v11, v11, 1.0
	v_rcp_f32_e32 v15, v14
	s_nop 0
	v_fma_f32 v16, -v14, v15, 1.0
	v_fmac_f32_e32 v15, v16, v15
	v_div_scale_f32 v16, vcc, 1.0, v11, 1.0
	v_mul_f32_e32 v17, v16, v15
	v_fma_f32 v18, -v14, v17, v16
	v_fmac_f32_e32 v17, v18, v15
	v_fma_f32 v14, -v14, v17, v16
	v_div_fmas_f32 v14, v14, v15, v17
	v_div_fixup_f32 v11, v14, v11, 1.0
	v_mul_f32_e32 v11, v118, v11
	v_fma_mixlo_f16 v11, v117, v11, 0
	ds_write_b16 v9, v11 offset:1392
	v_mul_f32_e32 v11, 0xbfb8aa3b, v116
	v_exp_f32_e32 v11, v11
	s_nop 0
	v_add_f32_e32 v11, 1.0, v11
	v_div_scale_f32 v14, s[2:3], v11, v11, 1.0
	v_rcp_f32_e32 v15, v14
	s_nop 0
	v_fma_f32 v16, -v14, v15, 1.0
	v_fmac_f32_e32 v15, v16, v15
	v_div_scale_f32 v16, vcc, 1.0, v11, 1.0
	v_mul_f32_e32 v17, v16, v15
	v_fma_f32 v18, -v14, v17, v16
	v_fmac_f32_e32 v17, v18, v15
	v_fma_f32 v14, -v14, v17, v16
	v_div_fmas_f32 v14, v14, v15, v17
; DI float sigmoidf_(float x) { return 1.f / (1.f + __expf(-x)); }
; DI void moe_e1_phase(const Params& P, int l, char* smem, int* tb) {
;     ...
;       for (int h = 0; h < 2; h++) {
; #pragma unroll
;         for (int ml = 0; ml < 4; ml++)
; #pragma unroll
;           for (int n = 0; n < 2; n++)
; #pragma unroll
;             for (int j = 0; j < 4; j++) {
;               float a1 = acc[h * 4 + ml][n][j], a3 = acc[h * 4 + ml][n + 2][j];
;               *(half_t*)(stg + (ml * 16 + fq2 * 4 + j) * 80 + (n * 16 + fr2) * 2) = (half_t)(a1 * sigmoidf_(a1) * a3);
;             }
	v_div_fixup_f32 v11, v14, v11, 1.0
	v_mul_f32_e32 v11, v116, v11
	v_fma_mixlo_f16 v11, v115, v11, 0
	ds_write_b16 v9, v11 offset:1472
	v_mul_f32_e32 v11, 0xbfb8aa3b, v114
	v_exp_f32_e32 v11, v11
	s_nop 0
	v_add_f32_e32 v11, 1.0, v11
	v_div_scale_f32 v14, s[2:3], v11, v11, 1.0
	v_rcp_f32_e32 v15, v14
	s_nop 0
	v_fma_f32 v16, -v14, v15, 1.0
	v_fmac_f32_e32 v15, v16, v15
	v_div_scale_f32 v16, vcc, 1.0, v11, 1.0
	v_mul_f32_e32 v17, v16, v15
	v_fma_f32 v18, -v14, v17, v16
	v_fmac_f32_e32 v17, v18, v15
	v_fma_f32 v14, -v14, v17, v16
	v_div_fmas_f32 v14, v14, v15, v17
	v_div_fixup_f32 v11, v14, v11, 1.0
	v_mul_f32_e32 v11, v114, v11
	v_fma_mixlo_f16 v11, v113, v11, 0
	ds_write_b16 v9, v11 offset:1552
	v_mul_f32_e32 v11, 0xbfb8aa3b, v112
	v_exp_f32_e32 v11, v11
	s_nop 0
	v_add_f32_e32 v11, 1.0, v11
	v_div_scale_f32 v14, s[2:3], v11, v11, 1.0
	v_rcp_f32_e32 v15, v14
	s_nop 0
	v_fma_f32 v16, -v14, v15, 1.0
	v_fmac_f32_e32 v15, v16, v15
	v_div_scale_f32 v16, vcc, 1.0, v11, 1.0
	v_mul_f32_e32 v17, v16, v15
	v_fma_f32 v18, -v14, v17, v16
	v_fmac_f32_e32 v17, v18, v15
	v_fma_f32 v14, -v14, v17, v16
	v_div_fmas_f32 v14, v14, v15, v17
	v_div_fixup_f32 v11, v14, v11, 1.0
	v_mul_f32_e32 v11, v112, v11
	v_fma_mixlo_f16 v11, v111, v11, 0
	ds_write_b16 v9, v11 offset:2560
	v_mul_f32_e32 v11, 0xbfb8aa3b, v110
	v_exp_f32_e32 v11, v11
	s_nop 0
	v_add_f32_e32 v11, 1.0, v11
	v_div_scale_f32 v14, s[2:3], v11, v11, 1.0
	v_rcp_f32_e32 v15, v14
	s_nop 0
	v_fma_f32 v16, -v14, v15, 1.0
	v_fmac_f32_e32 v15, v16, v15
	v_div_scale_f32 v16, vcc, 1.0, v11, 1.0
	v_mul_f32_e32 v17, v16, v15
	v_fma_f32 v18, -v14, v17, v16
	v_fmac_f32_e32 v17, v18, v15
	v_fma_f32 v14, -v14, v17, v16
	v_div_fmas_f32 v14, v14, v15, v17
	v_div_fixup_f32 v11, v14, v11, 1.0
	v_mul_f32_e32 v11, v110, v11
	v_fma_mixlo_f16 v11, v109, v11, 0
	ds_write_b16 v9, v11 offset:2640
	v_mul_f32_e32 v11, 0xbfb8aa3b, v108
	v_exp_f32_e32 v11, v11
	s_nop 0
	v_add_f32_e32 v11, 1.0, v11
	v_div_scale_f32 v14, s[2:3], v11, v11, 1.0
	v_rcp_f32_e32 v15, v14
	s_nop 0
	v_fma_f32 v16, -v14, v15, 1.0
	v_fmac_f32_e32 v15, v16, v15
	v_div_scale_f32 v16, vcc, 1.0, v11, 1.0
	v_mul_f32_e32 v17, v16, v15
	v_fma_f32 v18, -v14, v17, v16
	v_fmac_f32_e32 v17, v18, v15
	v_fma_f32 v14, -v14, v17, v16
	v_div_fmas_f32 v14, v14, v15, v17
	v_div_fixup_f32 v11, v14, v11, 1.0
	v_mul_f32_e32 v11, v108, v11
	v_fma_mixlo_f16 v11, v107, v11, 0
	ds_write_b16 v9, v11 offset:2720
	v_mul_f32_e32 v11, 0xbfb8aa3b, v106
	v_exp_f32_e32 v11, v11
	s_nop 0
	v_add_f32_e32 v11, 1.0, v11
	v_div_scale_f32 v14, s[2:3], v11, v11, 1.0
	v_rcp_f32_e32 v15, v14
	s_nop 0
	v_fma_f32 v16, -v14, v15, 1.0
	v_fmac_f32_e32 v15, v16, v15
	v_div_scale_f32 v16, vcc, 1.0, v11, 1.0
	v_mul_f32_e32 v17, v16, v15
	v_fma_f32 v18, -v14, v17, v16
	v_fmac_f32_e32 v17, v18, v15
	v_fma_f32 v14, -v14, v17, v16
	v_div_fmas_f32 v14, v14, v15, v17
	v_div_fixup_f32 v11, v14, v11, 1.0
	v_mul_f32_e32 v11, v106, v11
	v_fma_mixlo_f16 v11, v105, v11, 0
	ds_write_b16 v9, v11 offset:2800
	v_mul_f32_e32 v11, 0xbfb8aa3b, v104
	v_exp_f32_e32 v11, v11
	s_nop 0
	v_add_f32_e32 v11, 1.0, v11
	v_div_scale_f32 v14, s[2:3], v11, v11, 1.0
	v_rcp_f32_e32 v15, v14
	s_nop 0
	v_fma_f32 v16, -v14, v15, 1.0
	v_fmac_f32_e32 v15, v16, v15
	v_div_scale_f32 v16, vcc, 1.0, v11, 1.0
	v_mul_f32_e32 v17, v16, v15
	v_fma_f32 v18, -v14, v17, v16
	v_fmac_f32_e32 v17, v18, v15
	v_fma_f32 v14, -v14, v17, v16
	v_div_fmas_f32 v14, v14, v15, v17
	v_div_fixup_f32 v11, v14, v11, 1.0
	v_mul_f32_e32 v11, v104, v11
	v_fma_mixlo_f16 v11, v103, v11, 0
	ds_write_b16 v9, v11 offset:2592
	v_mul_f32_e32 v11, 0xbfb8aa3b, v102
	v_exp_f32_e32 v11, v11
	s_nop 0
	v_add_f32_e32 v11, 1.0, v11
	v_div_scale_f32 v14, s[2:3], v11, v11, 1.0
	v_rcp_f32_e32 v15, v14
	s_nop 0
	v_fma_f32 v16, -v14, v15, 1.0
	v_fmac_f32_e32 v15, v16, v15
	v_div_scale_f32 v16, vcc, 1.0, v11, 1.0
	v_mul_f32_e32 v17, v16, v15
	v_fma_f32 v18, -v14, v17, v16
	v_fmac_f32_e32 v17, v18, v15
	v_fma_f32 v14, -v14, v17, v16
	v_div_fmas_f32 v14, v14, v15, v17
	v_div_fixup_f32 v11, v14, v11, 1.0
	v_mul_f32_e32 v11, v102, v11
	v_fma_mixlo_f16 v11, v101, v11, 0
	ds_write_b16 v9, v11 offset:2672
	v_mul_f32_e32 v11, 0xbfb8aa3b, v100
	v_exp_f32_e32 v11, v11
	s_nop 0
	v_add_f32_e32 v11, 1.0, v11
	v_div_scale_f32 v14, s[2:3], v11, v11, 1.0
	v_rcp_f32_e32 v15, v14
	s_nop 0
	v_fma_f32 v16, -v14, v15, 1.0
	v_fmac_f32_e32 v15, v16, v15
	v_div_scale_f32 v16, vcc, 1.0, v11, 1.0
	v_mul_f32_e32 v17, v16, v15
	v_fma_f32 v18, -v14, v17, v16
	v_fmac_f32_e32 v17, v18, v15
	v_fma_f32 v14, -v14, v17, v16
	v_div_fmas_f32 v14, v14, v15, v17
	v_div_fixup_f32 v11, v14, v11, 1.0
	v_mul_f32_e32 v11, v100, v11
	v_fma_mixlo_f16 v11, v99, v11, 0
	ds_write_b16 v9, v11 offset:2752
	v_mul_f32_e32 v11, 0xbfb8aa3b, v98
	v_exp_f32_e32 v11, v11
	s_nop 0
	v_add_f32_e32 v11, 1.0, v11
	v_div_scale_f32 v14, s[2:3], v11, v11, 1.0
	v_rcp_f32_e32 v15, v14
	s_nop 0
	v_fma_f32 v16, -v14, v15, 1.0
	v_fmac_f32_e32 v15, v16, v15
	v_div_scale_f32 v16, vcc, 1.0, v11, 1.0
	v_mul_f32_e32 v17, v16, v15
	v_fma_f32 v18, -v14, v17, v16
	v_fmac_f32_e32 v17, v18, v15
	v_fma_f32 v14, -v14, v17, v16
	v_div_fmas_f32 v14, v14, v15, v17
	v_div_fixup_f32 v11, v14, v11, 1.0
	v_mul_f32_e32 v11, v98, v11
	v_fma_mixlo_f16 v11, v97, v11, 0
	ds_write_b16 v9, v11 offset:2832
	v_mul_f32_e32 v11, 0xbfb8aa3b, v96
; DI float sigmoidf_(float x) { return 1.f / (1.f + __expf(-x)); }
; DI void moe_e1_phase(const Params& P, int l, char* smem, int* tb) {
;     ...
;       for (int h = 0; h < 2; h++) {
; #pragma unroll
;         for (int ml = 0; ml < 4; ml++)
; #pragma unroll
;           for (int n = 0; n < 2; n++)
; #pragma unroll
;             for (int j = 0; j < 4; j++) {
;               float a1 = acc[h * 4 + ml][n][j], a3 = acc[h * 4 + ml][n + 2][j];
;               *(half_t*)(stg + (ml * 16 + fq2 * 4 + j) * 80 + (n * 16 + fr2) * 2) = (half_t)(a1 * sigmoidf_(a1) * a3);
;             }
;         __builtin_amdgcn_wave_barrier();
; #pragma unroll
;         for (int i = 0; i < 4; i++) {
;           const int c = i * 64 + lane2, row = c >> 2, c16 = c & 3;
;           h8 v = *(const h8*)(stg + row * 80 + c16 * 16);
;           *(h8*)(Hd + (size_t)(h * 64 + row) * 512 + c16 * 8) = v;
;         }
;         __builtin_amdgcn_wave_barrier();
	v_exp_f32_e32 v11, v11
	s_nop 0
	v_add_f32_e32 v11, 1.0, v11
	v_div_scale_f32 v14, s[2:3], v11, v11, 1.0
	v_rcp_f32_e32 v15, v14
	s_nop 0
	v_fma_f32 v16, -v14, v15, 1.0
	v_fmac_f32_e32 v15, v16, v15
	v_div_scale_f32 v16, vcc, 1.0, v11, 1.0
	v_mul_f32_e32 v17, v16, v15
	v_fma_f32 v18, -v14, v17, v16
	v_fmac_f32_e32 v17, v18, v15
	v_fma_f32 v14, -v14, v17, v16
	v_div_fmas_f32 v14, v14, v15, v17
	v_div_fixup_f32 v11, v14, v11, 1.0
	v_mul_f32_e32 v11, v96, v11
	v_fma_mixlo_f16 v11, v95, v11, 0
	ds_write_b16 v9, v11 offset:3840
	v_mul_f32_e32 v11, 0xbfb8aa3b, v94
	v_exp_f32_e32 v11, v11
	s_nop 0
	v_add_f32_e32 v11, 1.0, v11
	v_div_scale_f32 v14, s[2:3], v11, v11, 1.0
	v_rcp_f32_e32 v15, v14
	s_nop 0
	v_fma_f32 v16, -v14, v15, 1.0
	v_fmac_f32_e32 v15, v16, v15
	v_div_scale_f32 v16, vcc, 1.0, v11, 1.0
	v_mul_f32_e32 v17, v16, v15
	v_fma_f32 v18, -v14, v17, v16
	v_fmac_f32_e32 v17, v18, v15
	v_fma_f32 v14, -v14, v17, v16
	v_div_fmas_f32 v14, v14, v15, v17
	v_div_fixup_f32 v11, v14, v11, 1.0
	v_mul_f32_e32 v11, v94, v11
	v_fma_mixlo_f16 v11, v93, v11, 0
	ds_write_b16 v9, v11 offset:3920
	v_mul_f32_e32 v11, 0xbfb8aa3b, v92
	v_exp_f32_e32 v11, v11
	s_nop 0
	v_add_f32_e32 v11, 1.0, v11
	v_div_scale_f32 v14, s[2:3], v11, v11, 1.0
	v_rcp_f32_e32 v15, v14
	s_nop 0
	v_fma_f32 v16, -v14, v15, 1.0
	v_fmac_f32_e32 v15, v16, v15
	v_div_scale_f32 v16, vcc, 1.0, v11, 1.0
	v_mul_f32_e32 v17, v16, v15
	v_fma_f32 v18, -v14, v17, v16
	v_fmac_f32_e32 v17, v18, v15
	v_fma_f32 v14, -v14, v17, v16
	v_div_fmas_f32 v14, v14, v15, v17
	v_div_fixup_f32 v11, v14, v11, 1.0
	v_mul_f32_e32 v11, v92, v11
	v_fma_mixlo_f16 v11, v91, v11, 0
	ds_write_b16 v9, v11 offset:4000
	v_mul_f32_e32 v11, 0xbfb8aa3b, v90
	v_exp_f32_e32 v11, v11
	s_nop 0
	v_add_f32_e32 v11, 1.0, v11
	v_div_scale_f32 v14, s[2:3], v11, v11, 1.0
	v_rcp_f32_e32 v15, v14
	s_nop 0
	v_fma_f32 v16, -v14, v15, 1.0
	v_fmac_f32_e32 v15, v16, v15
	v_div_scale_f32 v16, vcc, 1.0, v11, 1.0
	v_mul_f32_e32 v17, v16, v15
	v_fma_f32 v18, -v14, v17, v16
	v_fmac_f32_e32 v17, v18, v15
	v_fma_f32 v14, -v14, v17, v16
	v_div_fmas_f32 v14, v14, v15, v17
	v_div_fixup_f32 v11, v14, v11, 1.0
	v_mul_f32_e32 v11, v90, v11
	v_fma_mixlo_f16 v11, v89, v11, 0
	ds_write_b16 v9, v11 offset:4080
	v_mul_f32_e32 v11, 0xbfb8aa3b, v88
	v_exp_f32_e32 v11, v11
	s_nop 0
	v_add_f32_e32 v11, 1.0, v11
	v_div_scale_f32 v14, s[2:3], v11, v11, 1.0
	v_rcp_f32_e32 v15, v14
	s_nop 0
	v_fma_f32 v16, -v14, v15, 1.0
	v_fmac_f32_e32 v15, v16, v15
	v_div_scale_f32 v16, vcc, 1.0, v11, 1.0
	v_mul_f32_e32 v17, v16, v15
	v_fma_f32 v18, -v14, v17, v16
	v_fmac_f32_e32 v17, v18, v15
	v_fma_f32 v14, -v14, v17, v16
	v_div_fmas_f32 v14, v14, v15, v17
	v_div_fixup_f32 v11, v14, v11, 1.0
	v_mul_f32_e32 v11, v88, v11
	v_fma_mixlo_f16 v11, v87, v11, 0
	ds_write_b16 v9, v11 offset:3872
	v_mul_f32_e32 v11, 0xbfb8aa3b, v86
	v_exp_f32_e32 v11, v11
	s_nop 0
	v_add_f32_e32 v11, 1.0, v11
	v_div_scale_f32 v14, s[2:3], v11, v11, 1.0
	v_rcp_f32_e32 v15, v14
	s_nop 0
	v_fma_f32 v16, -v14, v15, 1.0
	v_fmac_f32_e32 v15, v16, v15
	v_div_scale_f32 v16, vcc, 1.0, v11, 1.0
	v_mul_f32_e32 v17, v16, v15
	v_fma_f32 v18, -v14, v17, v16
	v_fmac_f32_e32 v17, v18, v15
	v_fma_f32 v14, -v14, v17, v16
	v_div_fmas_f32 v14, v14, v15, v17
	v_div_fixup_f32 v11, v14, v11, 1.0
	v_mul_f32_e32 v11, v86, v11
	v_fma_mixlo_f16 v11, v85, v11, 0
	ds_write_b16 v9, v11 offset:3952
	v_mul_f32_e32 v11, 0xbfb8aa3b, v84
	v_exp_f32_e32 v11, v11
	s_nop 0
	v_add_f32_e32 v11, 1.0, v11
	v_div_scale_f32 v14, s[2:3], v11, v11, 1.0
	v_rcp_f32_e32 v15, v14
	s_nop 0
	v_fma_f32 v16, -v14, v15, 1.0
	v_fmac_f32_e32 v15, v16, v15
	v_div_scale_f32 v16, vcc, 1.0, v11, 1.0
	v_mul_f32_e32 v17, v16, v15
	v_fma_f32 v18, -v14, v17, v16
	v_fmac_f32_e32 v17, v18, v15
	v_fma_f32 v14, -v14, v17, v16
	v_div_fmas_f32 v14, v14, v15, v17
	v_div_fixup_f32 v11, v14, v11, 1.0
	v_mul_f32_e32 v11, v84, v11
	v_fma_mixlo_f16 v11, v57, v11, 0
	ds_write_b16 v9, v11 offset:4032
	v_mul_f32_e32 v11, 0xbfb8aa3b, v27
	v_exp_f32_e32 v11, v11
	s_nop 0
	v_add_f32_e32 v11, 1.0, v11
	v_div_scale_f32 v14, s[2:3], v11, v11, 1.0
	v_rcp_f32_e32 v15, v14
	s_mov_b32 s2, 0x10000
	v_fma_f32 v16, -v14, v15, 1.0
	v_fmac_f32_e32 v15, v16, v15
	v_div_scale_f32 v16, vcc, 1.0, v11, 1.0
	v_mul_f32_e32 v17, v16, v15
	v_fma_f32 v18, -v14, v17, v16
	v_fmac_f32_e32 v17, v18, v15
	v_fma_f32 v14, -v14, v17, v16
	v_div_fmas_f32 v14, v14, v15, v17
	v_div_fixup_f32 v11, v14, v11, 1.0
	v_mul_f32_e32 v11, v27, v11
	v_fma_mixlo_f16 v11, v25, v11, 0
	ds_write_b16 v9, v11 offset:4112
	ds_read_b128 v[14:17], v8
	v_add_co_u32_e32 v0, vcc, s2, v0
	s_nop 1
	v_addc_co_u32_e32 v1, vcc, 0, v1, vcc
	s_waitcnt lgkmcnt(0)
	global_store_dwordx4 v[0:1], v[14:17], off nt
	ds_read_b128 v[14:17], v12
	v_add_co_u32_e32 v0, vcc, s2, v4
	s_nop 1
	v_addc_co_u32_e32 v1, vcc, 0, v5, vcc
	s_waitcnt lgkmcnt(0)
	global_store_dwordx4 v[0:1], v[14:17], off nt
	ds_read_b128 v[12:15], v13
	v_add_co_u32_e32 v0, vcc, 0x10000, v6
	s_nop 1
	v_addc_co_u32_e32 v1, vcc, 0, v7, vcc
	ds_read_b128 v[4:7], v10
	s_waitcnt lgkmcnt(1)
	global_store_dwordx4 v[0:1], v[12:15], off nt
	v_add_co_u32_e32 v0, vcc, 0x10000, v2
	s_nop 1
	v_addc_co_u32_e32 v1, vcc, 0, v3, vcc
	s_andn2_b64 vcc, exec, s[0:1]
	s_waitcnt lgkmcnt(0)
	global_store_dwordx4 v[0:1], v[4:7], off nt
	s_cbranch_vccz .LBB0_590
